# GEMM K-loops: post-MFMA barrier signalled 8 MFMAs early with prio-2 tail (on top of attn resched + pooling rewrite)
# speedup vs baseline: 1.0253x; 1.0094x over previous
; #define PG8_STAGE(bufoff, gbase, voff) do { _Pragma("unroll") for (int _i = 0; _i < 2; ++_i) \
;         __builtin_amdgcn_global_load_lds((const unsigned*)((const char*)(gbase) + (voff)[_i]), (PG8_LAS unsigned*)(lds + (bufoff) + ldsw + _i * 8192), 16, 0, 0); } while (0)
; #define PG8_LDA(dst, b, h) do { _Pragma("unroll") for (int m = 0; m < 4; ++m) _Pragma("unroll") for (int k = 0; k < 2; ++k) dst[m][k] = *(const PG8_LAS bf16x8*)(lds + PG8_SA(b, h) + aoff + m * 2048 + k * 1024); } while (0)
; #define PG8_LDB(dst, b, h) do { _Pragma("unroll") for (int n = 0; n < 2; ++n) _Pragma("unroll") for (int k = 0; k < 2; ++k) dst[n][k] = *(const PG8_LAS bf16x8*)(lds + PG8_SB(b, h) + boff + n * 2048 + k * 1024); } while (0)
; #define PG8_MMA(ai, bj, At, Bt) do { __builtin_amdgcn_s_setprio(1); _Pragma("unroll") for (int m = 0; m < 4; ++m) _Pragma("unroll") for (int n = 0; n < 2; ++n) _Pragma("unroll") for (int k = 0; k < 2; ++k) \
;         acc[ai][bj][m][n] = __builtin_amdgcn_mfma_f32_16x16x32_bf16(Bt[n][k], At[m][k], acc[ai][bj][m][n], 0, 0, 0); __builtin_amdgcn_s_setprio(0); } while (0)
; #define PG8_WAIT_V(n) asm volatile("s_waitcnt vmcnt(" #n ")" ::: "memory")
; #define PG8_WAIT_L(n) asm volatile("s_waitcnt lgkmcnt(" #n ")" ::: "memory")
; #define PG8_BAR __builtin_amdgcn_s_barrier()
; #define PG8_SCHED __builtin_amdgcn_sched_barrier(0)
; template <class Epi, class Sched, bool ALIGN_EPI = false, bool SP2 = false>
; __device__ __forceinline__ void gemm_phase(PG8_LAS unsigned char* lds, const Gemm g, const Sched& S, const Epi& E) {
;     ...
;             PG8_LDB(B0, 0, 0); PG8_LDB(B1, 0, 1); PG8_SCHED; PG8_LDA(At, 0, 0); PG8_STAGE(PG8_SA(1, 1), a1 + hstep, voffA);
;             PG8_WAIT_V(8); PG8_WAIT_L(0); PG8_BAR; PG8_MMA(0, 0, At, B0); PG8_MMA(0, 1, At, B1); PG8_BAR; PG8_SCHED;
;             PG8_LDA(At, 0, 1); PG8_STAGE(PG8_SB(0, 0), b2, voffB); PG8_STAGE(PG8_SB(0, 1), b2 + hstep, voffB); PG8_STAGE(PG8_SA(0, 0), a2, voffA);
;             PG8_WAIT_V(8); PG8_WAIT_L(0); PG8_BAR; PG8_MMA(1, 0, At, B0); PG8_MMA(1, 1, At, B1); PG8_BAR; PG8_SCHED;
.LBB0_207:
	ds_read_b128 v[150:153], v147
	ds_read_b128 v[158:161], v147 offset:1024
	ds_read_b128 v[162:165], v147 offset:2048
	ds_read_b128 v[166:169], v147 offset:3072
	ds_read_b128 v[170:173], v148
	ds_read_b128 v[174:177], v148 offset:1024
	ds_read_b128 v[178:181], v148 offset:2048
	ds_read_b128 v[182:185], v148 offset:3072
	s_add_u32 s10, s50, 0xfffc0080
	s_addc_u32 s11, s51, -1
	s_cmp_eq_u32 s74, 12
	s_cselect_b32 s61, s23, s11
	s_cselect_b32 s60, s89, s10
	s_cselect_b32 s59, s21, s92
	s_cselect_b32 s58, s90, s91
	v_lshl_add_u64 v[154:155], s[50:51], 0, v[136:137]
	s_add_i32 m0, s49, 0xc000
	ds_read_b128 v[186:189], v149
	ds_read_b128 v[190:193], v149 offset:1024
	ds_read_b128 v[194:197], v149 offset:2048
	ds_read_b128 v[198:201], v149 offset:3072
	ds_read_b128 v[204:207], v149 offset:4096
	ds_read_b128 v[208:211], v149 offset:5120
	ds_read_b128 v[212:215], v149 offset:6144
	ds_read_b128 v[216:219], v149 offset:7168
	global_load_lds_dwordx4 v[154:155], off
	v_lshl_add_u64 v[154:155], s[50:51], 0, v[138:139]
	s_add_i32 m0, s49, 0xe000
	s_nop 0
	global_load_lds_dwordx4 v[154:155], off
	s_waitcnt vmcnt(8)
	s_waitcnt lgkmcnt(0)
	s_barrier
	s_setprio 1
	s_waitcnt lgkmcnt(0)
	v_mfma_f32_16x16x32_bf16 v[124:127], v[150:153], v[186:189], v[124:127]
	v_mfma_f32_16x16x32_bf16 v[120:123], v[162:165], v[186:189], v[120:123]
	v_mfma_f32_16x16x32_bf16 v[108:111], v[150:153], v[194:197], v[108:111]
	v_mfma_f32_16x16x32_bf16 v[104:107], v[162:165], v[194:197], v[104:107]
	v_mfma_f32_16x16x32_bf16 v[92:95], v[150:153], v[204:207], v[92:95]
	v_mfma_f32_16x16x32_bf16 v[88:91], v[162:165], v[204:207], v[88:91]
	v_mfma_f32_16x16x32_bf16 v[76:79], v[150:153], v[212:215], v[76:79]
	v_mfma_f32_16x16x32_bf16 v[72:75], v[162:165], v[212:215], v[72:75]
	v_mfma_f32_16x16x32_bf16 v[124:127], v[158:161], v[190:193], v[124:127]
	v_mfma_f32_16x16x32_bf16 v[120:123], v[166:169], v[190:193], v[120:123]
	v_mfma_f32_16x16x32_bf16 v[108:111], v[158:161], v[198:201], v[108:111]
	v_mfma_f32_16x16x32_bf16 v[104:107], v[166:169], v[198:201], v[104:107]
	v_mfma_f32_16x16x32_bf16 v[92:95], v[158:161], v[208:211], v[92:95]
	v_mfma_f32_16x16x32_bf16 v[88:91], v[166:169], v[208:211], v[88:91]
	v_mfma_f32_16x16x32_bf16 v[76:79], v[158:161], v[216:219], v[76:79]
	v_mfma_f32_16x16x32_bf16 v[72:75], v[166:169], v[216:219], v[72:75]
	s_setprio 0
	s_setprio 1
	v_mfma_f32_16x16x32_bf16 v[116:119], v[170:173], v[186:189], v[116:119]
	v_mfma_f32_16x16x32_bf16 v[112:115], v[178:181], v[186:189], v[112:115]
	v_mfma_f32_16x16x32_bf16 v[100:103], v[170:173], v[194:197], v[100:103]
	v_mfma_f32_16x16x32_bf16 v[96:99], v[178:181], v[194:197], v[96:99]
	v_mfma_f32_16x16x32_bf16 v[84:87], v[170:173], v[204:207], v[84:87]
	v_mfma_f32_16x16x32_bf16 v[80:83], v[178:181], v[204:207], v[80:83]
	v_mfma_f32_16x16x32_bf16 v[68:71], v[170:173], v[212:215], v[68:71]
	v_mfma_f32_16x16x32_bf16 v[64:67], v[178:181], v[212:215], v[64:67]
	s_barrier
	s_setprio 2
	v_mfma_f32_16x16x32_bf16 v[116:119], v[174:177], v[190:193], v[116:119]
	v_mfma_f32_16x16x32_bf16 v[112:115], v[182:185], v[190:193], v[112:115]
	v_mfma_f32_16x16x32_bf16 v[100:103], v[174:177], v[198:201], v[100:103]
	v_mfma_f32_16x16x32_bf16 v[96:99], v[182:185], v[198:201], v[96:99]
	v_mfma_f32_16x16x32_bf16 v[84:87], v[174:177], v[208:211], v[84:87]
	v_mfma_f32_16x16x32_bf16 v[80:83], v[182:185], v[208:211], v[80:83]
	v_mfma_f32_16x16x32_bf16 v[68:71], v[174:177], v[216:219], v[68:71]
	v_mfma_f32_16x16x32_bf16 v[64:67], v[182:185], v[216:219], v[64:67]
	s_setprio 0
	s_add_i32 s10, s85, s33
	v_lshl_add_u64 v[154:155], s[58:59], 0, v[132:133]
	s_mov_b32 m0, s10
	ds_read_b128 v[186:189], v149 offset:16384
	ds_read_b128 v[190:193], v149 offset:17408
	ds_read_b128 v[194:197], v149 offset:18432
	ds_read_b128 v[198:201], v149 offset:19456
	ds_read_b128 v[204:207], v149 offset:20480
	ds_read_b128 v[208:211], v149 offset:21504
	ds_read_b128 v[212:215], v149 offset:22528
	ds_read_b128 v[216:219], v149 offset:23552
	global_load_lds_dwordx4 v[154:155], off
	s_add_i32 m0, s10, 0x2000
	s_add_u32 s94, s58, 0x40000
	v_lshl_add_u64 v[220:221], s[58:59], 0, v[128:129]
	s_addc_u32 s95, s59, 0
	s_add_i32 s10, s86, s33
	global_load_lds_dwordx4 v[220:221], off
	v_lshl_add_u64 v[222:223], s[94:95], 0, v[132:133]
	s_mov_b32 m0, s10
	v_lshl_add_u64 v[224:225], s[60:61], 0, v[130:131]
	global_load_lds_dwordx4 v[222:223], off
	v_lshl_add_u64 v[222:223], s[94:95], 0, v[128:129]
	s_add_i32 m0, s10, 0x2000
	s_nop 0
	global_load_lds_dwordx4 v[222:223], off
	v_lshl_add_u64 v[222:223], s[60:61], 0, v[134:135]
	s_mov_b32 m0, s49
	s_nop 0
	global_load_lds_dwordx4 v[222:223], off
	s_mov_b32 m0, s63
	s_nop 0
	global_load_lds_dwordx4 v[224:225], off
	s_waitcnt vmcnt(8)
	s_waitcnt lgkmcnt(0)
	s_barrier
	s_setprio 1
	s_waitcnt lgkmcnt(0)
	v_mfma_f32_16x16x32_bf16 v[60:63], v[150:153], v[186:189], v[60:63]
	v_mfma_f32_16x16x32_bf16 v[56:59], v[162:165], v[186:189], v[56:59]
	v_mfma_f32_16x16x32_bf16 v[44:47], v[150:153], v[194:197], v[44:47]
	v_mfma_f32_16x16x32_bf16 v[40:43], v[162:165], v[194:197], v[40:43]
	v_mfma_f32_16x16x32_bf16 v[28:31], v[150:153], v[204:207], v[28:31]
	v_mfma_f32_16x16x32_bf16 v[24:27], v[162:165], v[204:207], v[24:27]
	v_mfma_f32_16x16x32_bf16 v[12:15], v[150:153], v[212:215], v[12:15]
	v_mfma_f32_16x16x32_bf16 v[8:11], v[162:165], v[212:215], v[8:11]
	v_mfma_f32_16x16x32_bf16 v[60:63], v[158:161], v[190:193], v[60:63]
	v_mfma_f32_16x16x32_bf16 v[56:59], v[166:169], v[190:193], v[56:59]
	v_mfma_f32_16x16x32_bf16 v[44:47], v[158:161], v[198:201], v[44:47]
	v_mfma_f32_16x16x32_bf16 v[40:43], v[166:169], v[198:201], v[40:43]
	v_mfma_f32_16x16x32_bf16 v[28:31], v[158:161], v[208:211], v[28:31]
	v_mfma_f32_16x16x32_bf16 v[24:27], v[166:169], v[208:211], v[24:27]
	v_mfma_f32_16x16x32_bf16 v[12:15], v[158:161], v[216:219], v[12:15]
	v_mfma_f32_16x16x32_bf16 v[8:11], v[166:169], v[216:219], v[8:11]
	s_setprio 0
	s_setprio 1
	v_mfma_f32_16x16x32_bf16 v[52:55], v[170:173], v[186:189], v[52:55]
	v_mfma_f32_16x16x32_bf16 v[48:51], v[178:181], v[186:189], v[48:51]
	v_mfma_f32_16x16x32_bf16 v[36:39], v[170:173], v[194:197], v[36:39]
	v_mfma_f32_16x16x32_bf16 v[32:35], v[178:181], v[194:197], v[32:35]
	v_mfma_f32_16x16x32_bf16 v[20:23], v[170:173], v[204:207], v[20:23]
	v_mfma_f32_16x16x32_bf16 v[16:19], v[178:181], v[204:207], v[16:19]
	v_mfma_f32_16x16x32_bf16 v[4:7], v[170:173], v[212:215], v[4:7]
	v_mfma_f32_16x16x32_bf16 v[0:3], v[178:181], v[212:215], v[0:3]
	s_barrier
; #define PG8_STAGE(bufoff, gbase, voff) do { _Pragma("unroll") for (int _i = 0; _i < 2; ++_i) \
;         __builtin_amdgcn_global_load_lds((const unsigned*)((const char*)(gbase) + (voff)[_i]), (PG8_LAS unsigned*)(lds + (bufoff) + ldsw + _i * 8192), 16, 0, 0); } while (0)
; #define PG8_LDA(dst, b, h) do { _Pragma("unroll") for (int m = 0; m < 4; ++m) _Pragma("unroll") for (int k = 0; k < 2; ++k) dst[m][k] = *(const PG8_LAS bf16x8*)(lds + PG8_SA(b, h) + aoff + m * 2048 + k * 1024); } while (0)
; #define PG8_LDB(dst, b, h) do { _Pragma("unroll") for (int n = 0; n < 2; ++n) _Pragma("unroll") for (int k = 0; k < 2; ++k) dst[n][k] = *(const PG8_LAS bf16x8*)(lds + PG8_SB(b, h) + boff + n * 2048 + k * 1024); } while (0)
; #define PG8_MMA(ai, bj, At, Bt) do { __builtin_amdgcn_s_setprio(1); _Pragma("unroll") for (int m = 0; m < 4; ++m) _Pragma("unroll") for (int n = 0; n < 2; ++n) _Pragma("unroll") for (int k = 0; k < 2; ++k) \
;         acc[ai][bj][m][n] = __builtin_amdgcn_mfma_f32_16x16x32_bf16(Bt[n][k], At[m][k], acc[ai][bj][m][n], 0, 0, 0); __builtin_amdgcn_s_setprio(0); } while (0)
; #define PG8_WAIT_V(n) asm volatile("s_waitcnt vmcnt(" #n ")" ::: "memory")
; #define PG8_WAIT_L(n) asm volatile("s_waitcnt lgkmcnt(" #n ")" ::: "memory")
; #define PG8_BAR __builtin_amdgcn_s_barrier()
; #define PG8_SCHED __builtin_amdgcn_sched_barrier(0)
; template <class Epi, class Sched, bool ALIGN_EPI = false, bool SP2 = false>
; __device__ __forceinline__ void gemm_phase(PG8_LAS unsigned char* lds, const Gemm g, const Sched& S, const Epi& E) {
;     ...
;             PG8_WAIT_V(8); PG8_WAIT_L(0); PG8_BAR; PG8_MMA(1, 0, At, B0); PG8_MMA(1, 1, At, B1); PG8_BAR; PG8_SCHED;
;             PG8_LDB(B0, 1, 0); PG8_LDB(B1, 1, 1); PG8_SCHED; PG8_LDA(At, 1, 0); PG8_STAGE(PG8_SA(0, 1), a2 + hstep, voffA);
;             PG8_WAIT_V(8); PG8_WAIT_L(0); PG8_BAR; PG8_MMA(0, 0, At, B0); PG8_MMA(0, 1, At, B1); PG8_BAR; PG8_SCHED;
	s_setprio 2
	v_mfma_f32_16x16x32_bf16 v[52:55], v[174:177], v[190:193], v[52:55]
	v_mfma_f32_16x16x32_bf16 v[48:51], v[182:185], v[190:193], v[48:51]
	v_mfma_f32_16x16x32_bf16 v[36:39], v[174:177], v[198:201], v[36:39]
	v_mfma_f32_16x16x32_bf16 v[32:35], v[182:185], v[198:201], v[32:35]
	v_mfma_f32_16x16x32_bf16 v[20:23], v[174:177], v[208:211], v[20:23]
	v_mfma_f32_16x16x32_bf16 v[16:19], v[182:185], v[208:211], v[16:19]
	v_mfma_f32_16x16x32_bf16 v[4:7], v[174:177], v[216:219], v[4:7]
	v_mfma_f32_16x16x32_bf16 v[0:3], v[182:185], v[216:219], v[0:3]
	s_setprio 0
	s_add_i32 s10, 0, 0x18000
	v_add_u32_e32 v157, s10, v145
	s_add_i32 s11, 0, 0x1c000
	ds_read_b128 v[150:153], v157
	ds_read_b128 v[158:161], v157 offset:1024
	ds_read_b128 v[162:165], v157 offset:2048
	ds_read_b128 v[166:169], v157 offset:3072
	v_add_u32_e32 v157, s11, v145
	ds_read_b128 v[170:173], v157
	ds_read_b128 v[174:177], v157 offset:1024
	ds_read_b128 v[178:181], v157 offset:2048
	ds_read_b128 v[182:185], v157 offset:3072
	s_add_u32 s60, s60, 0x40000
	s_addc_u32 s61, s61, 0
	s_mov_b32 m0, s64
	v_lshl_add_u64 v[226:227], s[60:61], 0, v[134:135]
	ds_read_b128 v[186:189], v149 offset:32768
	ds_read_b128 v[190:193], v149 offset:33792
	ds_read_b128 v[194:197], v149 offset:34816
	ds_read_b128 v[198:201], v149 offset:35840
	ds_read_b128 v[204:207], v149 offset:36864
	ds_read_b128 v[208:211], v149 offset:37888
	ds_read_b128 v[212:215], v149 offset:38912
	ds_read_b128 v[216:219], v149 offset:39936
	global_load_lds_dwordx4 v[226:227], off
	v_lshl_add_u64 v[226:227], s[60:61], 0, v[130:131]
	s_mov_b32 m0, s65
	s_nop 0
	global_load_lds_dwordx4 v[226:227], off
	s_waitcnt vmcnt(8)
	s_waitcnt lgkmcnt(0)
	s_barrier
	s_setprio 1
	s_waitcnt lgkmcnt(0)
	v_mfma_f32_16x16x32_bf16 v[124:127], v[150:153], v[186:189], v[124:127]
	v_mfma_f32_16x16x32_bf16 v[120:123], v[162:165], v[186:189], v[120:123]
	v_mfma_f32_16x16x32_bf16 v[108:111], v[150:153], v[194:197], v[108:111]
	v_mfma_f32_16x16x32_bf16 v[104:107], v[162:165], v[194:197], v[104:107]
	v_mfma_f32_16x16x32_bf16 v[92:95], v[150:153], v[204:207], v[92:95]
	v_mfma_f32_16x16x32_bf16 v[88:91], v[162:165], v[204:207], v[88:91]
	v_mfma_f32_16x16x32_bf16 v[76:79], v[150:153], v[212:215], v[76:79]
	v_mfma_f32_16x16x32_bf16 v[72:75], v[162:165], v[212:215], v[72:75]
	v_mfma_f32_16x16x32_bf16 v[124:127], v[158:161], v[190:193], v[124:127]
	v_mfma_f32_16x16x32_bf16 v[120:123], v[166:169], v[190:193], v[120:123]
	v_mfma_f32_16x16x32_bf16 v[108:111], v[158:161], v[198:201], v[108:111]
	v_mfma_f32_16x16x32_bf16 v[104:107], v[166:169], v[198:201], v[104:107]
	v_mfma_f32_16x16x32_bf16 v[92:95], v[158:161], v[208:211], v[92:95]
	v_mfma_f32_16x16x32_bf16 v[88:91], v[166:169], v[208:211], v[88:91]
	v_mfma_f32_16x16x32_bf16 v[76:79], v[158:161], v[216:219], v[76:79]
	v_mfma_f32_16x16x32_bf16 v[72:75], v[166:169], v[216:219], v[72:75]
	s_setprio 0
	s_setprio 1
	v_mfma_f32_16x16x32_bf16 v[116:119], v[170:173], v[186:189], v[116:119]
	v_mfma_f32_16x16x32_bf16 v[112:115], v[178:181], v[186:189], v[112:115]
	v_mfma_f32_16x16x32_bf16 v[100:103], v[170:173], v[194:197], v[100:103]
	v_mfma_f32_16x16x32_bf16 v[96:99], v[178:181], v[194:197], v[96:99]
	v_mfma_f32_16x16x32_bf16 v[84:87], v[170:173], v[204:207], v[84:87]
	v_mfma_f32_16x16x32_bf16 v[80:83], v[178:181], v[204:207], v[80:83]
	v_mfma_f32_16x16x32_bf16 v[68:71], v[170:173], v[212:215], v[68:71]
	v_mfma_f32_16x16x32_bf16 v[64:67], v[178:181], v[212:215], v[64:67]
	s_barrier
; #define PG8_STAGE(bufoff, gbase, voff) do { _Pragma("unroll") for (int _i = 0; _i < 2; ++_i) \
;         __builtin_amdgcn_global_load_lds((const unsigned*)((const char*)(gbase) + (voff)[_i]), (PG8_LAS unsigned*)(lds + (bufoff) + ldsw + _i * 8192), 16, 0, 0); } while (0)
; #define PG8_LDA(dst, b, h) do { _Pragma("unroll") for (int m = 0; m < 4; ++m) _Pragma("unroll") for (int k = 0; k < 2; ++k) dst[m][k] = *(const PG8_LAS bf16x8*)(lds + PG8_SA(b, h) + aoff + m * 2048 + k * 1024); } while (0)
; #define PG8_MMA(ai, bj, At, Bt) do { __builtin_amdgcn_s_setprio(1); _Pragma("unroll") for (int m = 0; m < 4; ++m) _Pragma("unroll") for (int n = 0; n < 2; ++n) _Pragma("unroll") for (int k = 0; k < 2; ++k) \
;         acc[ai][bj][m][n] = __builtin_amdgcn_mfma_f32_16x16x32_bf16(Bt[n][k], At[m][k], acc[ai][bj][m][n], 0, 0, 0); __builtin_amdgcn_s_setprio(0); } while (0)
; #define PG8_WAIT_V(n) asm volatile("s_waitcnt vmcnt(" #n ")" ::: "memory")
; #define PG8_WAIT_L(n) asm volatile("s_waitcnt lgkmcnt(" #n ")" ::: "memory")
; #define PG8_BAR __builtin_amdgcn_s_barrier()
; #define PG8_SCHED __builtin_amdgcn_sched_barrier(0)
; template <class Epi, class Sched, bool ALIGN_EPI = false, bool SP2 = false>
; __device__ __forceinline__ void gemm_phase(PG8_LAS unsigned char* lds, const Gemm g, const Sched& S, const Epi& E) {
;     ...
;         for (int t = 0; t < nt; t += 2) {
;     ...
;             PG8_WAIT_V(8); PG8_WAIT_L(0); PG8_BAR; PG8_MMA(0, 0, At, B0); PG8_MMA(0, 1, At, B1); PG8_BAR; PG8_SCHED;
;             PG8_LDA(At, 1, 1); PG8_STAGE(PG8_SB(1, 0), b3, voffB); PG8_STAGE(PG8_SB(1, 1), b3 + hstep, voffB); PG8_STAGE(PG8_SA(1, 0), a3, voffA);
;             PG8_WAIT_V(8); PG8_WAIT_L(0); PG8_BAR; PG8_MMA(1, 0, At, B0); PG8_MMA(1, 1, At, B1); PG8_BAR; PG8_SCHED;
	s_setprio 2
	v_mfma_f32_16x16x32_bf16 v[116:119], v[174:177], v[190:193], v[116:119]
	v_mfma_f32_16x16x32_bf16 v[112:115], v[182:185], v[190:193], v[112:115]
	v_mfma_f32_16x16x32_bf16 v[100:103], v[174:177], v[198:201], v[100:103]
	v_mfma_f32_16x16x32_bf16 v[96:99], v[182:185], v[198:201], v[96:99]
	v_mfma_f32_16x16x32_bf16 v[84:87], v[174:177], v[208:211], v[84:87]
	v_mfma_f32_16x16x32_bf16 v[80:83], v[182:185], v[208:211], v[80:83]
	v_mfma_f32_16x16x32_bf16 v[68:71], v[174:177], v[216:219], v[68:71]
	v_mfma_f32_16x16x32_bf16 v[64:67], v[182:185], v[216:219], v[64:67]
	s_setprio 0
	s_add_i32 s10, s10, s33
	v_lshl_add_u64 v[154:155], v[154:155], 0, s[8:9]
	s_mov_b32 m0, s10
	ds_read_b128 v[186:189], v149 offset:49152
	ds_read_b128 v[190:193], v149 offset:50176
	ds_read_b128 v[194:197], v149 offset:51200
	ds_read_b128 v[198:201], v149 offset:52224
	ds_read_b128 v[204:207], v149 offset:53248
	ds_read_b128 v[208:211], v149 offset:54272
	ds_read_b128 v[212:215], v149 offset:55296
	ds_read_b128 v[216:219], v149 offset:56320
	global_load_lds_dwordx4 v[154:155], off
	s_add_i32 m0, s10, 0x2000
	s_add_u32 s58, s58, 0x40080
	v_lshl_add_u64 v[154:155], v[220:221], 0, s[8:9]
	s_addc_u32 s59, s59, 0
	s_add_i32 s10, s11, s33
	global_load_lds_dwordx4 v[154:155], off
	v_lshl_add_u64 v[154:155], s[58:59], 0, v[132:133]
	s_mov_b32 m0, s10
	s_nop 0
	global_load_lds_dwordx4 v[154:155], off
	v_lshl_add_u64 v[154:155], s[58:59], 0, v[128:129]
	s_add_i32 m0, s10, 0x2000
	s_nop 0
	global_load_lds_dwordx4 v[154:155], off
	v_lshl_add_u64 v[154:155], v[222:223], 0, s[8:9]
	s_mov_b32 m0, s71
	s_nop 0
	global_load_lds_dwordx4 v[154:155], off
	v_lshl_add_u64 v[154:155], v[224:225], 0, s[8:9]
	s_mov_b32 m0, s72
	s_nop 0
	global_load_lds_dwordx4 v[154:155], off
	s_waitcnt vmcnt(8)
	s_waitcnt lgkmcnt(0)
	s_barrier
	s_setprio 1
	s_waitcnt lgkmcnt(0)
	v_mfma_f32_16x16x32_bf16 v[60:63], v[150:153], v[186:189], v[60:63]
	v_mfma_f32_16x16x32_bf16 v[56:59], v[162:165], v[186:189], v[56:59]
	v_mfma_f32_16x16x32_bf16 v[44:47], v[150:153], v[194:197], v[44:47]
	v_mfma_f32_16x16x32_bf16 v[40:43], v[162:165], v[194:197], v[40:43]
	v_mfma_f32_16x16x32_bf16 v[28:31], v[150:153], v[204:207], v[28:31]
	v_mfma_f32_16x16x32_bf16 v[24:27], v[162:165], v[204:207], v[24:27]
	v_mfma_f32_16x16x32_bf16 v[12:15], v[150:153], v[212:215], v[12:15]
	v_mfma_f32_16x16x32_bf16 v[8:11], v[162:165], v[212:215], v[8:11]
	v_mfma_f32_16x16x32_bf16 v[60:63], v[158:161], v[190:193], v[60:63]
	v_mfma_f32_16x16x32_bf16 v[56:59], v[166:169], v[190:193], v[56:59]
	v_mfma_f32_16x16x32_bf16 v[44:47], v[158:161], v[198:201], v[44:47]
	v_mfma_f32_16x16x32_bf16 v[40:43], v[166:169], v[198:201], v[40:43]
	v_mfma_f32_16x16x32_bf16 v[28:31], v[158:161], v[208:211], v[28:31]
	v_mfma_f32_16x16x32_bf16 v[24:27], v[166:169], v[208:211], v[24:27]
	v_mfma_f32_16x16x32_bf16 v[12:15], v[158:161], v[216:219], v[12:15]
	v_mfma_f32_16x16x32_bf16 v[8:11], v[166:169], v[216:219], v[8:11]
	s_setprio 0
	s_setprio 1
	v_mfma_f32_16x16x32_bf16 v[52:55], v[170:173], v[186:189], v[52:55]
	v_mfma_f32_16x16x32_bf16 v[48:51], v[178:181], v[186:189], v[48:51]
	v_mfma_f32_16x16x32_bf16 v[36:39], v[170:173], v[194:197], v[36:39]
	v_mfma_f32_16x16x32_bf16 v[32:35], v[178:181], v[194:197], v[32:35]
	v_mfma_f32_16x16x32_bf16 v[20:23], v[170:173], v[204:207], v[20:23]
	v_mfma_f32_16x16x32_bf16 v[16:19], v[178:181], v[204:207], v[16:19]
	v_mfma_f32_16x16x32_bf16 v[4:7], v[170:173], v[212:215], v[4:7]
	v_mfma_f32_16x16x32_bf16 v[0:3], v[178:181], v[212:215], v[0:3]
	s_barrier
	s_setprio 2
	v_mfma_f32_16x16x32_bf16 v[52:55], v[174:177], v[190:193], v[52:55]
	v_mfma_f32_16x16x32_bf16 v[48:51], v[182:185], v[190:193], v[48:51]
	v_mfma_f32_16x16x32_bf16 v[36:39], v[174:177], v[198:201], v[36:39]
	v_mfma_f32_16x16x32_bf16 v[32:35], v[182:185], v[198:201], v[32:35]
	v_mfma_f32_16x16x32_bf16 v[20:23], v[174:177], v[208:211], v[20:23]
	v_mfma_f32_16x16x32_bf16 v[16:19], v[182:185], v[208:211], v[16:19]
	v_mfma_f32_16x16x32_bf16 v[4:7], v[174:177], v[216:219], v[4:7]
	v_mfma_f32_16x16x32_bf16 v[0:3], v[182:185], v[216:219], v[0:3]
	s_setprio 0
	s_add_i32 s74, s74, 2
	s_add_u32 s50, s50, 0x100
	s_addc_u32 s51, s51, 0
	s_add_u32 s91, s91, 0x100
	s_addc_u32 s92, s92, 0
	s_cmp_gt_u32 s74, 13
	s_cbranch_scc0 .LBB0_207
	s_and_b64 vcc, exec, s[18:19]
	s_cbranch_vccz .LBB0_210
	s_barrier

; #define PG8_STAGE(bufoff, gbase, voff) do { _Pragma("unroll") for (int _i = 0; _i < 2; ++_i) \
;         __builtin_amdgcn_global_load_lds((const unsigned*)((const char*)(gbase) + (voff)[_i]), (PG8_LAS unsigned*)(lds + (bufoff) + ldsw + _i * 8192), 16, 0, 0); } while (0)
; #define PG8_LDA(dst, b, h) do { _Pragma("unroll") for (int m = 0; m < 4; ++m) _Pragma("unroll") for (int k = 0; k < 2; ++k) dst[m][k] = *(const PG8_LAS bf16x8*)(lds + PG8_SA(b, h) + aoff + m * 2048 + k * 1024); } while (0)
; #define PG8_LDB(dst, b, h) do { _Pragma("unroll") for (int n = 0; n < 2; ++n) _Pragma("unroll") for (int k = 0; k < 2; ++k) dst[n][k] = *(const PG8_LAS bf16x8*)(lds + PG8_SB(b, h) + boff + n * 2048 + k * 1024); } while (0)
; #define PG8_MMA(ai, bj, At, Bt) do { __builtin_amdgcn_s_setprio(1); _Pragma("unroll") for (int m = 0; m < 4; ++m) _Pragma("unroll") for (int n = 0; n < 2; ++n) _Pragma("unroll") for (int k = 0; k < 2; ++k) \
;         acc[ai][bj][m][n] = __builtin_amdgcn_mfma_f32_16x16x32_bf16(Bt[n][k], At[m][k], acc[ai][bj][m][n], 0, 0, 0); __builtin_amdgcn_s_setprio(0); } while (0)
; #define PG8_WAIT_V(n) asm volatile("s_waitcnt vmcnt(" #n ")" ::: "memory")
; #define PG8_WAIT_L(n) asm volatile("s_waitcnt lgkmcnt(" #n ")" ::: "memory")
; #define PG8_BAR __builtin_amdgcn_s_barrier()
; #define PG8_SCHED __builtin_amdgcn_sched_barrier(0)
; template <class Epi, class Sched, bool ALIGN_EPI = false, bool SP2 = false>
; __device__ __forceinline__ void gemm_phase(PG8_LAS unsigned char* lds, const Gemm g, const Sched& S, const Epi& E) {
;     ...
;             PG8_LDB(B0, 0, 0); PG8_LDB(B1, 0, 1); PG8_SCHED; PG8_LDA(At, 0, 0); PG8_STAGE(PG8_SA(1, 1), a1 + hstep, voffA);
;             PG8_WAIT_V(8); PG8_WAIT_L(0); PG8_BAR; PG8_MMA(0, 0, At, B0); PG8_MMA(0, 1, At, B1); PG8_BAR; PG8_SCHED;
;             PG8_LDA(At, 0, 1); PG8_STAGE(PG8_SB(0, 0), b2, voffB); PG8_STAGE(PG8_SB(0, 1), b2 + hstep, voffB); PG8_STAGE(PG8_SA(0, 0), a2, voffA);
;             PG8_WAIT_V(8); PG8_WAIT_L(0); PG8_BAR; PG8_MMA(1, 0, At, B0); PG8_MMA(1, 1, At, B1); PG8_BAR; PG8_SCHED;
.LBB0_287:
	ds_read_b128 v[144:147], v153
	ds_read_b128 v[158:161], v153 offset:1024
	ds_read_b128 v[162:165], v153 offset:2048
	ds_read_b128 v[166:169], v153 offset:3072
	ds_read_b128 v[170:173], v154
	ds_read_b128 v[174:177], v154 offset:1024
	ds_read_b128 v[178:181], v154 offset:2048
	ds_read_b128 v[182:185], v154 offset:3072
	s_add_u32 s50, s48, 0x100
	s_addc_u32 s51, s49, 0
	s_cmp_eq_u32 s90, 40
	s_cselect_b32 s61, s5, s51
	s_cselect_b32 s60, s4, s50
	s_cselect_b32 s59, s47, s75
	s_cselect_b32 s58, s46, s74
	v_lshl_add_u64 v[148:149], s[48:49], 0, v[136:137]
	s_add_i32 m0, s45, 0xc000
	ds_read_b128 v[186:189], v155
	ds_read_b128 v[190:193], v155 offset:1024
	ds_read_b128 v[194:197], v155 offset:2048
	ds_read_b128 v[198:201], v155 offset:3072
	ds_read_b128 v[204:207], v155 offset:4096
	ds_read_b128 v[208:211], v155 offset:5120
	ds_read_b128 v[212:215], v155 offset:6144
	ds_read_b128 v[216:219], v155 offset:7168
	global_load_lds_dwordx4 v[148:149], off
	v_lshl_add_u64 v[148:149], s[48:49], 0, v[138:139]
	s_add_i32 m0, s45, 0xe000
	s_nop 0
	global_load_lds_dwordx4 v[148:149], off
	s_waitcnt vmcnt(8)
	s_waitcnt lgkmcnt(0)
	s_barrier
	s_setprio 1
	s_waitcnt lgkmcnt(0)
	v_mfma_f32_16x16x32_bf16 v[124:127], v[144:147], v[186:189], v[124:127]
	v_mfma_f32_16x16x32_bf16 v[120:123], v[162:165], v[186:189], v[120:123]
	v_mfma_f32_16x16x32_bf16 v[116:119], v[144:147], v[194:197], v[116:119]
	v_mfma_f32_16x16x32_bf16 v[108:111], v[162:165], v[194:197], v[108:111]
	v_mfma_f32_16x16x32_bf16 v[92:95], v[144:147], v[204:207], v[92:95]
	v_mfma_f32_16x16x32_bf16 v[88:91], v[162:165], v[204:207], v[88:91]
	v_mfma_f32_16x16x32_bf16 v[84:87], v[144:147], v[212:215], v[84:87]
	v_mfma_f32_16x16x32_bf16 v[80:83], v[162:165], v[212:215], v[80:83]
	v_mfma_f32_16x16x32_bf16 v[124:127], v[158:161], v[190:193], v[124:127]
	v_mfma_f32_16x16x32_bf16 v[120:123], v[166:169], v[190:193], v[120:123]
	v_mfma_f32_16x16x32_bf16 v[116:119], v[158:161], v[198:201], v[116:119]
	v_mfma_f32_16x16x32_bf16 v[108:111], v[166:169], v[198:201], v[108:111]
	v_mfma_f32_16x16x32_bf16 v[92:95], v[158:161], v[208:211], v[92:95]
	v_mfma_f32_16x16x32_bf16 v[88:91], v[166:169], v[208:211], v[88:91]
	v_mfma_f32_16x16x32_bf16 v[84:87], v[158:161], v[216:219], v[84:87]
	v_mfma_f32_16x16x32_bf16 v[80:83], v[166:169], v[216:219], v[80:83]
	s_setprio 0
	s_setprio 1
	v_mfma_f32_16x16x32_bf16 v[112:115], v[170:173], v[186:189], v[112:115]
	v_mfma_f32_16x16x32_bf16 v[104:107], v[178:181], v[186:189], v[104:107]
	v_mfma_f32_16x16x32_bf16 v[100:103], v[170:173], v[194:197], v[100:103]
	v_mfma_f32_16x16x32_bf16 v[96:99], v[178:181], v[194:197], v[96:99]
	v_mfma_f32_16x16x32_bf16 v[76:79], v[170:173], v[204:207], v[76:79]
	v_mfma_f32_16x16x32_bf16 v[72:75], v[178:181], v[204:207], v[72:75]
	v_mfma_f32_16x16x32_bf16 v[68:71], v[170:173], v[212:215], v[68:71]
	v_mfma_f32_16x16x32_bf16 v[64:67], v[178:181], v[212:215], v[64:67]
	s_barrier
	s_setprio 2
	v_mfma_f32_16x16x32_bf16 v[112:115], v[174:177], v[190:193], v[112:115]
	v_mfma_f32_16x16x32_bf16 v[104:107], v[182:185], v[190:193], v[104:107]
	v_mfma_f32_16x16x32_bf16 v[100:103], v[174:177], v[198:201], v[100:103]
	v_mfma_f32_16x16x32_bf16 v[96:99], v[182:185], v[198:201], v[96:99]
	v_mfma_f32_16x16x32_bf16 v[76:79], v[174:177], v[208:211], v[76:79]
	v_mfma_f32_16x16x32_bf16 v[72:75], v[182:185], v[208:211], v[72:75]
	v_mfma_f32_16x16x32_bf16 v[68:71], v[174:177], v[216:219], v[68:71]
	v_mfma_f32_16x16x32_bf16 v[64:67], v[182:185], v[216:219], v[64:67]
	s_setprio 0
	s_add_i32 s10, s84, s33
	v_lshl_add_u64 v[148:149], s[58:59], 0, v[130:131]
	s_mov_b32 m0, s10
	ds_read_b128 v[186:189], v155 offset:16384
	ds_read_b128 v[190:193], v155 offset:17408
	ds_read_b128 v[194:197], v155 offset:18432
	ds_read_b128 v[198:201], v155 offset:19456
	ds_read_b128 v[204:207], v155 offset:20480
	ds_read_b128 v[208:211], v155 offset:21504
	ds_read_b128 v[212:215], v155 offset:22528
	ds_read_b128 v[216:219], v155 offset:23552
	global_load_lds_dwordx4 v[148:149], off
	s_add_i32 m0, s10, 0x2000
	s_add_u32 s48, s58, 0xb0000
	v_lshl_add_u64 v[220:221], s[58:59], 0, v[134:135]
	s_addc_u32 s49, s59, 0
	s_add_i32 s10, s85, s33
	global_load_lds_dwordx4 v[220:221], off
	v_lshl_add_u64 v[222:223], s[48:49], 0, v[130:131]
	s_mov_b32 m0, s10
	v_lshl_add_u64 v[224:225], s[60:61], 0, v[132:133]
	global_load_lds_dwordx4 v[222:223], off
	v_lshl_add_u64 v[222:223], s[48:49], 0, v[134:135]
	s_add_i32 m0, s10, 0x2000
	s_nop 0
	global_load_lds_dwordx4 v[222:223], off
	v_lshl_add_u64 v[222:223], s[60:61], 0, v[128:129]
	s_mov_b32 m0, s45
	s_nop 0
	global_load_lds_dwordx4 v[222:223], off
	s_mov_b32 m0, s62
	s_nop 0
	global_load_lds_dwordx4 v[224:225], off
	s_waitcnt vmcnt(8)
	s_waitcnt lgkmcnt(0)
	s_barrier
	s_setprio 1
	s_waitcnt lgkmcnt(0)
	v_mfma_f32_16x16x32_bf16 v[60:63], v[144:147], v[186:189], v[60:63]
	v_mfma_f32_16x16x32_bf16 v[56:59], v[162:165], v[186:189], v[56:59]
	v_mfma_f32_16x16x32_bf16 v[52:55], v[144:147], v[194:197], v[52:55]
	v_mfma_f32_16x16x32_bf16 v[48:51], v[162:165], v[194:197], v[48:51]
	v_mfma_f32_16x16x32_bf16 v[28:31], v[144:147], v[204:207], v[28:31]
	v_mfma_f32_16x16x32_bf16 v[24:27], v[162:165], v[204:207], v[24:27]
	v_mfma_f32_16x16x32_bf16 v[20:23], v[144:147], v[212:215], v[20:23]
	v_mfma_f32_16x16x32_bf16 v[16:19], v[162:165], v[212:215], v[16:19]
	v_mfma_f32_16x16x32_bf16 v[60:63], v[158:161], v[190:193], v[60:63]
	v_mfma_f32_16x16x32_bf16 v[56:59], v[166:169], v[190:193], v[56:59]
	v_mfma_f32_16x16x32_bf16 v[52:55], v[158:161], v[198:201], v[52:55]
	v_mfma_f32_16x16x32_bf16 v[48:51], v[166:169], v[198:201], v[48:51]
	v_mfma_f32_16x16x32_bf16 v[28:31], v[158:161], v[208:211], v[28:31]
	v_mfma_f32_16x16x32_bf16 v[24:27], v[166:169], v[208:211], v[24:27]
	v_mfma_f32_16x16x32_bf16 v[20:23], v[158:161], v[216:219], v[20:23]
	v_mfma_f32_16x16x32_bf16 v[16:19], v[166:169], v[216:219], v[16:19]
	s_setprio 0
	s_setprio 1
	v_mfma_f32_16x16x32_bf16 v[44:47], v[170:173], v[186:189], v[44:47]
	v_mfma_f32_16x16x32_bf16 v[40:43], v[178:181], v[186:189], v[40:43]
	v_mfma_f32_16x16x32_bf16 v[36:39], v[170:173], v[194:197], v[36:39]
	v_mfma_f32_16x16x32_bf16 v[32:35], v[178:181], v[194:197], v[32:35]
	v_mfma_f32_16x16x32_bf16 v[12:15], v[170:173], v[204:207], v[12:15]
	v_mfma_f32_16x16x32_bf16 v[8:11], v[178:181], v[204:207], v[8:11]
	v_mfma_f32_16x16x32_bf16 v[4:7], v[170:173], v[212:215], v[4:7]
	v_mfma_f32_16x16x32_bf16 v[0:3], v[178:181], v[212:215], v[0:3]
	s_barrier
; #define PG8_STAGE(bufoff, gbase, voff) do { _Pragma("unroll") for (int _i = 0; _i < 2; ++_i) \
;         __builtin_amdgcn_global_load_lds((const unsigned*)((const char*)(gbase) + (voff)[_i]), (PG8_LAS unsigned*)(lds + (bufoff) + ldsw + _i * 8192), 16, 0, 0); } while (0)
; #define PG8_LDA(dst, b, h) do { _Pragma("unroll") for (int m = 0; m < 4; ++m) _Pragma("unroll") for (int k = 0; k < 2; ++k) dst[m][k] = *(const PG8_LAS bf16x8*)(lds + PG8_SA(b, h) + aoff + m * 2048 + k * 1024); } while (0)
; #define PG8_LDB(dst, b, h) do { _Pragma("unroll") for (int n = 0; n < 2; ++n) _Pragma("unroll") for (int k = 0; k < 2; ++k) dst[n][k] = *(const PG8_LAS bf16x8*)(lds + PG8_SB(b, h) + boff + n * 2048 + k * 1024); } while (0)
; #define PG8_MMA(ai, bj, At, Bt) do { __builtin_amdgcn_s_setprio(1); _Pragma("unroll") for (int m = 0; m < 4; ++m) _Pragma("unroll") for (int n = 0; n < 2; ++n) _Pragma("unroll") for (int k = 0; k < 2; ++k) \
;         acc[ai][bj][m][n] = __builtin_amdgcn_mfma_f32_16x16x32_bf16(Bt[n][k], At[m][k], acc[ai][bj][m][n], 0, 0, 0); __builtin_amdgcn_s_setprio(0); } while (0)
; #define PG8_WAIT_V(n) asm volatile("s_waitcnt vmcnt(" #n ")" ::: "memory")
; #define PG8_WAIT_L(n) asm volatile("s_waitcnt lgkmcnt(" #n ")" ::: "memory")
; #define PG8_BAR __builtin_amdgcn_s_barrier()
; #define PG8_SCHED __builtin_amdgcn_sched_barrier(0)
; template <class Epi, class Sched, bool ALIGN_EPI = false, bool SP2 = false>
; __device__ __forceinline__ void gemm_phase(PG8_LAS unsigned char* lds, const Gemm g, const Sched& S, const Epi& E) {
;     ...
;             PG8_WAIT_V(8); PG8_WAIT_L(0); PG8_BAR; PG8_MMA(1, 0, At, B0); PG8_MMA(1, 1, At, B1); PG8_BAR; PG8_SCHED;
;             PG8_LDB(B0, 1, 0); PG8_LDB(B1, 1, 1); PG8_SCHED; PG8_LDA(At, 1, 0); PG8_STAGE(PG8_SA(0, 1), a2 + hstep, voffA);
;             PG8_WAIT_V(8); PG8_WAIT_L(0); PG8_BAR; PG8_MMA(0, 0, At, B0); PG8_MMA(0, 1, At, B1); PG8_BAR; PG8_SCHED;
	s_setprio 2
	v_mfma_f32_16x16x32_bf16 v[44:47], v[174:177], v[190:193], v[44:47]
	v_mfma_f32_16x16x32_bf16 v[40:43], v[182:185], v[190:193], v[40:43]
	v_mfma_f32_16x16x32_bf16 v[36:39], v[174:177], v[198:201], v[36:39]
	v_mfma_f32_16x16x32_bf16 v[32:35], v[182:185], v[198:201], v[32:35]
	v_mfma_f32_16x16x32_bf16 v[12:15], v[174:177], v[208:211], v[12:15]
	v_mfma_f32_16x16x32_bf16 v[8:11], v[182:185], v[208:211], v[8:11]
	v_mfma_f32_16x16x32_bf16 v[4:7], v[174:177], v[216:219], v[4:7]
	v_mfma_f32_16x16x32_bf16 v[0:3], v[182:185], v[216:219], v[0:3]
	s_setprio 0
	s_add_i32 s10, 0, 0x18000
	v_add_u32_e32 v157, s10, v151
	s_add_i32 s11, 0, 0x1c000
	ds_read_b128 v[144:147], v157
	ds_read_b128 v[158:161], v157 offset:1024
	ds_read_b128 v[162:165], v157 offset:2048
	ds_read_b128 v[166:169], v157 offset:3072
	v_add_u32_e32 v157, s11, v151
	ds_read_b128 v[170:173], v157
	ds_read_b128 v[174:177], v157 offset:1024
	ds_read_b128 v[178:181], v157 offset:2048
	ds_read_b128 v[182:185], v157 offset:3072
	s_add_u32 s48, s60, 0xb0000
	s_addc_u32 s49, s61, 0
	s_mov_b32 m0, s63
	v_lshl_add_u64 v[226:227], s[48:49], 0, v[128:129]
	ds_read_b128 v[186:189], v155 offset:32768
	ds_read_b128 v[190:193], v155 offset:33792
	ds_read_b128 v[194:197], v155 offset:34816
	ds_read_b128 v[198:201], v155 offset:35840
	ds_read_b128 v[204:207], v155 offset:36864
	ds_read_b128 v[208:211], v155 offset:37888
	ds_read_b128 v[212:215], v155 offset:38912
	ds_read_b128 v[216:219], v155 offset:39936
	global_load_lds_dwordx4 v[226:227], off
	v_lshl_add_u64 v[226:227], s[48:49], 0, v[132:133]
	s_mov_b32 m0, s64
	s_nop 0
	global_load_lds_dwordx4 v[226:227], off
	s_waitcnt vmcnt(8)
	s_waitcnt lgkmcnt(0)
	s_barrier
	s_setprio 1
	s_waitcnt lgkmcnt(0)
	v_mfma_f32_16x16x32_bf16 v[124:127], v[144:147], v[186:189], v[124:127]
	v_mfma_f32_16x16x32_bf16 v[120:123], v[162:165], v[186:189], v[120:123]
	v_mfma_f32_16x16x32_bf16 v[116:119], v[144:147], v[194:197], v[116:119]
	v_mfma_f32_16x16x32_bf16 v[108:111], v[162:165], v[194:197], v[108:111]
	v_mfma_f32_16x16x32_bf16 v[92:95], v[144:147], v[204:207], v[92:95]
	v_mfma_f32_16x16x32_bf16 v[88:91], v[162:165], v[204:207], v[88:91]
	v_mfma_f32_16x16x32_bf16 v[84:87], v[144:147], v[212:215], v[84:87]
	v_mfma_f32_16x16x32_bf16 v[80:83], v[162:165], v[212:215], v[80:83]
	v_mfma_f32_16x16x32_bf16 v[124:127], v[158:161], v[190:193], v[124:127]
	v_mfma_f32_16x16x32_bf16 v[120:123], v[166:169], v[190:193], v[120:123]
	v_mfma_f32_16x16x32_bf16 v[116:119], v[158:161], v[198:201], v[116:119]
	v_mfma_f32_16x16x32_bf16 v[108:111], v[166:169], v[198:201], v[108:111]
	v_mfma_f32_16x16x32_bf16 v[92:95], v[158:161], v[208:211], v[92:95]
	v_mfma_f32_16x16x32_bf16 v[88:91], v[166:169], v[208:211], v[88:91]
	v_mfma_f32_16x16x32_bf16 v[84:87], v[158:161], v[216:219], v[84:87]
	v_mfma_f32_16x16x32_bf16 v[80:83], v[166:169], v[216:219], v[80:83]
	s_setprio 0
	s_setprio 1
	v_mfma_f32_16x16x32_bf16 v[112:115], v[170:173], v[186:189], v[112:115]
	v_mfma_f32_16x16x32_bf16 v[104:107], v[178:181], v[186:189], v[104:107]
	v_mfma_f32_16x16x32_bf16 v[100:103], v[170:173], v[194:197], v[100:103]
	v_mfma_f32_16x16x32_bf16 v[96:99], v[178:181], v[194:197], v[96:99]
	v_mfma_f32_16x16x32_bf16 v[76:79], v[170:173], v[204:207], v[76:79]
	v_mfma_f32_16x16x32_bf16 v[72:75], v[178:181], v[204:207], v[72:75]
	v_mfma_f32_16x16x32_bf16 v[68:71], v[170:173], v[212:215], v[68:71]
	v_mfma_f32_16x16x32_bf16 v[64:67], v[178:181], v[212:215], v[64:67]
	s_barrier
; #define PG8_STAGE(bufoff, gbase, voff) do { _Pragma("unroll") for (int _i = 0; _i < 2; ++_i) \
;         __builtin_amdgcn_global_load_lds((const unsigned*)((const char*)(gbase) + (voff)[_i]), (PG8_LAS unsigned*)(lds + (bufoff) + ldsw + _i * 8192), 16, 0, 0); } while (0)
; #define PG8_LDA(dst, b, h) do { _Pragma("unroll") for (int m = 0; m < 4; ++m) _Pragma("unroll") for (int k = 0; k < 2; ++k) dst[m][k] = *(const PG8_LAS bf16x8*)(lds + PG8_SA(b, h) + aoff + m * 2048 + k * 1024); } while (0)
; #define PG8_MMA(ai, bj, At, Bt) do { __builtin_amdgcn_s_setprio(1); _Pragma("unroll") for (int m = 0; m < 4; ++m) _Pragma("unroll") for (int n = 0; n < 2; ++n) _Pragma("unroll") for (int k = 0; k < 2; ++k) \
;         acc[ai][bj][m][n] = __builtin_amdgcn_mfma_f32_16x16x32_bf16(Bt[n][k], At[m][k], acc[ai][bj][m][n], 0, 0, 0); __builtin_amdgcn_s_setprio(0); } while (0)
; #define PG8_WAIT_V(n) asm volatile("s_waitcnt vmcnt(" #n ")" ::: "memory")
; #define PG8_WAIT_L(n) asm volatile("s_waitcnt lgkmcnt(" #n ")" ::: "memory")
; #define PG8_BAR __builtin_amdgcn_s_barrier()
; #define PG8_SCHED __builtin_amdgcn_sched_barrier(0)
; template <class Epi, class Sched, bool ALIGN_EPI = false, bool SP2 = false>
; __device__ __forceinline__ void gemm_phase(PG8_LAS unsigned char* lds, const Gemm g, const Sched& S, const Epi& E) {
;     ...
;         for (int t = 0; t < nt; t += 2) {
;     ...
;             PG8_WAIT_V(8); PG8_WAIT_L(0); PG8_BAR; PG8_MMA(0, 0, At, B0); PG8_MMA(0, 1, At, B1); PG8_BAR; PG8_SCHED;
;             PG8_LDA(At, 1, 1); PG8_STAGE(PG8_SB(1, 0), b3, voffB); PG8_STAGE(PG8_SB(1, 1), b3 + hstep, voffB); PG8_STAGE(PG8_SA(1, 0), a3, voffA);
;             PG8_WAIT_V(8); PG8_WAIT_L(0); PG8_BAR; PG8_MMA(1, 0, At, B0); PG8_MMA(1, 1, At, B1); PG8_BAR; PG8_SCHED;
	s_setprio 2
	v_mfma_f32_16x16x32_bf16 v[112:115], v[174:177], v[190:193], v[112:115]
	v_mfma_f32_16x16x32_bf16 v[104:107], v[182:185], v[190:193], v[104:107]
	v_mfma_f32_16x16x32_bf16 v[100:103], v[174:177], v[198:201], v[100:103]
	v_mfma_f32_16x16x32_bf16 v[96:99], v[182:185], v[198:201], v[96:99]
	v_mfma_f32_16x16x32_bf16 v[76:79], v[174:177], v[208:211], v[76:79]
	v_mfma_f32_16x16x32_bf16 v[72:75], v[182:185], v[208:211], v[72:75]
	v_mfma_f32_16x16x32_bf16 v[68:71], v[174:177], v[216:219], v[68:71]
	v_mfma_f32_16x16x32_bf16 v[64:67], v[182:185], v[216:219], v[64:67]
	s_setprio 0
	s_add_i32 s10, s10, s33
	v_lshl_add_u64 v[148:149], v[148:149], 0, s[20:21]
	s_mov_b32 m0, s10
	ds_read_b128 v[186:189], v155 offset:49152
	ds_read_b128 v[190:193], v155 offset:50176
	ds_read_b128 v[194:197], v155 offset:51200
	ds_read_b128 v[198:201], v155 offset:52224
	ds_read_b128 v[204:207], v155 offset:53248
	ds_read_b128 v[208:211], v155 offset:54272
	ds_read_b128 v[212:215], v155 offset:55296
	ds_read_b128 v[216:219], v155 offset:56320
	global_load_lds_dwordx4 v[148:149], off
	s_add_i32 m0, s10, 0x2000
	s_add_u32 s48, s58, 0xb0080
	v_lshl_add_u64 v[148:149], v[220:221], 0, s[20:21]
	s_addc_u32 s49, s59, 0
	s_add_i32 s10, s11, s33
	global_load_lds_dwordx4 v[148:149], off
	v_lshl_add_u64 v[148:149], s[48:49], 0, v[130:131]
	s_mov_b32 m0, s10
	s_nop 0
	global_load_lds_dwordx4 v[148:149], off
	v_lshl_add_u64 v[148:149], s[48:49], 0, v[134:135]
	s_add_i32 m0, s10, 0x2000
	s_nop 0
	global_load_lds_dwordx4 v[148:149], off
	v_lshl_add_u64 v[148:149], v[222:223], 0, s[20:21]
	s_mov_b32 m0, s70
	s_nop 0
	global_load_lds_dwordx4 v[148:149], off
	v_lshl_add_u64 v[148:149], v[224:225], 0, s[20:21]
	s_mov_b32 m0, s71
	s_nop 0
	global_load_lds_dwordx4 v[148:149], off
	s_waitcnt vmcnt(8)
	s_waitcnt lgkmcnt(0)
	s_barrier
	s_setprio 1
	s_waitcnt lgkmcnt(0)
	v_mfma_f32_16x16x32_bf16 v[60:63], v[144:147], v[186:189], v[60:63]
	v_mfma_f32_16x16x32_bf16 v[56:59], v[162:165], v[186:189], v[56:59]
	v_mfma_f32_16x16x32_bf16 v[52:55], v[144:147], v[194:197], v[52:55]
	v_mfma_f32_16x16x32_bf16 v[48:51], v[162:165], v[194:197], v[48:51]
	v_mfma_f32_16x16x32_bf16 v[28:31], v[144:147], v[204:207], v[28:31]
	v_mfma_f32_16x16x32_bf16 v[24:27], v[162:165], v[204:207], v[24:27]
	v_mfma_f32_16x16x32_bf16 v[20:23], v[144:147], v[212:215], v[20:23]
	v_mfma_f32_16x16x32_bf16 v[16:19], v[162:165], v[212:215], v[16:19]
	v_mfma_f32_16x16x32_bf16 v[60:63], v[158:161], v[190:193], v[60:63]
	v_mfma_f32_16x16x32_bf16 v[56:59], v[166:169], v[190:193], v[56:59]
	v_mfma_f32_16x16x32_bf16 v[52:55], v[158:161], v[198:201], v[52:55]
	v_mfma_f32_16x16x32_bf16 v[48:51], v[166:169], v[198:201], v[48:51]
	v_mfma_f32_16x16x32_bf16 v[28:31], v[158:161], v[208:211], v[28:31]
	v_mfma_f32_16x16x32_bf16 v[24:27], v[166:169], v[208:211], v[24:27]
	v_mfma_f32_16x16x32_bf16 v[20:23], v[158:161], v[216:219], v[20:23]
	v_mfma_f32_16x16x32_bf16 v[16:19], v[166:169], v[216:219], v[16:19]
	s_setprio 0
	s_setprio 1
	v_mfma_f32_16x16x32_bf16 v[44:47], v[170:173], v[186:189], v[44:47]
	v_mfma_f32_16x16x32_bf16 v[40:43], v[178:181], v[186:189], v[40:43]
	v_mfma_f32_16x16x32_bf16 v[36:39], v[170:173], v[194:197], v[36:39]
	v_mfma_f32_16x16x32_bf16 v[32:35], v[178:181], v[194:197], v[32:35]
	v_mfma_f32_16x16x32_bf16 v[12:15], v[170:173], v[204:207], v[12:15]
	v_mfma_f32_16x16x32_bf16 v[8:11], v[178:181], v[204:207], v[8:11]
	v_mfma_f32_16x16x32_bf16 v[4:7], v[170:173], v[212:215], v[4:7]
	v_mfma_f32_16x16x32_bf16 v[0:3], v[178:181], v[212:215], v[0:3]
	s_barrier
	s_setprio 2
	v_mfma_f32_16x16x32_bf16 v[44:47], v[174:177], v[190:193], v[44:47]
	v_mfma_f32_16x16x32_bf16 v[40:43], v[182:185], v[190:193], v[40:43]
	v_mfma_f32_16x16x32_bf16 v[36:39], v[174:177], v[198:201], v[36:39]
	v_mfma_f32_16x16x32_bf16 v[32:35], v[182:185], v[198:201], v[32:35]
	v_mfma_f32_16x16x32_bf16 v[12:15], v[174:177], v[208:211], v[12:15]
	v_mfma_f32_16x16x32_bf16 v[8:11], v[182:185], v[208:211], v[8:11]
	v_mfma_f32_16x16x32_bf16 v[4:7], v[174:177], v[216:219], v[4:7]
	v_mfma_f32_16x16x32_bf16 v[0:3], v[182:185], v[216:219], v[0:3]
	s_setprio 0
	s_add_i32 s90, s90, 2
	s_add_u32 s74, s74, 0x100
	s_addc_u32 s75, s75, 0
	s_cmp_gt_u32 s90, 41
	s_mov_b64 s[48:49], s[50:51]
	s_cbranch_scc0 .LBB0_287
	s_and_b64 vcc, exec, s[22:23]
	s_cbranch_vccz .LBB0_290
	s_barrier

; #define PG8_STAGE(bufoff, gbase, voff) do { _Pragma("unroll") for (int _i = 0; _i < 2; ++_i) \
;         __builtin_amdgcn_global_load_lds((const unsigned*)((const char*)(gbase) + (voff)[_i]), (PG8_LAS unsigned*)(lds + (bufoff) + ldsw + _i * 8192), 16, 0, 0); } while (0)
; #define PG8_LDA(dst, b, h) do { _Pragma("unroll") for (int m = 0; m < 4; ++m) _Pragma("unroll") for (int k = 0; k < 2; ++k) dst[m][k] = *(const PG8_LAS bf16x8*)(lds + PG8_SA(b, h) + aoff + m * 2048 + k * 1024); } while (0)
; #define PG8_LDB(dst, b, h) do { _Pragma("unroll") for (int n = 0; n < 2; ++n) _Pragma("unroll") for (int k = 0; k < 2; ++k) dst[n][k] = *(const PG8_LAS bf16x8*)(lds + PG8_SB(b, h) + boff + n * 2048 + k * 1024); } while (0)
; #define PG8_MMA(ai, bj, At, Bt) do { __builtin_amdgcn_s_setprio(1); _Pragma("unroll") for (int m = 0; m < 4; ++m) _Pragma("unroll") for (int n = 0; n < 2; ++n) _Pragma("unroll") for (int k = 0; k < 2; ++k) \
;         acc[ai][bj][m][n] = __builtin_amdgcn_mfma_f32_16x16x32_bf16(Bt[n][k], At[m][k], acc[ai][bj][m][n], 0, 0, 0); __builtin_amdgcn_s_setprio(0); } while (0)
; #define PG8_WAIT_V(n) asm volatile("s_waitcnt vmcnt(" #n ")" ::: "memory")
; #define PG8_WAIT_L(n) asm volatile("s_waitcnt lgkmcnt(" #n ")" ::: "memory")
; #define PG8_BAR __builtin_amdgcn_s_barrier()
; #define PG8_SCHED __builtin_amdgcn_sched_barrier(0)
; template <class Epi, class Sched, bool ALIGN_EPI = false, bool SP2 = false>
; __device__ __forceinline__ void gemm_phase(PG8_LAS unsigned char* lds, const Gemm g, const Sched& S, const Epi& E) {
;     ...
;             PG8_LDB(B0, 0, 0); PG8_LDB(B1, 0, 1); PG8_SCHED; PG8_LDA(At, 0, 0); PG8_STAGE(PG8_SA(1, 1), a1 + hstep, voffA);
;             PG8_WAIT_V(8); PG8_WAIT_L(0); PG8_BAR; PG8_MMA(0, 0, At, B0); PG8_MMA(0, 1, At, B1); PG8_BAR; PG8_SCHED;
;             PG8_LDA(At, 0, 1); PG8_STAGE(PG8_SB(0, 0), b2, voffB); PG8_STAGE(PG8_SB(0, 1), b2 + hstep, voffB); PG8_STAGE(PG8_SA(0, 0), a2, voffA);
;             PG8_WAIT_V(8); PG8_WAIT_L(0); PG8_BAR; PG8_MMA(1, 0, At, B0); PG8_MMA(1, 1, At, B1); PG8_BAR; PG8_SCHED;
.LBB0_413:
	ds_read_b128 v[150:153], v162
	ds_read_b128 v[168:171], v162 offset:1024
	ds_read_b128 v[172:175], v162 offset:2048
	ds_read_b128 v[176:179], v162 offset:3072
	ds_read_b128 v[180:183], v163
	ds_read_b128 v[184:187], v163 offset:1024
	ds_read_b128 v[188:191], v163 offset:2048
	ds_read_b128 v[192:195], v163 offset:3072
	s_add_u32 s10, s82, 0xfffc0080
	s_addc_u32 s11, s83, -1
	s_cmp_eq_u32 s75, 12
	s_cselect_b32 s87, s59, s11
	s_cselect_b32 s86, s65, s10
	s_cselect_b32 s85, s57, s74
	s_cselect_b32 s84, vcc_lo, vcc_hi
	v_lshl_add_u64 v[154:155], s[82:83], 0, v[142:143]
	s_add_i32 m0, s90, 0xc000
	ds_read_b128 v[196:199], v164
	ds_read_b128 v[204:207], v164 offset:1024
	ds_read_b128 v[208:211], v164 offset:2048
	ds_read_b128 v[212:215], v164 offset:3072
	ds_read_b128 v[216:219], v164 offset:4096
	ds_read_b128 v[220:223], v164 offset:5120
	ds_read_b128 v[224:227], v164 offset:6144
	ds_read_b128 v[228:231], v164 offset:7168
	global_load_lds_dwordx4 v[154:155], off
	v_lshl_add_u64 v[154:155], s[82:83], 0, v[144:145]
	s_add_i32 m0, s90, 0xe000
	s_nop 0
	global_load_lds_dwordx4 v[154:155], off
	s_waitcnt vmcnt(8)
	s_waitcnt lgkmcnt(0)
	s_barrier
	s_setprio 1
	s_waitcnt lgkmcnt(0)
	v_mfma_f32_16x16x32_bf16 v[124:127], v[150:153], v[196:199], v[124:127]
	v_mfma_f32_16x16x32_bf16 v[120:123], v[172:175], v[196:199], v[120:123]
	v_mfma_f32_16x16x32_bf16 v[108:111], v[150:153], v[208:211], v[108:111]
	v_mfma_f32_16x16x32_bf16 v[104:107], v[172:175], v[208:211], v[104:107]
	v_mfma_f32_16x16x32_bf16 v[92:95], v[150:153], v[216:219], v[92:95]
	v_mfma_f32_16x16x32_bf16 v[88:91], v[172:175], v[216:219], v[88:91]
	v_mfma_f32_16x16x32_bf16 v[76:79], v[150:153], v[224:227], v[76:79]
	v_mfma_f32_16x16x32_bf16 v[72:75], v[172:175], v[224:227], v[72:75]
	v_mfma_f32_16x16x32_bf16 v[124:127], v[168:171], v[204:207], v[124:127]
	v_mfma_f32_16x16x32_bf16 v[120:123], v[176:179], v[204:207], v[120:123]
	v_mfma_f32_16x16x32_bf16 v[108:111], v[168:171], v[212:215], v[108:111]
	v_mfma_f32_16x16x32_bf16 v[104:107], v[176:179], v[212:215], v[104:107]
	v_mfma_f32_16x16x32_bf16 v[92:95], v[168:171], v[220:223], v[92:95]
	v_mfma_f32_16x16x32_bf16 v[88:91], v[176:179], v[220:223], v[88:91]
	v_mfma_f32_16x16x32_bf16 v[76:79], v[168:171], v[228:231], v[76:79]
	v_mfma_f32_16x16x32_bf16 v[72:75], v[176:179], v[228:231], v[72:75]
	s_setprio 0
	s_setprio 1
	v_mfma_f32_16x16x32_bf16 v[116:119], v[180:183], v[196:199], v[116:119]
	v_mfma_f32_16x16x32_bf16 v[112:115], v[188:191], v[196:199], v[112:115]
	v_mfma_f32_16x16x32_bf16 v[100:103], v[180:183], v[208:211], v[100:103]
	v_mfma_f32_16x16x32_bf16 v[96:99], v[188:191], v[208:211], v[96:99]
	v_mfma_f32_16x16x32_bf16 v[84:87], v[180:183], v[216:219], v[84:87]
	v_mfma_f32_16x16x32_bf16 v[80:83], v[188:191], v[216:219], v[80:83]
	v_mfma_f32_16x16x32_bf16 v[68:71], v[180:183], v[224:227], v[68:71]
	v_mfma_f32_16x16x32_bf16 v[64:67], v[188:191], v[224:227], v[64:67]
	s_barrier
	s_setprio 2
	v_mfma_f32_16x16x32_bf16 v[116:119], v[184:187], v[204:207], v[116:119]
	v_mfma_f32_16x16x32_bf16 v[112:115], v[192:195], v[204:207], v[112:115]
	v_mfma_f32_16x16x32_bf16 v[100:103], v[184:187], v[212:215], v[100:103]
	v_mfma_f32_16x16x32_bf16 v[96:99], v[192:195], v[212:215], v[96:99]
	v_mfma_f32_16x16x32_bf16 v[84:87], v[184:187], v[220:223], v[84:87]
	v_mfma_f32_16x16x32_bf16 v[80:83], v[192:195], v[220:223], v[80:83]
	v_mfma_f32_16x16x32_bf16 v[68:71], v[184:187], v[228:231], v[68:71]
	v_mfma_f32_16x16x32_bf16 v[64:67], v[192:195], v[228:231], v[64:67]
	s_setprio 0
	s_add_i32 s10, s71, s88
	v_lshl_add_u64 v[154:155], s[84:85], 0, v[132:133]
	s_mov_b32 m0, s10
	ds_read_b128 v[196:199], v164 offset:16384
	ds_read_b128 v[204:207], v164 offset:17408
	ds_read_b128 v[208:211], v164 offset:18432
	ds_read_b128 v[212:215], v164 offset:19456
	ds_read_b128 v[216:219], v164 offset:20480
	ds_read_b128 v[220:223], v164 offset:21504
	ds_read_b128 v[224:227], v164 offset:22528
	ds_read_b128 v[228:231], v164 offset:23552
	global_load_lds_dwordx4 v[154:155], off
	s_add_i32 m0, s10, 0x2000
	s_add_u32 s10, s84, 0x40000
	v_lshl_add_u64 v[200:201], s[84:85], 0, v[128:129]
	s_addc_u32 s11, s85, 0
	s_add_i32 s48, s72, s88
	global_load_lds_dwordx4 v[200:201], off
	v_lshl_add_u64 v[232:233], s[10:11], 0, v[132:133]
	s_mov_b32 m0, s48
	v_lshl_add_u64 v[234:235], s[86:87], 0, v[130:131]
	global_load_lds_dwordx4 v[232:233], off
	v_lshl_add_u64 v[232:233], s[10:11], 0, v[128:129]
	s_add_i32 m0, s48, 0x2000
	s_nop 0
	global_load_lds_dwordx4 v[232:233], off
	v_lshl_add_u64 v[232:233], s[86:87], 0, v[134:135]
	s_mov_b32 m0, s90
	s_nop 0
	global_load_lds_dwordx4 v[232:233], off
	s_mov_b32 m0, s91
	s_nop 0
	global_load_lds_dwordx4 v[234:235], off
	s_waitcnt vmcnt(8)
	s_waitcnt lgkmcnt(0)
	s_barrier
	s_setprio 1
	s_waitcnt lgkmcnt(0)
	v_mfma_f32_16x16x32_bf16 v[60:63], v[150:153], v[196:199], v[60:63]
	v_mfma_f32_16x16x32_bf16 v[56:59], v[172:175], v[196:199], v[56:59]
	v_mfma_f32_16x16x32_bf16 v[44:47], v[150:153], v[208:211], v[44:47]
	v_mfma_f32_16x16x32_bf16 v[36:39], v[172:175], v[208:211], v[36:39]
	v_mfma_f32_16x16x32_bf16 v[28:31], v[150:153], v[216:219], v[28:31]
	v_mfma_f32_16x16x32_bf16 v[24:27], v[172:175], v[216:219], v[24:27]
	v_mfma_f32_16x16x32_bf16 v[12:15], v[150:153], v[224:227], v[12:15]
	v_mfma_f32_16x16x32_bf16 v[4:7], v[172:175], v[224:227], v[4:7]
	v_mfma_f32_16x16x32_bf16 v[60:63], v[168:171], v[204:207], v[60:63]
	v_mfma_f32_16x16x32_bf16 v[56:59], v[176:179], v[204:207], v[56:59]
	v_mfma_f32_16x16x32_bf16 v[44:47], v[168:171], v[212:215], v[44:47]
	v_mfma_f32_16x16x32_bf16 v[36:39], v[176:179], v[212:215], v[36:39]
	v_mfma_f32_16x16x32_bf16 v[28:31], v[168:171], v[220:223], v[28:31]
	v_mfma_f32_16x16x32_bf16 v[24:27], v[176:179], v[220:223], v[24:27]
	v_mfma_f32_16x16x32_bf16 v[12:15], v[168:171], v[228:231], v[12:15]
	v_mfma_f32_16x16x32_bf16 v[4:7], v[176:179], v[228:231], v[4:7]
	s_setprio 0
	s_setprio 1
	v_mfma_f32_16x16x32_bf16 v[52:55], v[180:183], v[196:199], v[52:55]
	v_mfma_f32_16x16x32_bf16 v[48:51], v[188:191], v[196:199], v[48:51]
	v_mfma_f32_16x16x32_bf16 v[40:43], v[180:183], v[208:211], v[40:43]
	v_mfma_f32_16x16x32_bf16 v[32:35], v[188:191], v[208:211], v[32:35]
	v_mfma_f32_16x16x32_bf16 v[20:23], v[180:183], v[216:219], v[20:23]
	v_mfma_f32_16x16x32_bf16 v[16:19], v[188:191], v[216:219], v[16:19]
	v_mfma_f32_16x16x32_bf16 v[8:11], v[180:183], v[224:227], v[8:11]
	v_mfma_f32_16x16x32_bf16 v[0:3], v[188:191], v[224:227], v[0:3]
	s_barrier
; #define PG8_STAGE(bufoff, gbase, voff) do { _Pragma("unroll") for (int _i = 0; _i < 2; ++_i) \
;         __builtin_amdgcn_global_load_lds((const unsigned*)((const char*)(gbase) + (voff)[_i]), (PG8_LAS unsigned*)(lds + (bufoff) + ldsw + _i * 8192), 16, 0, 0); } while (0)
; #define PG8_LDA(dst, b, h) do { _Pragma("unroll") for (int m = 0; m < 4; ++m) _Pragma("unroll") for (int k = 0; k < 2; ++k) dst[m][k] = *(const PG8_LAS bf16x8*)(lds + PG8_SA(b, h) + aoff + m * 2048 + k * 1024); } while (0)
; #define PG8_LDB(dst, b, h) do { _Pragma("unroll") for (int n = 0; n < 2; ++n) _Pragma("unroll") for (int k = 0; k < 2; ++k) dst[n][k] = *(const PG8_LAS bf16x8*)(lds + PG8_SB(b, h) + boff + n * 2048 + k * 1024); } while (0)
; #define PG8_MMA(ai, bj, At, Bt) do { __builtin_amdgcn_s_setprio(1); _Pragma("unroll") for (int m = 0; m < 4; ++m) _Pragma("unroll") for (int n = 0; n < 2; ++n) _Pragma("unroll") for (int k = 0; k < 2; ++k) \
;         acc[ai][bj][m][n] = __builtin_amdgcn_mfma_f32_16x16x32_bf16(Bt[n][k], At[m][k], acc[ai][bj][m][n], 0, 0, 0); __builtin_amdgcn_s_setprio(0); } while (0)
; #define PG8_WAIT_V(n) asm volatile("s_waitcnt vmcnt(" #n ")" ::: "memory")
; #define PG8_WAIT_L(n) asm volatile("s_waitcnt lgkmcnt(" #n ")" ::: "memory")
; #define PG8_BAR __builtin_amdgcn_s_barrier()
; #define PG8_SCHED __builtin_amdgcn_sched_barrier(0)
; template <class Epi, class Sched, bool ALIGN_EPI = false, bool SP2 = false>
; __device__ __forceinline__ void gemm_phase(PG8_LAS unsigned char* lds, const Gemm g, const Sched& S, const Epi& E) {
;     ...
;             PG8_WAIT_V(8); PG8_WAIT_L(0); PG8_BAR; PG8_MMA(1, 0, At, B0); PG8_MMA(1, 1, At, B1); PG8_BAR; PG8_SCHED;
;             PG8_LDB(B0, 1, 0); PG8_LDB(B1, 1, 1); PG8_SCHED; PG8_LDA(At, 1, 0); PG8_STAGE(PG8_SA(0, 1), a2 + hstep, voffA);
;             PG8_WAIT_V(8); PG8_WAIT_L(0); PG8_BAR; PG8_MMA(0, 0, At, B0); PG8_MMA(0, 1, At, B1); PG8_BAR; PG8_SCHED;
	s_setprio 2
	v_mfma_f32_16x16x32_bf16 v[52:55], v[184:187], v[204:207], v[52:55]
	v_mfma_f32_16x16x32_bf16 v[48:51], v[192:195], v[204:207], v[48:51]
	v_mfma_f32_16x16x32_bf16 v[40:43], v[184:187], v[212:215], v[40:43]
	v_mfma_f32_16x16x32_bf16 v[32:35], v[192:195], v[212:215], v[32:35]
	v_mfma_f32_16x16x32_bf16 v[20:23], v[184:187], v[220:223], v[20:23]
	v_mfma_f32_16x16x32_bf16 v[16:19], v[192:195], v[220:223], v[16:19]
	v_mfma_f32_16x16x32_bf16 v[8:11], v[184:187], v[228:231], v[8:11]
	v_mfma_f32_16x16x32_bf16 v[0:3], v[192:195], v[228:231], v[0:3]
	s_setprio 0
	s_add_i32 s48, 0, 0x18000
	v_add_u32_e32 v136, s48, v158
	s_add_i32 s49, 0, 0x1c000
	ds_read_b128 v[150:153], v136
	ds_read_b128 v[168:171], v136 offset:1024
	ds_read_b128 v[172:175], v136 offset:2048
	ds_read_b128 v[176:179], v136 offset:3072
	v_add_u32_e32 v136, s49, v158
	ds_read_b128 v[180:183], v136
	ds_read_b128 v[184:187], v136 offset:1024
	ds_read_b128 v[188:191], v136 offset:2048
	ds_read_b128 v[192:195], v136 offset:3072
	s_add_u32 s10, s86, 0x40000
	s_addc_u32 s11, s87, 0
	s_mov_b32 m0, s92
	v_lshl_add_u64 v[236:237], s[10:11], 0, v[134:135]
	ds_read_b128 v[196:199], v164 offset:32768
	ds_read_b128 v[204:207], v164 offset:33792
	ds_read_b128 v[208:211], v164 offset:34816
	ds_read_b128 v[212:215], v164 offset:35840
	ds_read_b128 v[216:219], v164 offset:36864
	ds_read_b128 v[220:223], v164 offset:37888
	ds_read_b128 v[224:227], v164 offset:38912
	ds_read_b128 v[228:231], v164 offset:39936
	global_load_lds_dwordx4 v[236:237], off
	v_lshl_add_u64 v[236:237], s[10:11], 0, v[130:131]
	s_mov_b32 m0, s93
	s_nop 0
	global_load_lds_dwordx4 v[236:237], off
	s_waitcnt vmcnt(8)
	s_waitcnt lgkmcnt(0)
	s_barrier
	s_setprio 1
	s_waitcnt lgkmcnt(0)
	v_mfma_f32_16x16x32_bf16 v[124:127], v[150:153], v[196:199], v[124:127]
	v_mfma_f32_16x16x32_bf16 v[120:123], v[172:175], v[196:199], v[120:123]
	v_mfma_f32_16x16x32_bf16 v[108:111], v[150:153], v[208:211], v[108:111]
	v_mfma_f32_16x16x32_bf16 v[104:107], v[172:175], v[208:211], v[104:107]
	v_mfma_f32_16x16x32_bf16 v[92:95], v[150:153], v[216:219], v[92:95]
	v_mfma_f32_16x16x32_bf16 v[88:91], v[172:175], v[216:219], v[88:91]
	v_mfma_f32_16x16x32_bf16 v[76:79], v[150:153], v[224:227], v[76:79]
	v_mfma_f32_16x16x32_bf16 v[72:75], v[172:175], v[224:227], v[72:75]
	v_mfma_f32_16x16x32_bf16 v[124:127], v[168:171], v[204:207], v[124:127]
	v_mfma_f32_16x16x32_bf16 v[120:123], v[176:179], v[204:207], v[120:123]
	v_mfma_f32_16x16x32_bf16 v[108:111], v[168:171], v[212:215], v[108:111]
	v_mfma_f32_16x16x32_bf16 v[104:107], v[176:179], v[212:215], v[104:107]
	v_mfma_f32_16x16x32_bf16 v[92:95], v[168:171], v[220:223], v[92:95]
	v_mfma_f32_16x16x32_bf16 v[88:91], v[176:179], v[220:223], v[88:91]
	v_mfma_f32_16x16x32_bf16 v[76:79], v[168:171], v[228:231], v[76:79]
	v_mfma_f32_16x16x32_bf16 v[72:75], v[176:179], v[228:231], v[72:75]
	s_setprio 0
	s_setprio 1
	v_mfma_f32_16x16x32_bf16 v[116:119], v[180:183], v[196:199], v[116:119]
	v_mfma_f32_16x16x32_bf16 v[112:115], v[188:191], v[196:199], v[112:115]
	v_mfma_f32_16x16x32_bf16 v[100:103], v[180:183], v[208:211], v[100:103]
	v_mfma_f32_16x16x32_bf16 v[96:99], v[188:191], v[208:211], v[96:99]
	v_mfma_f32_16x16x32_bf16 v[84:87], v[180:183], v[216:219], v[84:87]
	v_mfma_f32_16x16x32_bf16 v[80:83], v[188:191], v[216:219], v[80:83]
	v_mfma_f32_16x16x32_bf16 v[68:71], v[180:183], v[224:227], v[68:71]
	v_mfma_f32_16x16x32_bf16 v[64:67], v[188:191], v[224:227], v[64:67]
	s_barrier
; #define PG8_STAGE(bufoff, gbase, voff) do { _Pragma("unroll") for (int _i = 0; _i < 2; ++_i) \
;         __builtin_amdgcn_global_load_lds((const unsigned*)((const char*)(gbase) + (voff)[_i]), (PG8_LAS unsigned*)(lds + (bufoff) + ldsw + _i * 8192), 16, 0, 0); } while (0)
; #define PG8_LDA(dst, b, h) do { _Pragma("unroll") for (int m = 0; m < 4; ++m) _Pragma("unroll") for (int k = 0; k < 2; ++k) dst[m][k] = *(const PG8_LAS bf16x8*)(lds + PG8_SA(b, h) + aoff + m * 2048 + k * 1024); } while (0)
; #define PG8_LDB(dst, b, h) do { _Pragma("unroll") for (int n = 0; n < 2; ++n) _Pragma("unroll") for (int k = 0; k < 2; ++k) dst[n][k] = *(const PG8_LAS bf16x8*)(lds + PG8_SB(b, h) + boff + n * 2048 + k * 1024); } while (0)
; #define PG8_MMA(ai, bj, At, Bt) do { __builtin_amdgcn_s_setprio(1); _Pragma("unroll") for (int m = 0; m < 4; ++m) _Pragma("unroll") for (int n = 0; n < 2; ++n) _Pragma("unroll") for (int k = 0; k < 2; ++k) \
;         acc[ai][bj][m][n] = __builtin_amdgcn_mfma_f32_16x16x32_bf16(Bt[n][k], At[m][k], acc[ai][bj][m][n], 0, 0, 0); __builtin_amdgcn_s_setprio(0); } while (0)
; #define PG8_WAIT_V(n) asm volatile("s_waitcnt vmcnt(" #n ")" ::: "memory")
; #define PG8_WAIT_L(n) asm volatile("s_waitcnt lgkmcnt(" #n ")" ::: "memory")
; #define PG8_BAR __builtin_amdgcn_s_barrier()
; #define PG8_SCHED __builtin_amdgcn_sched_barrier(0)
; template <class Epi, class Sched, bool ALIGN_EPI = false, bool SP2 = false>
; __device__ __forceinline__ void gemm_phase(PG8_LAS unsigned char* lds, const Gemm g, const Sched& S, const Epi& E) {
;     ...
;             PG8_LDB(B0, 1, 0); PG8_LDB(B1, 1, 1); PG8_SCHED; PG8_LDA(At, 1, 0); PG8_STAGE(PG8_SA(0, 1), a2 + hstep, voffA);
;             PG8_WAIT_V(8); PG8_WAIT_L(0); PG8_BAR; PG8_MMA(0, 0, At, B0); PG8_MMA(0, 1, At, B1); PG8_BAR; PG8_SCHED;
;             PG8_LDA(At, 1, 1); PG8_STAGE(PG8_SB(1, 0), b3, voffB); PG8_STAGE(PG8_SB(1, 1), b3 + hstep, voffB); PG8_STAGE(PG8_SA(1, 0), a3, voffA);
;             PG8_WAIT_V(8); PG8_WAIT_L(0); PG8_BAR; PG8_MMA(1, 0, At, B0); PG8_MMA(1, 1, At, B1); PG8_BAR; PG8_SCHED;
;     ...
;         if constexpr (ALIGN_EPI) { if (wr == 0) PG8_BAR; }
	s_setprio 2
	v_mfma_f32_16x16x32_bf16 v[116:119], v[184:187], v[204:207], v[116:119]
	v_mfma_f32_16x16x32_bf16 v[112:115], v[192:195], v[204:207], v[112:115]
	v_mfma_f32_16x16x32_bf16 v[100:103], v[184:187], v[212:215], v[100:103]
	v_mfma_f32_16x16x32_bf16 v[96:99], v[192:195], v[212:215], v[96:99]
	v_mfma_f32_16x16x32_bf16 v[84:87], v[184:187], v[220:223], v[84:87]
	v_mfma_f32_16x16x32_bf16 v[80:83], v[192:195], v[220:223], v[80:83]
	v_mfma_f32_16x16x32_bf16 v[68:71], v[184:187], v[228:231], v[68:71]
	v_mfma_f32_16x16x32_bf16 v[64:67], v[192:195], v[228:231], v[64:67]
	s_setprio 0
	s_add_i32 s10, s48, s88
	v_lshl_add_u64 v[154:155], v[154:155], 0, s[44:45]
	s_mov_b32 m0, s10
	ds_read_b128 v[196:199], v164 offset:49152
	ds_read_b128 v[204:207], v164 offset:50176
	ds_read_b128 v[208:211], v164 offset:51200
	ds_read_b128 v[212:215], v164 offset:52224
	ds_read_b128 v[216:219], v164 offset:53248
	ds_read_b128 v[220:223], v164 offset:54272
	ds_read_b128 v[224:227], v164 offset:55296
	ds_read_b128 v[228:231], v164 offset:56320
	global_load_lds_dwordx4 v[154:155], off
	s_add_i32 m0, s10, 0x2000
	s_add_u32 s10, s84, 0x40080
	v_lshl_add_u64 v[154:155], v[200:201], 0, s[44:45]
	s_addc_u32 s11, s85, 0
	s_add_i32 s48, s49, s88
	global_load_lds_dwordx4 v[154:155], off
	v_lshl_add_u64 v[154:155], s[10:11], 0, v[132:133]
	s_mov_b32 m0, s48
	s_nop 0
	global_load_lds_dwordx4 v[154:155], off
	v_lshl_add_u64 v[154:155], s[10:11], 0, v[128:129]
	s_add_i32 m0, s48, 0x2000
	s_nop 0
	global_load_lds_dwordx4 v[154:155], off
	v_lshl_add_u64 v[154:155], v[232:233], 0, s[44:45]
	s_mov_b32 m0, s95
	s_nop 0
	global_load_lds_dwordx4 v[154:155], off
	v_lshl_add_u64 v[154:155], v[234:235], 0, s[44:45]
	s_mov_b32 m0, s96
	s_nop 0
	global_load_lds_dwordx4 v[154:155], off
	s_waitcnt vmcnt(8)
	s_waitcnt lgkmcnt(0)
	s_barrier
	s_setprio 1
	s_waitcnt lgkmcnt(0)
	v_mfma_f32_16x16x32_bf16 v[60:63], v[150:153], v[196:199], v[60:63]
	v_mfma_f32_16x16x32_bf16 v[56:59], v[172:175], v[196:199], v[56:59]
	v_mfma_f32_16x16x32_bf16 v[44:47], v[150:153], v[208:211], v[44:47]
	v_mfma_f32_16x16x32_bf16 v[36:39], v[172:175], v[208:211], v[36:39]
	v_mfma_f32_16x16x32_bf16 v[28:31], v[150:153], v[216:219], v[28:31]
	v_mfma_f32_16x16x32_bf16 v[24:27], v[172:175], v[216:219], v[24:27]
	v_mfma_f32_16x16x32_bf16 v[12:15], v[150:153], v[224:227], v[12:15]
	v_mfma_f32_16x16x32_bf16 v[4:7], v[172:175], v[224:227], v[4:7]
	v_mfma_f32_16x16x32_bf16 v[60:63], v[168:171], v[204:207], v[60:63]
	v_mfma_f32_16x16x32_bf16 v[56:59], v[176:179], v[204:207], v[56:59]
	v_mfma_f32_16x16x32_bf16 v[44:47], v[168:171], v[212:215], v[44:47]
	v_mfma_f32_16x16x32_bf16 v[36:39], v[176:179], v[212:215], v[36:39]
	v_mfma_f32_16x16x32_bf16 v[28:31], v[168:171], v[220:223], v[28:31]
	v_mfma_f32_16x16x32_bf16 v[24:27], v[176:179], v[220:223], v[24:27]
	v_mfma_f32_16x16x32_bf16 v[12:15], v[168:171], v[228:231], v[12:15]
	v_mfma_f32_16x16x32_bf16 v[4:7], v[176:179], v[228:231], v[4:7]
	s_setprio 0
	s_setprio 1
	v_mfma_f32_16x16x32_bf16 v[52:55], v[180:183], v[196:199], v[52:55]
	v_mfma_f32_16x16x32_bf16 v[48:51], v[188:191], v[196:199], v[48:51]
	v_mfma_f32_16x16x32_bf16 v[40:43], v[180:183], v[208:211], v[40:43]
	v_mfma_f32_16x16x32_bf16 v[32:35], v[188:191], v[208:211], v[32:35]
	v_mfma_f32_16x16x32_bf16 v[20:23], v[180:183], v[216:219], v[20:23]
	v_mfma_f32_16x16x32_bf16 v[16:19], v[188:191], v[216:219], v[16:19]
	v_mfma_f32_16x16x32_bf16 v[8:11], v[180:183], v[224:227], v[8:11]
	v_mfma_f32_16x16x32_bf16 v[0:3], v[188:191], v[224:227], v[0:3]
	s_barrier
	s_setprio 2
	v_mfma_f32_16x16x32_bf16 v[52:55], v[184:187], v[204:207], v[52:55]
	v_mfma_f32_16x16x32_bf16 v[48:51], v[192:195], v[204:207], v[48:51]
	v_mfma_f32_16x16x32_bf16 v[40:43], v[184:187], v[212:215], v[40:43]
	v_mfma_f32_16x16x32_bf16 v[32:35], v[192:195], v[212:215], v[32:35]
	v_mfma_f32_16x16x32_bf16 v[20:23], v[184:187], v[220:223], v[20:23]
	v_mfma_f32_16x16x32_bf16 v[16:19], v[192:195], v[220:223], v[16:19]
	v_mfma_f32_16x16x32_bf16 v[8:11], v[184:187], v[228:231], v[8:11]
	v_mfma_f32_16x16x32_bf16 v[0:3], v[192:195], v[228:231], v[0:3]
	s_setprio 0
	s_add_i32 s75, s75, 2
	s_add_u32 s82, s82, 0x100
	s_addc_u32 s83, s83, 0
	s_add_u32 vcc_hi, vcc_hi, 0x100
	s_addc_u32 s74, s74, 0
	s_cmp_gt_u32 s75, 13
	s_cbranch_scc0 .LBB0_413
	s_and_b64 vcc, exec, s[46:47]
	s_cbranch_vccz .LBB0_416
	s_barrier

; #define PG8_STAGE(bufoff, gbase, voff) do { _Pragma("unroll") for (int _i = 0; _i < 2; ++_i) \
;         __builtin_amdgcn_global_load_lds((const unsigned*)((const char*)(gbase) + (voff)[_i]), (PG8_LAS unsigned*)(lds + (bufoff) + ldsw + _i * 8192), 16, 0, 0); } while (0)
; #define PG8_LDA(dst, b, h) do { _Pragma("unroll") for (int m = 0; m < 4; ++m) _Pragma("unroll") for (int k = 0; k < 2; ++k) dst[m][k] = *(const PG8_LAS bf16x8*)(lds + PG8_SA(b, h) + aoff + m * 2048 + k * 1024); } while (0)
; #define PG8_LDB(dst, b, h) do { _Pragma("unroll") for (int n = 0; n < 2; ++n) _Pragma("unroll") for (int k = 0; k < 2; ++k) dst[n][k] = *(const PG8_LAS bf16x8*)(lds + PG8_SB(b, h) + boff + n * 2048 + k * 1024); } while (0)
; #define PG8_MMA(ai, bj, At, Bt) do { __builtin_amdgcn_s_setprio(1); _Pragma("unroll") for (int m = 0; m < 4; ++m) _Pragma("unroll") for (int n = 0; n < 2; ++n) _Pragma("unroll") for (int k = 0; k < 2; ++k) \
;         acc[ai][bj][m][n] = __builtin_amdgcn_mfma_f32_16x16x32_bf16(Bt[n][k], At[m][k], acc[ai][bj][m][n], 0, 0, 0); __builtin_amdgcn_s_setprio(0); } while (0)
; #define PG8_WAIT_V(n) asm volatile("s_waitcnt vmcnt(" #n ")" ::: "memory")
; #define PG8_WAIT_L(n) asm volatile("s_waitcnt lgkmcnt(" #n ")" ::: "memory")
; template <class Epi, class Sched, bool ALIGN_EPI = false, bool SP2 = false>
; __device__ __forceinline__ void gemm_phase(PG8_LAS unsigned char* lds, const Gemm g, const Sched& S, const Epi& E) {
;     ...
;             const bool last = (t == nt - 2);
;             const char* a1 = cA + (size_t)(t + 1) * kstep;
;             const char* a2 = last ? nA : cA + (size_t)(t + 2) * kstep; const char* b2 = last ? nB : cB + (size_t)(t + 2) * kstep;
;             const char* a3 = a2 + kstep; const char* b3 = b2 + kstep;
;             if (last && has_next) S.a_ready(nxt);
;             if constexpr (SP2) {
;             PG8_LDB(B0, 0, 0); PG8_LDB(B1, 0, 1); PG8_SCHED; PG8_LDA(At, 0, 0); PG8_STAGE(PG8_SA(1, 1), a1 + hstep, voffA);
;             PG8_WAIT_V(8); PG8_WAIT_L(0); PG8_BAR; PG8_MMA(0, 0, At, B0); PG8_MMA(0, 1, At, B1); PG8_BAR; PG8_SCHED;
;             PG8_LDA(At, 0, 1); PG8_STAGE(PG8_SB(0, 0), b2, voffB); PG8_STAGE(PG8_SB(0, 1), b2 + hstep, voffB); PG8_STAGE(PG8_SA(0, 0), a2, voffA);
;             PG8_WAIT_V(8); PG8_WAIT_L(0); PG8_BAR; PG8_MMA(1, 0, At, B0); PG8_MMA(1, 1, At, B1); PG8_BAR; PG8_SCHED;
.LBB0_445:
	ds_read_b128 v[152:155], v149
	ds_read_b128 v[158:161], v149 offset:1024
	ds_read_b128 v[162:165], v149 offset:2048
	ds_read_b128 v[166:169], v149 offset:3072
	ds_read_b128 v[170:173], v150
	ds_read_b128 v[174:177], v150 offset:1024
	ds_read_b128 v[178:181], v150 offset:2048
	ds_read_b128 v[182:185], v150 offset:3072
	s_add_u32 s10, s58, 0xfffc0080
	s_addc_u32 s11, s59, -1
	s_cmp_eq_u32 s75, 12
	s_cselect_b32 s63, s51, s11
	s_cselect_b32 s62, s87, s10
	s_cselect_b32 s61, s49, s74
	s_cselect_b32 s60, s88, s89
	v_lshl_add_u64 v[220:221], s[58:59], 0, v[138:139]
	s_add_i32 m0, s53, 0xc000
	ds_read_b128 v[186:189], v151
	ds_read_b128 v[190:193], v151 offset:1024
	ds_read_b128 v[194:197], v151 offset:2048
	ds_read_b128 v[198:201], v151 offset:3072
	ds_read_b128 v[204:207], v151 offset:4096
	ds_read_b128 v[208:211], v151 offset:5120
	ds_read_b128 v[212:215], v151 offset:6144
	ds_read_b128 v[216:219], v151 offset:7168
	global_load_lds_dwordx4 v[220:221], off
	v_lshl_add_u64 v[220:221], s[58:59], 0, v[140:141]
	s_add_i32 m0, s53, 0xe000
	s_nop 0
	global_load_lds_dwordx4 v[220:221], off
	s_waitcnt vmcnt(8)
	s_waitcnt lgkmcnt(0)
	s_barrier
	s_setprio 1
	s_waitcnt lgkmcnt(0)
	v_mfma_f32_16x16x32_bf16 v[124:127], v[152:155], v[186:189], v[124:127]
	v_mfma_f32_16x16x32_bf16 v[120:123], v[162:165], v[186:189], v[120:123]
	v_mfma_f32_16x16x32_bf16 v[116:119], v[152:155], v[194:197], v[116:119]
	v_mfma_f32_16x16x32_bf16 v[112:115], v[162:165], v[194:197], v[112:115]
	v_mfma_f32_16x16x32_bf16 v[100:103], v[152:155], v[204:207], v[100:103]
	v_mfma_f32_16x16x32_bf16 v[96:99], v[162:165], v[204:207], v[96:99]
	v_mfma_f32_16x16x32_bf16 v[84:87], v[152:155], v[212:215], v[84:87]
	v_mfma_f32_16x16x32_bf16 v[80:83], v[162:165], v[212:215], v[80:83]
	v_mfma_f32_16x16x32_bf16 v[124:127], v[158:161], v[190:193], v[124:127]
	v_mfma_f32_16x16x32_bf16 v[120:123], v[166:169], v[190:193], v[120:123]
	v_mfma_f32_16x16x32_bf16 v[116:119], v[158:161], v[198:201], v[116:119]
	v_mfma_f32_16x16x32_bf16 v[112:115], v[166:169], v[198:201], v[112:115]
	v_mfma_f32_16x16x32_bf16 v[100:103], v[158:161], v[208:211], v[100:103]
	v_mfma_f32_16x16x32_bf16 v[96:99], v[166:169], v[208:211], v[96:99]
	v_mfma_f32_16x16x32_bf16 v[84:87], v[158:161], v[216:219], v[84:87]
	v_mfma_f32_16x16x32_bf16 v[80:83], v[166:169], v[216:219], v[80:83]
	s_setprio 0
	s_setprio 1
	v_mfma_f32_16x16x32_bf16 v[108:111], v[170:173], v[186:189], v[108:111]
	v_mfma_f32_16x16x32_bf16 v[104:107], v[178:181], v[186:189], v[104:107]
	v_mfma_f32_16x16x32_bf16 v[92:95], v[170:173], v[194:197], v[92:95]
	v_mfma_f32_16x16x32_bf16 v[88:91], v[178:181], v[194:197], v[88:91]
	v_mfma_f32_16x16x32_bf16 v[76:79], v[170:173], v[204:207], v[76:79]
	v_mfma_f32_16x16x32_bf16 v[72:75], v[178:181], v[204:207], v[72:75]
	v_mfma_f32_16x16x32_bf16 v[68:71], v[170:173], v[212:215], v[68:71]
	v_mfma_f32_16x16x32_bf16 v[64:67], v[178:181], v[212:215], v[64:67]
	s_barrier
	s_setprio 2
	v_mfma_f32_16x16x32_bf16 v[108:111], v[174:177], v[190:193], v[108:111]
	v_mfma_f32_16x16x32_bf16 v[104:107], v[182:185], v[190:193], v[104:107]
	v_mfma_f32_16x16x32_bf16 v[92:95], v[174:177], v[198:201], v[92:95]
	v_mfma_f32_16x16x32_bf16 v[88:91], v[182:185], v[198:201], v[88:91]
	v_mfma_f32_16x16x32_bf16 v[76:79], v[174:177], v[208:211], v[76:79]
	v_mfma_f32_16x16x32_bf16 v[72:75], v[182:185], v[208:211], v[72:75]
	v_mfma_f32_16x16x32_bf16 v[68:71], v[174:177], v[216:219], v[68:71]
	v_mfma_f32_16x16x32_bf16 v[64:67], v[182:185], v[216:219], v[64:67]
	s_setprio 0
	s_add_i32 s10, s84, s33
	v_lshl_add_u64 v[220:221], s[60:61], 0, v[130:131]
	s_mov_b32 m0, s10
	ds_read_b128 v[186:189], v151 offset:16384
	ds_read_b128 v[190:193], v151 offset:17408
	ds_read_b128 v[194:197], v151 offset:18432
	ds_read_b128 v[198:201], v151 offset:19456
	ds_read_b128 v[204:207], v151 offset:20480
	ds_read_b128 v[208:211], v151 offset:21504
	ds_read_b128 v[212:215], v151 offset:22528
	ds_read_b128 v[216:219], v151 offset:23552
	global_load_lds_dwordx4 v[220:221], off
	s_add_i32 m0, s10, 0x2000
	s_add_u32 s10, s60, 0x40000
	v_lshl_add_u64 v[222:223], s[60:61], 0, v[134:135]
	s_addc_u32 s11, s61, 0
	s_add_i32 s90, s85, s33
	global_load_lds_dwordx4 v[222:223], off
	v_lshl_add_u64 v[224:225], s[10:11], 0, v[130:131]
	s_mov_b32 m0, s90
	v_lshl_add_u64 v[226:227], s[62:63], 0, v[132:133]
	global_load_lds_dwordx4 v[224:225], off
	v_lshl_add_u64 v[224:225], s[10:11], 0, v[134:135]
	s_add_i32 m0, s90, 0x2000
	s_nop 0
	global_load_lds_dwordx4 v[224:225], off
	v_lshl_add_u64 v[224:225], s[62:63], 0, v[128:129]
	s_mov_b32 m0, s53
	s_nop 0
	global_load_lds_dwordx4 v[224:225], off
	s_mov_b32 m0, s64
	s_nop 0
	global_load_lds_dwordx4 v[226:227], off
	s_waitcnt vmcnt(8)
	s_waitcnt lgkmcnt(0)
	s_barrier
	s_setprio 1
	s_waitcnt lgkmcnt(0)
	v_mfma_f32_16x16x32_bf16 v[60:63], v[152:155], v[186:189], v[60:63]
	v_mfma_f32_16x16x32_bf16 v[56:59], v[162:165], v[186:189], v[56:59]
	v_mfma_f32_16x16x32_bf16 v[52:55], v[152:155], v[194:197], v[52:55]
	v_mfma_f32_16x16x32_bf16 v[48:51], v[162:165], v[194:197], v[48:51]
	v_mfma_f32_16x16x32_bf16 v[36:39], v[152:155], v[204:207], v[36:39]
	v_mfma_f32_16x16x32_bf16 v[32:35], v[162:165], v[204:207], v[32:35]
	v_mfma_f32_16x16x32_bf16 v[20:23], v[152:155], v[212:215], v[20:23]
	v_mfma_f32_16x16x32_bf16 v[16:19], v[162:165], v[212:215], v[16:19]
	v_mfma_f32_16x16x32_bf16 v[60:63], v[158:161], v[190:193], v[60:63]
	v_mfma_f32_16x16x32_bf16 v[56:59], v[166:169], v[190:193], v[56:59]
	v_mfma_f32_16x16x32_bf16 v[52:55], v[158:161], v[198:201], v[52:55]
	v_mfma_f32_16x16x32_bf16 v[48:51], v[166:169], v[198:201], v[48:51]
	v_mfma_f32_16x16x32_bf16 v[36:39], v[158:161], v[208:211], v[36:39]
	v_mfma_f32_16x16x32_bf16 v[32:35], v[166:169], v[208:211], v[32:35]
	v_mfma_f32_16x16x32_bf16 v[20:23], v[158:161], v[216:219], v[20:23]
	v_mfma_f32_16x16x32_bf16 v[16:19], v[166:169], v[216:219], v[16:19]
	s_setprio 0
	s_setprio 1
	v_mfma_f32_16x16x32_bf16 v[44:47], v[170:173], v[186:189], v[44:47]
	v_mfma_f32_16x16x32_bf16 v[40:43], v[178:181], v[186:189], v[40:43]
	v_mfma_f32_16x16x32_bf16 v[28:31], v[170:173], v[194:197], v[28:31]
	v_mfma_f32_16x16x32_bf16 v[24:27], v[178:181], v[194:197], v[24:27]
	v_mfma_f32_16x16x32_bf16 v[12:15], v[170:173], v[204:207], v[12:15]
	v_mfma_f32_16x16x32_bf16 v[8:11], v[178:181], v[204:207], v[8:11]
	v_mfma_f32_16x16x32_bf16 v[4:7], v[170:173], v[212:215], v[4:7]
	v_mfma_f32_16x16x32_bf16 v[0:3], v[178:181], v[212:215], v[0:3]
	s_barrier
; #define PG8_STAGE(bufoff, gbase, voff) do { _Pragma("unroll") for (int _i = 0; _i < 2; ++_i) \
;         __builtin_amdgcn_global_load_lds((const unsigned*)((const char*)(gbase) + (voff)[_i]), (PG8_LAS unsigned*)(lds + (bufoff) + ldsw + _i * 8192), 16, 0, 0); } while (0)
; #define PG8_LDA(dst, b, h) do { _Pragma("unroll") for (int m = 0; m < 4; ++m) _Pragma("unroll") for (int k = 0; k < 2; ++k) dst[m][k] = *(const PG8_LAS bf16x8*)(lds + PG8_SA(b, h) + aoff + m * 2048 + k * 1024); } while (0)
; #define PG8_LDB(dst, b, h) do { _Pragma("unroll") for (int n = 0; n < 2; ++n) _Pragma("unroll") for (int k = 0; k < 2; ++k) dst[n][k] = *(const PG8_LAS bf16x8*)(lds + PG8_SB(b, h) + boff + n * 2048 + k * 1024); } while (0)
; #define PG8_MMA(ai, bj, At, Bt) do { __builtin_amdgcn_s_setprio(1); _Pragma("unroll") for (int m = 0; m < 4; ++m) _Pragma("unroll") for (int n = 0; n < 2; ++n) _Pragma("unroll") for (int k = 0; k < 2; ++k) \
;         acc[ai][bj][m][n] = __builtin_amdgcn_mfma_f32_16x16x32_bf16(Bt[n][k], At[m][k], acc[ai][bj][m][n], 0, 0, 0); __builtin_amdgcn_s_setprio(0); } while (0)
; #define PG8_WAIT_V(n) asm volatile("s_waitcnt vmcnt(" #n ")" ::: "memory")
; #define PG8_WAIT_L(n) asm volatile("s_waitcnt lgkmcnt(" #n ")" ::: "memory")
; #define PG8_BAR __builtin_amdgcn_s_barrier()
; #define PG8_SCHED __builtin_amdgcn_sched_barrier(0)
; template <class Epi, class Sched, bool ALIGN_EPI = false, bool SP2 = false>
; __device__ __forceinline__ void gemm_phase(PG8_LAS unsigned char* lds, const Gemm g, const Sched& S, const Epi& E) {
;     ...
;             PG8_WAIT_V(8); PG8_WAIT_L(0); PG8_BAR; PG8_MMA(1, 0, At, B0); PG8_MMA(1, 1, At, B1); PG8_BAR; PG8_SCHED;
;             PG8_LDB(B0, 1, 0); PG8_LDB(B1, 1, 1); PG8_SCHED; PG8_LDA(At, 1, 0); PG8_STAGE(PG8_SA(0, 1), a2 + hstep, voffA);
;             PG8_WAIT_V(8); PG8_WAIT_L(0); PG8_BAR; PG8_MMA(0, 0, At, B0); PG8_MMA(0, 1, At, B1); PG8_BAR; PG8_SCHED;
	s_setprio 2
	v_mfma_f32_16x16x32_bf16 v[44:47], v[174:177], v[190:193], v[44:47]
	v_mfma_f32_16x16x32_bf16 v[40:43], v[182:185], v[190:193], v[40:43]
	v_mfma_f32_16x16x32_bf16 v[28:31], v[174:177], v[198:201], v[28:31]
	v_mfma_f32_16x16x32_bf16 v[24:27], v[182:185], v[198:201], v[24:27]
	v_mfma_f32_16x16x32_bf16 v[12:15], v[174:177], v[208:211], v[12:15]
	v_mfma_f32_16x16x32_bf16 v[8:11], v[182:185], v[208:211], v[8:11]
	v_mfma_f32_16x16x32_bf16 v[4:7], v[174:177], v[216:219], v[4:7]
	v_mfma_f32_16x16x32_bf16 v[0:3], v[182:185], v[216:219], v[0:3]
	s_setprio 0
	s_add_i32 s90, 0, 0x18000
	v_add_u32_e32 v157, s90, v146
	s_add_i32 s91, 0, 0x1c000
	ds_read_b128 v[152:155], v157
	ds_read_b128 v[158:161], v157 offset:1024
	ds_read_b128 v[162:165], v157 offset:2048
	ds_read_b128 v[166:169], v157 offset:3072
	v_add_u32_e32 v157, s91, v146
	ds_read_b128 v[170:173], v157
	ds_read_b128 v[174:177], v157 offset:1024
	ds_read_b128 v[178:181], v157 offset:2048
	ds_read_b128 v[182:185], v157 offset:3072
	s_add_u32 s10, s62, 0x40000
	s_addc_u32 s11, s63, 0
	s_mov_b32 m0, s65
	v_lshl_add_u64 v[228:229], s[10:11], 0, v[128:129]
	ds_read_b128 v[186:189], v151 offset:32768
	ds_read_b128 v[190:193], v151 offset:33792
	ds_read_b128 v[194:197], v151 offset:34816
	ds_read_b128 v[198:201], v151 offset:35840
	ds_read_b128 v[204:207], v151 offset:36864
	ds_read_b128 v[208:211], v151 offset:37888
	ds_read_b128 v[212:215], v151 offset:38912
	ds_read_b128 v[216:219], v151 offset:39936
	global_load_lds_dwordx4 v[228:229], off
	v_lshl_add_u64 v[228:229], s[10:11], 0, v[132:133]
	s_mov_b32 m0, s70
	s_nop 0
	global_load_lds_dwordx4 v[228:229], off
	s_waitcnt vmcnt(8)
	s_waitcnt lgkmcnt(0)
	s_barrier
	s_setprio 1
	s_waitcnt lgkmcnt(0)
	v_mfma_f32_16x16x32_bf16 v[124:127], v[152:155], v[186:189], v[124:127]
	v_mfma_f32_16x16x32_bf16 v[120:123], v[162:165], v[186:189], v[120:123]
	v_mfma_f32_16x16x32_bf16 v[116:119], v[152:155], v[194:197], v[116:119]
	v_mfma_f32_16x16x32_bf16 v[112:115], v[162:165], v[194:197], v[112:115]
	v_mfma_f32_16x16x32_bf16 v[100:103], v[152:155], v[204:207], v[100:103]
	v_mfma_f32_16x16x32_bf16 v[96:99], v[162:165], v[204:207], v[96:99]
	v_mfma_f32_16x16x32_bf16 v[84:87], v[152:155], v[212:215], v[84:87]
	v_mfma_f32_16x16x32_bf16 v[80:83], v[162:165], v[212:215], v[80:83]
	v_mfma_f32_16x16x32_bf16 v[124:127], v[158:161], v[190:193], v[124:127]
	v_mfma_f32_16x16x32_bf16 v[120:123], v[166:169], v[190:193], v[120:123]
	v_mfma_f32_16x16x32_bf16 v[116:119], v[158:161], v[198:201], v[116:119]
	v_mfma_f32_16x16x32_bf16 v[112:115], v[166:169], v[198:201], v[112:115]
	v_mfma_f32_16x16x32_bf16 v[100:103], v[158:161], v[208:211], v[100:103]
	v_mfma_f32_16x16x32_bf16 v[96:99], v[166:169], v[208:211], v[96:99]
	v_mfma_f32_16x16x32_bf16 v[84:87], v[158:161], v[216:219], v[84:87]
	v_mfma_f32_16x16x32_bf16 v[80:83], v[166:169], v[216:219], v[80:83]
	s_setprio 0
	s_setprio 1
	v_mfma_f32_16x16x32_bf16 v[108:111], v[170:173], v[186:189], v[108:111]
	v_mfma_f32_16x16x32_bf16 v[104:107], v[178:181], v[186:189], v[104:107]
	v_mfma_f32_16x16x32_bf16 v[92:95], v[170:173], v[194:197], v[92:95]
	v_mfma_f32_16x16x32_bf16 v[88:91], v[178:181], v[194:197], v[88:91]
	v_mfma_f32_16x16x32_bf16 v[76:79], v[170:173], v[204:207], v[76:79]
	v_mfma_f32_16x16x32_bf16 v[72:75], v[178:181], v[204:207], v[72:75]
	v_mfma_f32_16x16x32_bf16 v[68:71], v[170:173], v[212:215], v[68:71]
	v_mfma_f32_16x16x32_bf16 v[64:67], v[178:181], v[212:215], v[64:67]
	s_barrier
; #define PG8_STAGE(bufoff, gbase, voff) do { _Pragma("unroll") for (int _i = 0; _i < 2; ++_i) \
;         __builtin_amdgcn_global_load_lds((const unsigned*)((const char*)(gbase) + (voff)[_i]), (PG8_LAS unsigned*)(lds + (bufoff) + ldsw + _i * 8192), 16, 0, 0); } while (0)
; #define PG8_LDA(dst, b, h) do { _Pragma("unroll") for (int m = 0; m < 4; ++m) _Pragma("unroll") for (int k = 0; k < 2; ++k) dst[m][k] = *(const PG8_LAS bf16x8*)(lds + PG8_SA(b, h) + aoff + m * 2048 + k * 1024); } while (0)
; #define PG8_MMA(ai, bj, At, Bt) do { __builtin_amdgcn_s_setprio(1); _Pragma("unroll") for (int m = 0; m < 4; ++m) _Pragma("unroll") for (int n = 0; n < 2; ++n) _Pragma("unroll") for (int k = 0; k < 2; ++k) \
;         acc[ai][bj][m][n] = __builtin_amdgcn_mfma_f32_16x16x32_bf16(Bt[n][k], At[m][k], acc[ai][bj][m][n], 0, 0, 0); __builtin_amdgcn_s_setprio(0); } while (0)
; #define PG8_WAIT_V(n) asm volatile("s_waitcnt vmcnt(" #n ")" ::: "memory")
; #define PG8_WAIT_L(n) asm volatile("s_waitcnt lgkmcnt(" #n ")" ::: "memory")
; #define PG8_BAR __builtin_amdgcn_s_barrier()
; #define PG8_SCHED __builtin_amdgcn_sched_barrier(0)
; template <class Epi, class Sched, bool ALIGN_EPI = false, bool SP2 = false>
; __device__ __forceinline__ void gemm_phase(PG8_LAS unsigned char* lds, const Gemm g, const Sched& S, const Epi& E) {
;     ...
;             PG8_WAIT_V(8); PG8_WAIT_L(0); PG8_BAR; PG8_MMA(0, 0, At, B0); PG8_MMA(0, 1, At, B1); PG8_BAR; PG8_SCHED;
;             PG8_LDA(At, 1, 1); PG8_STAGE(PG8_SB(1, 0), b3, voffB); PG8_STAGE(PG8_SB(1, 1), b3 + hstep, voffB); PG8_STAGE(PG8_SA(1, 0), a3, voffA);
;             PG8_WAIT_V(8); PG8_WAIT_L(0); PG8_BAR; PG8_MMA(1, 0, At, B0); PG8_MMA(1, 1, At, B1); PG8_BAR; PG8_SCHED;
;     ...
;         if constexpr (ALIGN_EPI) { if (wr == 0) PG8_BAR; }
	s_setprio 2
	v_mfma_f32_16x16x32_bf16 v[108:111], v[174:177], v[190:193], v[108:111]
	v_mfma_f32_16x16x32_bf16 v[104:107], v[182:185], v[190:193], v[104:107]
	v_mfma_f32_16x16x32_bf16 v[92:95], v[174:177], v[198:201], v[92:95]
	v_mfma_f32_16x16x32_bf16 v[88:91], v[182:185], v[198:201], v[88:91]
	v_mfma_f32_16x16x32_bf16 v[76:79], v[174:177], v[208:211], v[76:79]
	v_mfma_f32_16x16x32_bf16 v[72:75], v[182:185], v[208:211], v[72:75]
	v_mfma_f32_16x16x32_bf16 v[68:71], v[174:177], v[216:219], v[68:71]
	v_mfma_f32_16x16x32_bf16 v[64:67], v[182:185], v[216:219], v[64:67]
	s_setprio 0
	s_add_i32 s10, s90, s33
	v_lshl_add_u64 v[220:221], v[220:221], 0, s[44:45]
	s_mov_b32 m0, s10
	ds_read_b128 v[186:189], v151 offset:49152
	ds_read_b128 v[190:193], v151 offset:50176
	ds_read_b128 v[194:197], v151 offset:51200
	ds_read_b128 v[198:201], v151 offset:52224
	ds_read_b128 v[204:207], v151 offset:53248
	ds_read_b128 v[208:211], v151 offset:54272
	ds_read_b128 v[212:215], v151 offset:55296
	ds_read_b128 v[216:219], v151 offset:56320
	global_load_lds_dwordx4 v[220:221], off
	s_add_i32 m0, s10, 0x2000
	s_add_u32 s10, s60, 0x40080
	v_lshl_add_u64 v[220:221], v[222:223], 0, s[44:45]
	s_addc_u32 s11, s61, 0
	s_add_i32 s60, s91, s33
	global_load_lds_dwordx4 v[220:221], off
	v_lshl_add_u64 v[220:221], s[10:11], 0, v[130:131]
	s_mov_b32 m0, s60
	s_nop 0
	global_load_lds_dwordx4 v[220:221], off
	v_lshl_add_u64 v[220:221], s[10:11], 0, v[134:135]
	s_add_i32 m0, s60, 0x2000
	s_nop 0
	global_load_lds_dwordx4 v[220:221], off
	v_lshl_add_u64 v[220:221], v[224:225], 0, s[44:45]
	s_mov_b32 m0, s80
	s_nop 0
	global_load_lds_dwordx4 v[220:221], off
	v_lshl_add_u64 v[220:221], v[226:227], 0, s[44:45]
	s_mov_b32 m0, s81
	s_nop 0
	global_load_lds_dwordx4 v[220:221], off
	s_waitcnt vmcnt(8)
	s_waitcnt lgkmcnt(0)
	s_barrier
	s_setprio 1
	s_waitcnt lgkmcnt(0)
	v_mfma_f32_16x16x32_bf16 v[60:63], v[152:155], v[186:189], v[60:63]
	v_mfma_f32_16x16x32_bf16 v[56:59], v[162:165], v[186:189], v[56:59]
	v_mfma_f32_16x16x32_bf16 v[52:55], v[152:155], v[194:197], v[52:55]
	v_mfma_f32_16x16x32_bf16 v[48:51], v[162:165], v[194:197], v[48:51]
	v_mfma_f32_16x16x32_bf16 v[36:39], v[152:155], v[204:207], v[36:39]
	v_mfma_f32_16x16x32_bf16 v[32:35], v[162:165], v[204:207], v[32:35]
	v_mfma_f32_16x16x32_bf16 v[20:23], v[152:155], v[212:215], v[20:23]
	v_mfma_f32_16x16x32_bf16 v[16:19], v[162:165], v[212:215], v[16:19]
	v_mfma_f32_16x16x32_bf16 v[60:63], v[158:161], v[190:193], v[60:63]
	v_mfma_f32_16x16x32_bf16 v[56:59], v[166:169], v[190:193], v[56:59]
	v_mfma_f32_16x16x32_bf16 v[52:55], v[158:161], v[198:201], v[52:55]
	v_mfma_f32_16x16x32_bf16 v[48:51], v[166:169], v[198:201], v[48:51]
	v_mfma_f32_16x16x32_bf16 v[36:39], v[158:161], v[208:211], v[36:39]
	v_mfma_f32_16x16x32_bf16 v[32:35], v[166:169], v[208:211], v[32:35]
	v_mfma_f32_16x16x32_bf16 v[20:23], v[158:161], v[216:219], v[20:23]
	v_mfma_f32_16x16x32_bf16 v[16:19], v[166:169], v[216:219], v[16:19]
	s_setprio 0
	s_setprio 1
	v_mfma_f32_16x16x32_bf16 v[44:47], v[170:173], v[186:189], v[44:47]
	v_mfma_f32_16x16x32_bf16 v[40:43], v[178:181], v[186:189], v[40:43]
	v_mfma_f32_16x16x32_bf16 v[28:31], v[170:173], v[194:197], v[28:31]
	v_mfma_f32_16x16x32_bf16 v[24:27], v[178:181], v[194:197], v[24:27]
	v_mfma_f32_16x16x32_bf16 v[12:15], v[170:173], v[204:207], v[12:15]
	v_mfma_f32_16x16x32_bf16 v[8:11], v[178:181], v[204:207], v[8:11]
	v_mfma_f32_16x16x32_bf16 v[4:7], v[170:173], v[212:215], v[4:7]
	v_mfma_f32_16x16x32_bf16 v[0:3], v[178:181], v[212:215], v[0:3]
	s_barrier
	s_setprio 2
	v_mfma_f32_16x16x32_bf16 v[44:47], v[174:177], v[190:193], v[44:47]
	v_mfma_f32_16x16x32_bf16 v[40:43], v[182:185], v[190:193], v[40:43]
	v_mfma_f32_16x16x32_bf16 v[28:31], v[174:177], v[198:201], v[28:31]
	v_mfma_f32_16x16x32_bf16 v[24:27], v[182:185], v[198:201], v[24:27]
	v_mfma_f32_16x16x32_bf16 v[12:15], v[174:177], v[208:211], v[12:15]
	v_mfma_f32_16x16x32_bf16 v[8:11], v[182:185], v[208:211], v[8:11]
	v_mfma_f32_16x16x32_bf16 v[4:7], v[174:177], v[216:219], v[4:7]
	v_mfma_f32_16x16x32_bf16 v[0:3], v[182:185], v[216:219], v[0:3]
	s_setprio 0
	s_add_i32 s75, s75, 2
	s_add_u32 s58, s58, 0x100
	s_addc_u32 s59, s59, 0
	s_add_u32 s89, s89, 0x100
	s_addc_u32 s74, s74, 0
	s_cmp_gt_u32 s75, 13
	s_cbranch_scc0 .LBB0_445
	s_and_b64 vcc, exec, s[46:47]
	s_cbranch_vccz .LBB0_448
	s_barrier

; #define PG8_STAGE(bufoff, gbase, voff) do { _Pragma("unroll") for (int _i = 0; _i < 2; ++_i) \
;         __builtin_amdgcn_global_load_lds((const unsigned*)((const char*)(gbase) + (voff)[_i]), (PG8_LAS unsigned*)(lds + (bufoff) + ldsw + _i * 8192), 16, 0, 0); } while (0)
; #define PG8_LDA(dst, b, h) do { _Pragma("unroll") for (int m = 0; m < 4; ++m) _Pragma("unroll") for (int k = 0; k < 2; ++k) dst[m][k] = *(const PG8_LAS bf16x8*)(lds + PG8_SA(b, h) + aoff + m * 2048 + k * 1024); } while (0)
; #define PG8_LDB(dst, b, h) do { _Pragma("unroll") for (int n = 0; n < 2; ++n) _Pragma("unroll") for (int k = 0; k < 2; ++k) dst[n][k] = *(const PG8_LAS bf16x8*)(lds + PG8_SB(b, h) + boff + n * 2048 + k * 1024); } while (0)
; #define PG8_MMA(ai, bj, At, Bt) do { __builtin_amdgcn_s_setprio(1); _Pragma("unroll") for (int m = 0; m < 4; ++m) _Pragma("unroll") for (int n = 0; n < 2; ++n) _Pragma("unroll") for (int k = 0; k < 2; ++k) \
;         acc[ai][bj][m][n] = __builtin_amdgcn_mfma_f32_16x16x32_bf16(Bt[n][k], At[m][k], acc[ai][bj][m][n], 0, 0, 0); __builtin_amdgcn_s_setprio(0); } while (0)
; #define PG8_WAIT_V(n) asm volatile("s_waitcnt vmcnt(" #n ")" ::: "memory")
; #define PG8_WAIT_L(n) asm volatile("s_waitcnt lgkmcnt(" #n ")" ::: "memory")
; template <class Epi, class Sched, bool ALIGN_EPI = false, bool SP2 = false>
; __device__ __forceinline__ void gemm_phase(PG8_LAS unsigned char* lds, const Gemm g, const Sched& S, const Epi& E) {
;     ...
;             const bool last = (t == nt - 2);
;             const char* a1 = cA + (size_t)(t + 1) * kstep;
;             const char* a2 = last ? nA : cA + (size_t)(t + 2) * kstep; const char* b2 = last ? nB : cB + (size_t)(t + 2) * kstep;
;             const char* a3 = a2 + kstep; const char* b3 = b2 + kstep;
;             if (last && has_next) S.a_ready(nxt);
;             if constexpr (SP2) {
;             PG8_LDB(B0, 0, 0); PG8_LDB(B1, 0, 1); PG8_SCHED; PG8_LDA(At, 0, 0); PG8_STAGE(PG8_SA(1, 1), a1 + hstep, voffA);
;             PG8_WAIT_V(8); PG8_WAIT_L(0); PG8_BAR; PG8_MMA(0, 0, At, B0); PG8_MMA(0, 1, At, B1); PG8_BAR; PG8_SCHED;
;             PG8_LDA(At, 0, 1); PG8_STAGE(PG8_SB(0, 0), b2, voffB); PG8_STAGE(PG8_SB(0, 1), b2 + hstep, voffB); PG8_STAGE(PG8_SA(0, 0), a2, voffA);
;             PG8_WAIT_V(8); PG8_WAIT_L(0); PG8_BAR; PG8_MMA(1, 0, At, B0); PG8_MMA(1, 1, At, B1); PG8_BAR; PG8_SCHED;
.LBB0_647:
	s_add_u32 s10, s56, s58
	s_addc_u32 s11, s57, s59
	s_add_u32 s10, s10, 0x100
	s_addc_u32 s11, s11, 0
	s_add_u32 s60, s89, s58
	s_addc_u32 s61, s90, s59
	s_add_i32 s74, 0, 0x10000
	v_add_u32_e32 v1, s74, v184
	ds_read_b128 v[132:135], v1
	ds_read_b128 v[136:139], v1 offset:1024
	ds_read_b128 v[140:143], v1 offset:2048
	ds_read_b128 v[144:147], v1 offset:3072
	v_add_u32_e32 v1, s85, v184
	ds_read_b128 v[148:151], v1
	ds_read_b128 v[152:155], v1 offset:1024
	ds_read_b128 v[188:191], v1 offset:2048
	ds_read_b128 v[192:195], v1 offset:3072
	s_cmpk_eq_i32 s58, 0x700
	s_cselect_b32 s63, s51, s11
	s_cselect_b32 s62, s87, s10
	s_cselect_b32 s61, s49, s61
	s_cselect_b32 s60, s88, s60
	v_lshl_add_u64 v[2:3], v[178:179], 0, s[58:59]
	s_add_i32 m0, s64, 0xc000
	ds_read_b128 v[196:199], v186
	ds_read_b128 v[204:207], v186 offset:1024
	ds_read_b128 v[208:211], v186 offset:2048
	ds_read_b128 v[212:215], v186 offset:3072
	ds_read_b128 v[216:219], v186 offset:4096
	ds_read_b128 v[220:223], v186 offset:5120
	ds_read_b128 v[224:227], v186 offset:6144
	ds_read_b128 v[228:231], v186 offset:7168
	global_load_lds_dwordx4 v[2:3], off
	v_lshl_add_u64 v[2:3], v[180:181], 0, s[58:59]
	s_add_i32 m0, s64, 0xe000
	s_nop 0
	global_load_lds_dwordx4 v[2:3], off
	s_waitcnt vmcnt(8)
	s_waitcnt lgkmcnt(0)
	s_barrier
	s_setprio 1
	s_waitcnt lgkmcnt(0)
	v_mfma_f32_16x16x32_bf16 v[128:131], v[132:135], v[196:199], v[128:131]
	v_mfma_f32_16x16x32_bf16 v[124:127], v[140:143], v[196:199], v[124:127]
	v_mfma_f32_16x16x32_bf16 v[112:115], v[132:135], v[208:211], v[112:115]
	v_mfma_f32_16x16x32_bf16 v[108:111], v[140:143], v[208:211], v[108:111]
	v_mfma_f32_16x16x32_bf16 v[96:99], v[132:135], v[216:219], v[96:99]
	v_mfma_f32_16x16x32_bf16 v[92:95], v[140:143], v[216:219], v[92:95]
	v_mfma_f32_16x16x32_bf16 v[80:83], v[132:135], v[224:227], v[80:83]
	v_mfma_f32_16x16x32_bf16 v[76:79], v[140:143], v[224:227], v[76:79]
	v_mfma_f32_16x16x32_bf16 v[128:131], v[136:139], v[204:207], v[128:131]
	v_mfma_f32_16x16x32_bf16 v[124:127], v[144:147], v[204:207], v[124:127]
	v_mfma_f32_16x16x32_bf16 v[112:115], v[136:139], v[212:215], v[112:115]
	v_mfma_f32_16x16x32_bf16 v[108:111], v[144:147], v[212:215], v[108:111]
	v_mfma_f32_16x16x32_bf16 v[96:99], v[136:139], v[220:223], v[96:99]
	v_mfma_f32_16x16x32_bf16 v[92:95], v[144:147], v[220:223], v[92:95]
	v_mfma_f32_16x16x32_bf16 v[80:83], v[136:139], v[228:231], v[80:83]
	v_mfma_f32_16x16x32_bf16 v[76:79], v[144:147], v[228:231], v[76:79]
	s_setprio 0
	s_setprio 1
	v_mfma_f32_16x16x32_bf16 v[120:123], v[148:151], v[196:199], v[120:123]
	v_mfma_f32_16x16x32_bf16 v[116:119], v[188:191], v[196:199], v[116:119]
	v_mfma_f32_16x16x32_bf16 v[104:107], v[148:151], v[208:211], v[104:107]
	v_mfma_f32_16x16x32_bf16 v[100:103], v[188:191], v[208:211], v[100:103]
	v_mfma_f32_16x16x32_bf16 v[88:91], v[148:151], v[216:219], v[88:91]
	v_mfma_f32_16x16x32_bf16 v[84:87], v[188:191], v[216:219], v[84:87]
	v_mfma_f32_16x16x32_bf16 v[72:75], v[148:151], v[224:227], v[72:75]
	v_mfma_f32_16x16x32_bf16 v[68:71], v[188:191], v[224:227], v[68:71]
	s_barrier
	s_setprio 2
	v_mfma_f32_16x16x32_bf16 v[120:123], v[152:155], v[204:207], v[120:123]
	v_mfma_f32_16x16x32_bf16 v[116:119], v[192:195], v[204:207], v[116:119]
	v_mfma_f32_16x16x32_bf16 v[104:107], v[152:155], v[212:215], v[104:107]
	v_mfma_f32_16x16x32_bf16 v[100:103], v[192:195], v[212:215], v[100:103]
	v_mfma_f32_16x16x32_bf16 v[88:91], v[152:155], v[220:223], v[88:91]
	v_mfma_f32_16x16x32_bf16 v[84:87], v[192:195], v[220:223], v[84:87]
	v_mfma_f32_16x16x32_bf16 v[72:75], v[152:155], v[228:231], v[72:75]
	v_mfma_f32_16x16x32_bf16 v[68:71], v[192:195], v[228:231], v[68:71]
	s_setprio 0
	s_add_i32 s10, s74, s33
	v_lshl_add_u64 v[182:183], s[60:61], 0, v[160:161]
	s_mov_b32 m0, s10
	ds_read_b128 v[196:199], v186 offset:16384
	ds_read_b128 v[204:207], v186 offset:17408
	ds_read_b128 v[208:211], v186 offset:18432
	ds_read_b128 v[212:215], v186 offset:19456
	ds_read_b128 v[216:219], v186 offset:20480
	ds_read_b128 v[220:223], v186 offset:21504
	ds_read_b128 v[224:227], v186 offset:22528
	ds_read_b128 v[228:231], v186 offset:23552
	global_load_lds_dwordx4 v[182:183], off
	s_add_i32 m0, s10, 0x2000
	s_add_u32 s10, s60, 0x40000
	v_lshl_add_u64 v[200:201], s[60:61], 0, v[164:165]
	s_addc_u32 s11, s61, 0
	s_add_i32 s74, s85, s33
	global_load_lds_dwordx4 v[200:201], off
	v_lshl_add_u64 v[2:3], s[10:11], 0, v[160:161]
	s_mov_b32 m0, s74
	v_lshl_add_u64 v[232:233], s[62:63], 0, v[158:159]
	global_load_lds_dwordx4 v[2:3], off
	v_lshl_add_u64 v[2:3], s[10:11], 0, v[164:165]
	s_add_i32 m0, s74, 0x2000
	v_lshl_add_u64 v[234:235], s[62:63], 0, v[162:163]
	global_load_lds_dwordx4 v[2:3], off
	s_mov_b32 m0, s64
	s_nop 0
	global_load_lds_dwordx4 v[232:233], off
	s_mov_b32 m0, s65
	s_nop 0
	global_load_lds_dwordx4 v[234:235], off
	s_waitcnt vmcnt(8)
	s_waitcnt lgkmcnt(0)
	s_barrier
; #define PG8_STAGE(bufoff, gbase, voff) do { _Pragma("unroll") for (int _i = 0; _i < 2; ++_i) \
;         __builtin_amdgcn_global_load_lds((const unsigned*)((const char*)(gbase) + (voff)[_i]), (PG8_LAS unsigned*)(lds + (bufoff) + ldsw + _i * 8192), 16, 0, 0); } while (0)
; #define PG8_LDA(dst, b, h) do { _Pragma("unroll") for (int m = 0; m < 4; ++m) _Pragma("unroll") for (int k = 0; k < 2; ++k) dst[m][k] = *(const PG8_LAS bf16x8*)(lds + PG8_SA(b, h) + aoff + m * 2048 + k * 1024); } while (0)
; #define PG8_LDB(dst, b, h) do { _Pragma("unroll") for (int n = 0; n < 2; ++n) _Pragma("unroll") for (int k = 0; k < 2; ++k) dst[n][k] = *(const PG8_LAS bf16x8*)(lds + PG8_SB(b, h) + boff + n * 2048 + k * 1024); } while (0)
; #define PG8_MMA(ai, bj, At, Bt) do { __builtin_amdgcn_s_setprio(1); _Pragma("unroll") for (int m = 0; m < 4; ++m) _Pragma("unroll") for (int n = 0; n < 2; ++n) _Pragma("unroll") for (int k = 0; k < 2; ++k) \
;         acc[ai][bj][m][n] = __builtin_amdgcn_mfma_f32_16x16x32_bf16(Bt[n][k], At[m][k], acc[ai][bj][m][n], 0, 0, 0); __builtin_amdgcn_s_setprio(0); } while (0)
; #define PG8_WAIT_V(n) asm volatile("s_waitcnt vmcnt(" #n ")" ::: "memory")
; #define PG8_WAIT_L(n) asm volatile("s_waitcnt lgkmcnt(" #n ")" ::: "memory")
; #define PG8_BAR __builtin_amdgcn_s_barrier()
; #define PG8_SCHED __builtin_amdgcn_sched_barrier(0)
; template <class Epi, class Sched, bool ALIGN_EPI = false, bool SP2 = false>
; __device__ __forceinline__ void gemm_phase(PG8_LAS unsigned char* lds, const Gemm g, const Sched& S, const Epi& E) {
;     ...
;             PG8_WAIT_V(8); PG8_WAIT_L(0); PG8_BAR; PG8_MMA(1, 0, At, B0); PG8_MMA(1, 1, At, B1); PG8_BAR; PG8_SCHED;
;             PG8_LDB(B0, 1, 0); PG8_LDB(B1, 1, 1); PG8_SCHED; PG8_LDA(At, 1, 0); PG8_STAGE(PG8_SA(0, 1), a2 + hstep, voffA);
;             PG8_WAIT_V(8); PG8_WAIT_L(0); PG8_BAR; PG8_MMA(0, 0, At, B0); PG8_MMA(0, 1, At, B1); PG8_BAR; PG8_SCHED;
	s_setprio 1
	s_waitcnt lgkmcnt(0)
	v_mfma_f32_16x16x32_bf16 v[64:67], v[132:135], v[196:199], v[64:67]
	v_mfma_f32_16x16x32_bf16 v[60:63], v[140:143], v[196:199], v[60:63]
	v_mfma_f32_16x16x32_bf16 v[48:51], v[132:135], v[208:211], v[48:51]
	v_mfma_f32_16x16x32_bf16 v[44:47], v[140:143], v[208:211], v[44:47]
	v_mfma_f32_16x16x32_bf16 v[32:35], v[132:135], v[216:219], v[32:35]
	v_mfma_f32_16x16x32_bf16 v[28:31], v[140:143], v[216:219], v[28:31]
	v_mfma_f32_16x16x32_bf16 v[16:19], v[132:135], v[224:227], v[16:19]
	v_mfma_f32_16x16x32_bf16 v[12:15], v[140:143], v[224:227], v[12:15]
	v_mfma_f32_16x16x32_bf16 v[64:67], v[136:139], v[204:207], v[64:67]
	v_mfma_f32_16x16x32_bf16 v[60:63], v[144:147], v[204:207], v[60:63]
	v_mfma_f32_16x16x32_bf16 v[48:51], v[136:139], v[212:215], v[48:51]
	v_mfma_f32_16x16x32_bf16 v[44:47], v[144:147], v[212:215], v[44:47]
	v_mfma_f32_16x16x32_bf16 v[32:35], v[136:139], v[220:223], v[32:35]
	v_mfma_f32_16x16x32_bf16 v[28:31], v[144:147], v[220:223], v[28:31]
	v_mfma_f32_16x16x32_bf16 v[16:19], v[136:139], v[228:231], v[16:19]
	v_mfma_f32_16x16x32_bf16 v[12:15], v[144:147], v[228:231], v[12:15]
	s_setprio 0
	s_setprio 1
	v_mfma_f32_16x16x32_bf16 v[56:59], v[148:151], v[196:199], v[56:59]
	v_mfma_f32_16x16x32_bf16 v[52:55], v[188:191], v[196:199], v[52:55]
	v_mfma_f32_16x16x32_bf16 v[40:43], v[148:151], v[208:211], v[40:43]
	v_mfma_f32_16x16x32_bf16 v[36:39], v[188:191], v[208:211], v[36:39]
	v_mfma_f32_16x16x32_bf16 v[24:27], v[148:151], v[216:219], v[24:27]
	v_mfma_f32_16x16x32_bf16 v[20:23], v[188:191], v[216:219], v[20:23]
	v_mfma_f32_16x16x32_bf16 v[8:11], v[148:151], v[224:227], v[8:11]
	v_mfma_f32_16x16x32_bf16 v[2:5], v[188:191], v[224:227], v[4:7]
	s_barrier
	s_setprio 2
	v_mfma_f32_16x16x32_bf16 v[56:59], v[152:155], v[204:207], v[56:59]
	v_mfma_f32_16x16x32_bf16 v[52:55], v[192:195], v[204:207], v[52:55]
	v_mfma_f32_16x16x32_bf16 v[40:43], v[152:155], v[212:215], v[40:43]
	v_mfma_f32_16x16x32_bf16 v[36:39], v[192:195], v[212:215], v[36:39]
	v_mfma_f32_16x16x32_bf16 v[24:27], v[152:155], v[220:223], v[24:27]
	v_mfma_f32_16x16x32_bf16 v[20:23], v[192:195], v[220:223], v[20:23]
	v_mfma_f32_16x16x32_bf16 v[8:11], v[152:155], v[228:231], v[8:11]
	v_mfma_f32_16x16x32_bf16 v[2:5], v[192:195], v[228:231], v[2:5]
	s_setprio 0
	s_add_i32 s74, 0, 0x18000
	v_add_u32_e32 v1, s74, v184
	s_add_i32 s75, 0, 0x1c000
	ds_read_b128 v[132:135], v1
	ds_read_b128 v[136:139], v1 offset:1024
	ds_read_b128 v[140:143], v1 offset:2048
	ds_read_b128 v[144:147], v1 offset:3072
	v_add_u32_e32 v1, s75, v184
	ds_read_b128 v[148:151], v1
	ds_read_b128 v[152:155], v1 offset:1024
	ds_read_b128 v[188:191], v1 offset:2048
	ds_read_b128 v[192:195], v1 offset:3072
	s_add_u32 s10, s62, 0x40000
	s_addc_u32 s11, s63, 0
	s_mov_b32 m0, s66
	v_lshl_add_u64 v[6:7], s[10:11], 0, v[158:159]
	ds_read_b128 v[196:199], v186 offset:32768
	ds_read_b128 v[204:207], v186 offset:33792
	ds_read_b128 v[208:211], v186 offset:34816
	ds_read_b128 v[212:215], v186 offset:35840
	ds_read_b128 v[216:219], v186 offset:36864
	ds_read_b128 v[220:223], v186 offset:37888
	ds_read_b128 v[224:227], v186 offset:38912
	ds_read_b128 v[228:231], v186 offset:39936
	global_load_lds_dwordx4 v[6:7], off
	v_lshl_add_u64 v[6:7], s[10:11], 0, v[162:163]
	s_mov_b32 m0, s67
	s_nop 0
	global_load_lds_dwordx4 v[6:7], off
	s_waitcnt vmcnt(8)
	s_waitcnt lgkmcnt(0)
	s_barrier
	s_setprio 1
	s_waitcnt lgkmcnt(0)
	v_mfma_f32_16x16x32_bf16 v[128:131], v[132:135], v[196:199], v[128:131]
	v_mfma_f32_16x16x32_bf16 v[124:127], v[140:143], v[196:199], v[124:127]
	v_mfma_f32_16x16x32_bf16 v[112:115], v[132:135], v[208:211], v[112:115]
	v_mfma_f32_16x16x32_bf16 v[108:111], v[140:143], v[208:211], v[108:111]
	v_mfma_f32_16x16x32_bf16 v[96:99], v[132:135], v[216:219], v[96:99]
	v_mfma_f32_16x16x32_bf16 v[92:95], v[140:143], v[216:219], v[92:95]
	v_mfma_f32_16x16x32_bf16 v[80:83], v[132:135], v[224:227], v[80:83]
	v_mfma_f32_16x16x32_bf16 v[76:79], v[140:143], v[224:227], v[76:79]
	v_mfma_f32_16x16x32_bf16 v[128:131], v[136:139], v[204:207], v[128:131]
	v_mfma_f32_16x16x32_bf16 v[124:127], v[144:147], v[204:207], v[124:127]
	v_mfma_f32_16x16x32_bf16 v[112:115], v[136:139], v[212:215], v[112:115]
	v_mfma_f32_16x16x32_bf16 v[108:111], v[144:147], v[212:215], v[108:111]
	v_mfma_f32_16x16x32_bf16 v[96:99], v[136:139], v[220:223], v[96:99]
	v_mfma_f32_16x16x32_bf16 v[92:95], v[144:147], v[220:223], v[92:95]
	v_mfma_f32_16x16x32_bf16 v[80:83], v[136:139], v[228:231], v[80:83]
	v_mfma_f32_16x16x32_bf16 v[76:79], v[144:147], v[228:231], v[76:79]
	s_setprio 0
	s_setprio 1
	v_mfma_f32_16x16x32_bf16 v[120:123], v[148:151], v[196:199], v[120:123]
	v_mfma_f32_16x16x32_bf16 v[116:119], v[188:191], v[196:199], v[116:119]
	v_mfma_f32_16x16x32_bf16 v[104:107], v[148:151], v[208:211], v[104:107]
	v_mfma_f32_16x16x32_bf16 v[100:103], v[188:191], v[208:211], v[100:103]
	v_mfma_f32_16x16x32_bf16 v[88:91], v[148:151], v[216:219], v[88:91]
	v_mfma_f32_16x16x32_bf16 v[84:87], v[188:191], v[216:219], v[84:87]
	v_mfma_f32_16x16x32_bf16 v[72:75], v[148:151], v[224:227], v[72:75]
	v_mfma_f32_16x16x32_bf16 v[68:71], v[188:191], v[224:227], v[68:71]
	s_barrier
; #define PG8_STAGE(bufoff, gbase, voff) do { _Pragma("unroll") for (int _i = 0; _i < 2; ++_i) \
;         __builtin_amdgcn_global_load_lds((const unsigned*)((const char*)(gbase) + (voff)[_i]), (PG8_LAS unsigned*)(lds + (bufoff) + ldsw + _i * 8192), 16, 0, 0); } while (0)
; #define PG8_LDA(dst, b, h) do { _Pragma("unroll") for (int m = 0; m < 4; ++m) _Pragma("unroll") for (int k = 0; k < 2; ++k) dst[m][k] = *(const PG8_LAS bf16x8*)(lds + PG8_SA(b, h) + aoff + m * 2048 + k * 1024); } while (0)
; #define PG8_MMA(ai, bj, At, Bt) do { __builtin_amdgcn_s_setprio(1); _Pragma("unroll") for (int m = 0; m < 4; ++m) _Pragma("unroll") for (int n = 0; n < 2; ++n) _Pragma("unroll") for (int k = 0; k < 2; ++k) \
;         acc[ai][bj][m][n] = __builtin_amdgcn_mfma_f32_16x16x32_bf16(Bt[n][k], At[m][k], acc[ai][bj][m][n], 0, 0, 0); __builtin_amdgcn_s_setprio(0); } while (0)
; #define PG8_WAIT_V(n) asm volatile("s_waitcnt vmcnt(" #n ")" ::: "memory")
; #define PG8_WAIT_L(n) asm volatile("s_waitcnt lgkmcnt(" #n ")" ::: "memory")
; #define PG8_BAR __builtin_amdgcn_s_barrier()
; #define PG8_SCHED __builtin_amdgcn_sched_barrier(0)
; template <class Epi, class Sched, bool ALIGN_EPI = false, bool SP2 = false>
; __device__ __forceinline__ void gemm_phase(PG8_LAS unsigned char* lds, const Gemm g, const Sched& S, const Epi& E) {
;     ...
;             PG8_WAIT_V(8); PG8_WAIT_L(0); PG8_BAR; PG8_MMA(0, 0, At, B0); PG8_MMA(0, 1, At, B1); PG8_BAR; PG8_SCHED;
;             PG8_LDA(At, 1, 1); PG8_STAGE(PG8_SB(1, 0), b3, voffB); PG8_STAGE(PG8_SB(1, 1), b3 + hstep, voffB); PG8_STAGE(PG8_SA(1, 0), a3, voffA);
;             PG8_WAIT_V(8); PG8_WAIT_L(0); PG8_BAR; PG8_MMA(1, 0, At, B0); PG8_MMA(1, 1, At, B1); PG8_BAR; PG8_SCHED;
	s_setprio 2
	v_mfma_f32_16x16x32_bf16 v[120:123], v[152:155], v[204:207], v[120:123]
	v_mfma_f32_16x16x32_bf16 v[116:119], v[192:195], v[204:207], v[116:119]
	v_mfma_f32_16x16x32_bf16 v[104:107], v[152:155], v[212:215], v[104:107]
	v_mfma_f32_16x16x32_bf16 v[100:103], v[192:195], v[212:215], v[100:103]
	v_mfma_f32_16x16x32_bf16 v[88:91], v[152:155], v[220:223], v[88:91]
	v_mfma_f32_16x16x32_bf16 v[84:87], v[192:195], v[220:223], v[84:87]
	v_mfma_f32_16x16x32_bf16 v[72:75], v[152:155], v[228:231], v[72:75]
	v_mfma_f32_16x16x32_bf16 v[68:71], v[192:195], v[228:231], v[68:71]
	s_setprio 0
	s_add_i32 s10, s74, s33
	v_lshl_add_u64 v[6:7], v[182:183], 0, s[8:9]
	s_mov_b32 m0, s10
	ds_read_b128 v[196:199], v186 offset:49152
	ds_read_b128 v[204:207], v186 offset:50176
	ds_read_b128 v[208:211], v186 offset:51200
	ds_read_b128 v[212:215], v186 offset:52224
	ds_read_b128 v[216:219], v186 offset:53248
	ds_read_b128 v[220:223], v186 offset:54272
	ds_read_b128 v[224:227], v186 offset:55296
	ds_read_b128 v[228:231], v186 offset:56320
	global_load_lds_dwordx4 v[6:7], off
	s_add_i32 m0, s10, 0x2000
	s_add_u32 s10, s60, 0x40080
	v_lshl_add_u64 v[6:7], v[200:201], 0, s[8:9]
	s_addc_u32 s11, s61, 0
	s_add_i32 s60, s75, s33
	global_load_lds_dwordx4 v[6:7], off
	v_lshl_add_u64 v[6:7], s[10:11], 0, v[160:161]
	s_mov_b32 m0, s60
	s_nop 0
	global_load_lds_dwordx4 v[6:7], off
	v_lshl_add_u64 v[6:7], s[10:11], 0, v[164:165]
	s_add_i32 m0, s60, 0x2000
	s_nop 0
	global_load_lds_dwordx4 v[6:7], off
	v_lshl_add_u64 v[6:7], v[232:233], 0, s[8:9]
	s_mov_b32 m0, s71
	s_nop 0
	global_load_lds_dwordx4 v[6:7], off
	v_lshl_add_u64 v[6:7], v[234:235], 0, s[8:9]
	s_mov_b32 m0, s72
	s_nop 0
	global_load_lds_dwordx4 v[6:7], off
	s_waitcnt vmcnt(8)
	s_waitcnt lgkmcnt(0)
	s_barrier
	s_setprio 1
	s_waitcnt lgkmcnt(0)
	v_mfma_f32_16x16x32_bf16 v[64:67], v[132:135], v[196:199], v[64:67]
	v_mfma_f32_16x16x32_bf16 v[60:63], v[140:143], v[196:199], v[60:63]
	v_mfma_f32_16x16x32_bf16 v[48:51], v[132:135], v[208:211], v[48:51]
	v_mfma_f32_16x16x32_bf16 v[44:47], v[140:143], v[208:211], v[44:47]
	v_mfma_f32_16x16x32_bf16 v[32:35], v[132:135], v[216:219], v[32:35]
	v_mfma_f32_16x16x32_bf16 v[28:31], v[140:143], v[216:219], v[28:31]
	v_mfma_f32_16x16x32_bf16 v[16:19], v[132:135], v[224:227], v[16:19]
	v_mfma_f32_16x16x32_bf16 v[12:15], v[140:143], v[224:227], v[12:15]
	v_mfma_f32_16x16x32_bf16 v[64:67], v[136:139], v[204:207], v[64:67]
	v_mfma_f32_16x16x32_bf16 v[60:63], v[144:147], v[204:207], v[60:63]
	v_mfma_f32_16x16x32_bf16 v[48:51], v[136:139], v[212:215], v[48:51]
	v_mfma_f32_16x16x32_bf16 v[44:47], v[144:147], v[212:215], v[44:47]
	v_mfma_f32_16x16x32_bf16 v[32:35], v[136:139], v[220:223], v[32:35]
	v_mfma_f32_16x16x32_bf16 v[28:31], v[144:147], v[220:223], v[28:31]
	v_mfma_f32_16x16x32_bf16 v[16:19], v[136:139], v[228:231], v[16:19]
	v_mfma_f32_16x16x32_bf16 v[12:15], v[144:147], v[228:231], v[12:15]
	s_setprio 0
	s_setprio 1
	v_mfma_f32_16x16x32_bf16 v[56:59], v[148:151], v[196:199], v[56:59]
	v_mfma_f32_16x16x32_bf16 v[52:55], v[188:191], v[196:199], v[52:55]
	v_mfma_f32_16x16x32_bf16 v[40:43], v[148:151], v[208:211], v[40:43]
	v_mfma_f32_16x16x32_bf16 v[36:39], v[188:191], v[208:211], v[36:39]
	v_mfma_f32_16x16x32_bf16 v[24:27], v[148:151], v[216:219], v[24:27]
	v_mfma_f32_16x16x32_bf16 v[20:23], v[188:191], v[216:219], v[20:23]
	v_mfma_f32_16x16x32_bf16 v[6:9], v[148:151], v[224:227], v[8:11]
	v_mfma_f32_16x16x32_bf16 v[2:5], v[188:191], v[224:227], v[2:5]
	s_barrier
	s_setprio 2
	v_mfma_f32_16x16x32_bf16 v[56:59], v[152:155], v[204:207], v[56:59]
	v_mfma_f32_16x16x32_bf16 v[52:55], v[192:195], v[204:207], v[52:55]
	v_mfma_f32_16x16x32_bf16 v[40:43], v[152:155], v[212:215], v[40:43]
	v_mfma_f32_16x16x32_bf16 v[36:39], v[192:195], v[212:215], v[36:39]
	v_mfma_f32_16x16x32_bf16 v[24:27], v[152:155], v[220:223], v[24:27]
	v_mfma_f32_16x16x32_bf16 v[20:23], v[192:195], v[220:223], v[20:23]
	v_mfma_f32_16x16x32_bf16 v[8:11], v[152:155], v[228:231], v[6:9]
	v_mfma_f32_16x16x32_bf16 v[4:7], v[192:195], v[228:231], v[2:5]
	s_setprio 0
	s_add_i32 s91, s91, 2
	s_add_u32 s58, s58, 0x100
	s_addc_u32 s59, s59, 0
	s_cmp_gt_u32 s91, 13
	s_cbranch_scc1 .LBB0_650

; #define PG8_STAGE(bufoff, gbase, voff) do { _Pragma("unroll") for (int _i = 0; _i < 2; ++_i) \
;         __builtin_amdgcn_global_load_lds((const unsigned*)((const char*)(gbase) + (voff)[_i]), (PG8_LAS unsigned*)(lds + (bufoff) + ldsw + _i * 8192), 16, 0, 0); } while (0)
; #define PG8_LDA(dst, b, h) do { _Pragma("unroll") for (int m = 0; m < 4; ++m) _Pragma("unroll") for (int k = 0; k < 2; ++k) dst[m][k] = *(const PG8_LAS bf16x8*)(lds + PG8_SA(b, h) + aoff + m * 2048 + k * 1024); } while (0)
; #define PG8_LDB(dst, b, h) do { _Pragma("unroll") for (int n = 0; n < 2; ++n) _Pragma("unroll") for (int k = 0; k < 2; ++k) dst[n][k] = *(const PG8_LAS bf16x8*)(lds + PG8_SB(b, h) + boff + n * 2048 + k * 1024); } while (0)
; #define PG8_MMA(ai, bj, At, Bt) do { __builtin_amdgcn_s_setprio(1); _Pragma("unroll") for (int m = 0; m < 4; ++m) _Pragma("unroll") for (int n = 0; n < 2; ++n) _Pragma("unroll") for (int k = 0; k < 2; ++k) \
;         acc[ai][bj][m][n] = __builtin_amdgcn_mfma_f32_16x16x32_bf16(Bt[n][k], At[m][k], acc[ai][bj][m][n], 0, 0, 0); __builtin_amdgcn_s_setprio(0); } while (0)
; #define PG8_WAIT_V(n) asm volatile("s_waitcnt vmcnt(" #n ")" ::: "memory")
; #define PG8_WAIT_L(n) asm volatile("s_waitcnt lgkmcnt(" #n ")" ::: "memory")
; template <class Epi, class Sched, bool ALIGN_EPI = false, bool SP2 = false>
; __device__ __forceinline__ void gemm_phase(PG8_LAS unsigned char* lds, const Gemm g, const Sched& S, const Epi& E) {
;     ...
;             const bool last = (t == nt - 2);
;             const char* a1 = cA + (size_t)(t + 1) * kstep;
;             const char* a2 = last ? nA : cA + (size_t)(t + 2) * kstep; const char* b2 = last ? nB : cB + (size_t)(t + 2) * kstep;
;             const char* a3 = a2 + kstep; const char* b3 = b2 + kstep;
;             if (last && has_next) S.a_ready(nxt);
;             if constexpr (SP2) {
;             PG8_LDB(B0, 0, 0); PG8_LDB(B1, 0, 1); PG8_SCHED; PG8_LDA(At, 0, 0); PG8_STAGE(PG8_SA(1, 1), a1 + hstep, voffA);
;             PG8_WAIT_V(8); PG8_WAIT_L(0); PG8_BAR; PG8_MMA(0, 0, At, B0); PG8_MMA(0, 1, At, B1); PG8_BAR; PG8_SCHED;
;             PG8_LDA(At, 0, 1); PG8_STAGE(PG8_SB(0, 0), b2, voffB); PG8_STAGE(PG8_SB(0, 1), b2 + hstep, voffB); PG8_STAGE(PG8_SA(0, 0), a2, voffA);
;             PG8_WAIT_V(8); PG8_WAIT_L(0); PG8_BAR; PG8_MMA(1, 0, At, B0); PG8_MMA(1, 1, At, B1); PG8_BAR; PG8_SCHED;
.LBB0_724:
	ds_read_b128 v[144:147], v155
	ds_read_b128 v[148:151], v155 offset:1024
	ds_read_b128 v[160:163], v155 offset:2048
	ds_read_b128 v[164:167], v155 offset:3072
	ds_read_b128 v[168:171], v157
	ds_read_b128 v[172:175], v157 offset:1024
	ds_read_b128 v[176:179], v157 offset:2048
	ds_read_b128 v[180:183], v157 offset:3072
	s_add_u32 s10, s56, 0xfffc0080
	s_addc_u32 s11, s57, -1
	s_cmp_eq_u32 s75, 12
	s_cselect_b32 s61, s49, s11
	s_cselect_b32 s60, s76, s10
	s_cselect_b32 s59, s47, s74
	s_cselect_b32 s58, s77, s78
	v_lshl_add_u64 v[200:201], s[56:57], 0, v[136:137]
	s_add_i32 m0, s39, 0xc000
	ds_read_b128 v[184:187], v158
	ds_read_b128 v[188:191], v158 offset:1024
	ds_read_b128 v[192:195], v158 offset:2048
	ds_read_b128 v[196:199], v158 offset:3072
	ds_read_b128 v[204:207], v158 offset:4096
	ds_read_b128 v[208:211], v158 offset:5120
	ds_read_b128 v[212:215], v158 offset:6144
	ds_read_b128 v[216:219], v158 offset:7168
	global_load_lds_dwordx4 v[200:201], off
	v_lshl_add_u64 v[200:201], s[56:57], 0, v[138:139]
	s_add_i32 m0, s39, 0xe000
	s_nop 0
	global_load_lds_dwordx4 v[200:201], off
	s_waitcnt vmcnt(8)
	s_waitcnt lgkmcnt(0)
	s_barrier
	s_setprio 1
	s_waitcnt lgkmcnt(0)
	v_mfma_f32_16x16x32_bf16 v[124:127], v[144:147], v[184:187], v[124:127]
	v_mfma_f32_16x16x32_bf16 v[120:123], v[160:163], v[184:187], v[120:123]
	v_mfma_f32_16x16x32_bf16 v[116:119], v[144:147], v[192:195], v[116:119]
	v_mfma_f32_16x16x32_bf16 v[112:115], v[160:163], v[192:195], v[112:115]
	v_mfma_f32_16x16x32_bf16 v[96:99], v[144:147], v[204:207], v[96:99]
	v_mfma_f32_16x16x32_bf16 v[88:91], v[160:163], v[204:207], v[88:91]
	v_mfma_f32_16x16x32_bf16 v[80:83], v[144:147], v[212:215], v[80:83]
	v_mfma_f32_16x16x32_bf16 v[72:75], v[160:163], v[212:215], v[72:75]
	v_mfma_f32_16x16x32_bf16 v[124:127], v[148:151], v[188:191], v[124:127]
	v_mfma_f32_16x16x32_bf16 v[120:123], v[164:167], v[188:191], v[120:123]
	v_mfma_f32_16x16x32_bf16 v[116:119], v[148:151], v[196:199], v[116:119]
	v_mfma_f32_16x16x32_bf16 v[112:115], v[164:167], v[196:199], v[112:115]
	v_mfma_f32_16x16x32_bf16 v[96:99], v[148:151], v[208:211], v[96:99]
	v_mfma_f32_16x16x32_bf16 v[88:91], v[164:167], v[208:211], v[88:91]
	v_mfma_f32_16x16x32_bf16 v[80:83], v[148:151], v[216:219], v[80:83]
	v_mfma_f32_16x16x32_bf16 v[72:75], v[164:167], v[216:219], v[72:75]
	s_setprio 0
	s_setprio 1
	v_mfma_f32_16x16x32_bf16 v[108:111], v[168:171], v[184:187], v[108:111]
	v_mfma_f32_16x16x32_bf16 v[104:107], v[176:179], v[184:187], v[104:107]
	v_mfma_f32_16x16x32_bf16 v[100:103], v[168:171], v[192:195], v[100:103]
	v_mfma_f32_16x16x32_bf16 v[92:95], v[176:179], v[192:195], v[92:95]
	v_mfma_f32_16x16x32_bf16 v[84:87], v[168:171], v[204:207], v[84:87]
	v_mfma_f32_16x16x32_bf16 v[76:79], v[176:179], v[204:207], v[76:79]
	v_mfma_f32_16x16x32_bf16 v[68:71], v[168:171], v[212:215], v[68:71]
	v_mfma_f32_16x16x32_bf16 v[64:67], v[176:179], v[212:215], v[64:67]
	s_barrier
	s_setprio 2
	v_mfma_f32_16x16x32_bf16 v[108:111], v[172:175], v[188:191], v[108:111]
	v_mfma_f32_16x16x32_bf16 v[104:107], v[180:183], v[188:191], v[104:107]
	v_mfma_f32_16x16x32_bf16 v[100:103], v[172:175], v[196:199], v[100:103]
	v_mfma_f32_16x16x32_bf16 v[92:95], v[180:183], v[196:199], v[92:95]
	v_mfma_f32_16x16x32_bf16 v[84:87], v[172:175], v[208:211], v[84:87]
	v_mfma_f32_16x16x32_bf16 v[76:79], v[180:183], v[208:211], v[76:79]
	v_mfma_f32_16x16x32_bf16 v[68:71], v[172:175], v[216:219], v[68:71]
	v_mfma_f32_16x16x32_bf16 v[64:67], v[180:183], v[216:219], v[64:67]
	s_setprio 0
	s_add_i32 s10, s71, s33
	v_lshl_add_u64 v[200:201], s[58:59], 0, v[130:131]
	s_mov_b32 m0, s10
	ds_read_b128 v[184:187], v158 offset:16384
	ds_read_b128 v[188:191], v158 offset:17408
	ds_read_b128 v[192:195], v158 offset:18432
	ds_read_b128 v[196:199], v158 offset:19456
	ds_read_b128 v[204:207], v158 offset:20480
	ds_read_b128 v[208:211], v158 offset:21504
	ds_read_b128 v[212:215], v158 offset:22528
	ds_read_b128 v[216:219], v158 offset:23552
	global_load_lds_dwordx4 v[200:201], off
	s_add_i32 m0, s10, 0x2000
	s_add_u32 s10, s58, 0x40000
	v_lshl_add_u64 v[220:221], s[58:59], 0, v[134:135]
	s_addc_u32 s11, s59, 0
	s_add_i32 s79, s72, s33
	global_load_lds_dwordx4 v[220:221], off
	v_lshl_add_u64 v[222:223], s[10:11], 0, v[130:131]
	s_mov_b32 m0, s79
	v_lshl_add_u64 v[224:225], s[60:61], 0, v[132:133]
	global_load_lds_dwordx4 v[222:223], off
	v_lshl_add_u64 v[222:223], s[10:11], 0, v[134:135]
	s_add_i32 m0, s79, 0x2000
	s_nop 0
	global_load_lds_dwordx4 v[222:223], off
	v_lshl_add_u64 v[222:223], s[60:61], 0, v[128:129]
	s_mov_b32 m0, s39
	s_nop 0
	global_load_lds_dwordx4 v[222:223], off
	s_mov_b32 m0, s55
	s_nop 0
	global_load_lds_dwordx4 v[224:225], off
	s_waitcnt vmcnt(8)
	s_waitcnt lgkmcnt(0)
	s_barrier
	s_setprio 1
	s_waitcnt lgkmcnt(0)
	v_mfma_f32_16x16x32_bf16 v[60:63], v[144:147], v[184:187], v[60:63]
	v_mfma_f32_16x16x32_bf16 v[56:59], v[160:163], v[184:187], v[56:59]
	v_mfma_f32_16x16x32_bf16 v[48:51], v[144:147], v[192:195], v[48:51]
	v_mfma_f32_16x16x32_bf16 v[40:43], v[160:163], v[192:195], v[40:43]
	v_mfma_f32_16x16x32_bf16 v[32:35], v[144:147], v[204:207], v[32:35]
	v_mfma_f32_16x16x32_bf16 v[24:27], v[160:163], v[204:207], v[24:27]
	v_mfma_f32_16x16x32_bf16 v[16:19], v[144:147], v[212:215], v[16:19]
	v_mfma_f32_16x16x32_bf16 v[8:11], v[160:163], v[212:215], v[8:11]
	v_mfma_f32_16x16x32_bf16 v[60:63], v[148:151], v[188:191], v[60:63]
	v_mfma_f32_16x16x32_bf16 v[56:59], v[164:167], v[188:191], v[56:59]
	v_mfma_f32_16x16x32_bf16 v[48:51], v[148:151], v[196:199], v[48:51]
	v_mfma_f32_16x16x32_bf16 v[40:43], v[164:167], v[196:199], v[40:43]
	v_mfma_f32_16x16x32_bf16 v[32:35], v[148:151], v[208:211], v[32:35]
	v_mfma_f32_16x16x32_bf16 v[24:27], v[164:167], v[208:211], v[24:27]
	v_mfma_f32_16x16x32_bf16 v[16:19], v[148:151], v[216:219], v[16:19]
	v_mfma_f32_16x16x32_bf16 v[8:11], v[164:167], v[216:219], v[8:11]
	s_setprio 0
	s_setprio 1
	v_mfma_f32_16x16x32_bf16 v[52:55], v[168:171], v[184:187], v[52:55]
	v_mfma_f32_16x16x32_bf16 v[44:47], v[176:179], v[184:187], v[44:47]
	v_mfma_f32_16x16x32_bf16 v[36:39], v[168:171], v[192:195], v[36:39]
	v_mfma_f32_16x16x32_bf16 v[28:31], v[176:179], v[192:195], v[28:31]
	v_mfma_f32_16x16x32_bf16 v[20:23], v[168:171], v[204:207], v[20:23]
	v_mfma_f32_16x16x32_bf16 v[12:15], v[176:179], v[204:207], v[12:15]
	v_mfma_f32_16x16x32_bf16 v[4:7], v[168:171], v[212:215], v[4:7]
	v_mfma_f32_16x16x32_bf16 v[0:3], v[176:179], v[212:215], v[0:3]
	s_barrier
; #define PG8_STAGE(bufoff, gbase, voff) do { _Pragma("unroll") for (int _i = 0; _i < 2; ++_i) \
;         __builtin_amdgcn_global_load_lds((const unsigned*)((const char*)(gbase) + (voff)[_i]), (PG8_LAS unsigned*)(lds + (bufoff) + ldsw + _i * 8192), 16, 0, 0); } while (0)
; #define PG8_LDA(dst, b, h) do { _Pragma("unroll") for (int m = 0; m < 4; ++m) _Pragma("unroll") for (int k = 0; k < 2; ++k) dst[m][k] = *(const PG8_LAS bf16x8*)(lds + PG8_SA(b, h) + aoff + m * 2048 + k * 1024); } while (0)
; #define PG8_LDB(dst, b, h) do { _Pragma("unroll") for (int n = 0; n < 2; ++n) _Pragma("unroll") for (int k = 0; k < 2; ++k) dst[n][k] = *(const PG8_LAS bf16x8*)(lds + PG8_SB(b, h) + boff + n * 2048 + k * 1024); } while (0)
; #define PG8_MMA(ai, bj, At, Bt) do { __builtin_amdgcn_s_setprio(1); _Pragma("unroll") for (int m = 0; m < 4; ++m) _Pragma("unroll") for (int n = 0; n < 2; ++n) _Pragma("unroll") for (int k = 0; k < 2; ++k) \
;         acc[ai][bj][m][n] = __builtin_amdgcn_mfma_f32_16x16x32_bf16(Bt[n][k], At[m][k], acc[ai][bj][m][n], 0, 0, 0); __builtin_amdgcn_s_setprio(0); } while (0)
; #define PG8_WAIT_V(n) asm volatile("s_waitcnt vmcnt(" #n ")" ::: "memory")
; #define PG8_WAIT_L(n) asm volatile("s_waitcnt lgkmcnt(" #n ")" ::: "memory")
; #define PG8_BAR __builtin_amdgcn_s_barrier()
; #define PG8_SCHED __builtin_amdgcn_sched_barrier(0)
; template <class Epi, class Sched, bool ALIGN_EPI = false, bool SP2 = false>
; __device__ __forceinline__ void gemm_phase(PG8_LAS unsigned char* lds, const Gemm g, const Sched& S, const Epi& E) {
;     ...
;             PG8_WAIT_V(8); PG8_WAIT_L(0); PG8_BAR; PG8_MMA(1, 0, At, B0); PG8_MMA(1, 1, At, B1); PG8_BAR; PG8_SCHED;
;             PG8_LDB(B0, 1, 0); PG8_LDB(B1, 1, 1); PG8_SCHED; PG8_LDA(At, 1, 0); PG8_STAGE(PG8_SA(0, 1), a2 + hstep, voffA);
;             PG8_WAIT_V(8); PG8_WAIT_L(0); PG8_BAR; PG8_MMA(0, 0, At, B0); PG8_MMA(0, 1, At, B1); PG8_BAR; PG8_SCHED;
	s_setprio 2
	v_mfma_f32_16x16x32_bf16 v[52:55], v[172:175], v[188:191], v[52:55]
	v_mfma_f32_16x16x32_bf16 v[44:47], v[180:183], v[188:191], v[44:47]
	v_mfma_f32_16x16x32_bf16 v[36:39], v[172:175], v[196:199], v[36:39]
	v_mfma_f32_16x16x32_bf16 v[28:31], v[180:183], v[196:199], v[28:31]
	v_mfma_f32_16x16x32_bf16 v[20:23], v[172:175], v[208:211], v[20:23]
	v_mfma_f32_16x16x32_bf16 v[12:15], v[180:183], v[208:211], v[12:15]
	v_mfma_f32_16x16x32_bf16 v[4:7], v[172:175], v[216:219], v[4:7]
	v_mfma_f32_16x16x32_bf16 v[0:3], v[180:183], v[216:219], v[0:3]
	s_setprio 0
	s_add_i32 s79, 0, 0x18000
	v_add_u32_e32 v159, s79, v153
	s_add_i32 s80, 0, 0x1c000
	ds_read_b128 v[144:147], v159
	ds_read_b128 v[148:151], v159 offset:1024
	ds_read_b128 v[160:163], v159 offset:2048
	ds_read_b128 v[164:167], v159 offset:3072
	v_add_u32_e32 v159, s80, v153
	ds_read_b128 v[168:171], v159
	ds_read_b128 v[172:175], v159 offset:1024
	ds_read_b128 v[176:179], v159 offset:2048
	ds_read_b128 v[180:183], v159 offset:3072
	s_add_u32 s10, s60, 0x40000
	s_addc_u32 s11, s61, 0
	s_mov_b32 m0, s62
	v_lshl_add_u64 v[226:227], s[10:11], 0, v[128:129]
	ds_read_b128 v[184:187], v158 offset:32768
	ds_read_b128 v[188:191], v158 offset:33792
	ds_read_b128 v[192:195], v158 offset:34816
	ds_read_b128 v[196:199], v158 offset:35840
	ds_read_b128 v[204:207], v158 offset:36864
	ds_read_b128 v[208:211], v158 offset:37888
	ds_read_b128 v[212:215], v158 offset:38912
	ds_read_b128 v[216:219], v158 offset:39936
	global_load_lds_dwordx4 v[226:227], off
	v_lshl_add_u64 v[226:227], s[10:11], 0, v[132:133]
	s_mov_b32 m0, s63
	s_nop 0
	global_load_lds_dwordx4 v[226:227], off
	s_waitcnt vmcnt(8)
	s_waitcnt lgkmcnt(0)
	s_barrier
	s_setprio 1
	s_waitcnt lgkmcnt(0)
	v_mfma_f32_16x16x32_bf16 v[124:127], v[144:147], v[184:187], v[124:127]
	v_mfma_f32_16x16x32_bf16 v[120:123], v[160:163], v[184:187], v[120:123]
	v_mfma_f32_16x16x32_bf16 v[116:119], v[144:147], v[192:195], v[116:119]
	v_mfma_f32_16x16x32_bf16 v[112:115], v[160:163], v[192:195], v[112:115]
	v_mfma_f32_16x16x32_bf16 v[96:99], v[144:147], v[204:207], v[96:99]
	v_mfma_f32_16x16x32_bf16 v[88:91], v[160:163], v[204:207], v[88:91]
	v_mfma_f32_16x16x32_bf16 v[80:83], v[144:147], v[212:215], v[80:83]
	v_mfma_f32_16x16x32_bf16 v[72:75], v[160:163], v[212:215], v[72:75]
	v_mfma_f32_16x16x32_bf16 v[124:127], v[148:151], v[188:191], v[124:127]
	v_mfma_f32_16x16x32_bf16 v[120:123], v[164:167], v[188:191], v[120:123]
	v_mfma_f32_16x16x32_bf16 v[116:119], v[148:151], v[196:199], v[116:119]
	v_mfma_f32_16x16x32_bf16 v[112:115], v[164:167], v[196:199], v[112:115]
	v_mfma_f32_16x16x32_bf16 v[96:99], v[148:151], v[208:211], v[96:99]
	v_mfma_f32_16x16x32_bf16 v[88:91], v[164:167], v[208:211], v[88:91]
	v_mfma_f32_16x16x32_bf16 v[80:83], v[148:151], v[216:219], v[80:83]
	v_mfma_f32_16x16x32_bf16 v[72:75], v[164:167], v[216:219], v[72:75]
	s_setprio 0
	s_setprio 1
	v_mfma_f32_16x16x32_bf16 v[108:111], v[168:171], v[184:187], v[108:111]
	v_mfma_f32_16x16x32_bf16 v[104:107], v[176:179], v[184:187], v[104:107]
	v_mfma_f32_16x16x32_bf16 v[100:103], v[168:171], v[192:195], v[100:103]
	v_mfma_f32_16x16x32_bf16 v[92:95], v[176:179], v[192:195], v[92:95]
	v_mfma_f32_16x16x32_bf16 v[84:87], v[168:171], v[204:207], v[84:87]
	v_mfma_f32_16x16x32_bf16 v[76:79], v[176:179], v[204:207], v[76:79]
	v_mfma_f32_16x16x32_bf16 v[68:71], v[168:171], v[212:215], v[68:71]
	v_mfma_f32_16x16x32_bf16 v[64:67], v[176:179], v[212:215], v[64:67]
	s_barrier
; #define PG8_STAGE(bufoff, gbase, voff) do { _Pragma("unroll") for (int _i = 0; _i < 2; ++_i) \
;         __builtin_amdgcn_global_load_lds((const unsigned*)((const char*)(gbase) + (voff)[_i]), (PG8_LAS unsigned*)(lds + (bufoff) + ldsw + _i * 8192), 16, 0, 0); } while (0)
; #define PG8_LDA(dst, b, h) do { _Pragma("unroll") for (int m = 0; m < 4; ++m) _Pragma("unroll") for (int k = 0; k < 2; ++k) dst[m][k] = *(const PG8_LAS bf16x8*)(lds + PG8_SA(b, h) + aoff + m * 2048 + k * 1024); } while (0)
; #define PG8_MMA(ai, bj, At, Bt) do { __builtin_amdgcn_s_setprio(1); _Pragma("unroll") for (int m = 0; m < 4; ++m) _Pragma("unroll") for (int n = 0; n < 2; ++n) _Pragma("unroll") for (int k = 0; k < 2; ++k) \
;         acc[ai][bj][m][n] = __builtin_amdgcn_mfma_f32_16x16x32_bf16(Bt[n][k], At[m][k], acc[ai][bj][m][n], 0, 0, 0); __builtin_amdgcn_s_setprio(0); } while (0)
; #define PG8_WAIT_V(n) asm volatile("s_waitcnt vmcnt(" #n ")" ::: "memory")
; #define PG8_WAIT_L(n) asm volatile("s_waitcnt lgkmcnt(" #n ")" ::: "memory")
; #define PG8_BAR __builtin_amdgcn_s_barrier()
; #define PG8_SCHED __builtin_amdgcn_sched_barrier(0)
; template <class Epi, class Sched, bool ALIGN_EPI = false, bool SP2 = false>
; __device__ __forceinline__ void gemm_phase(PG8_LAS unsigned char* lds, const Gemm g, const Sched& S, const Epi& E) {
;     ...
;             PG8_WAIT_V(8); PG8_WAIT_L(0); PG8_BAR; PG8_MMA(0, 0, At, B0); PG8_MMA(0, 1, At, B1); PG8_BAR; PG8_SCHED;
;             PG8_LDA(At, 1, 1); PG8_STAGE(PG8_SB(1, 0), b3, voffB); PG8_STAGE(PG8_SB(1, 1), b3 + hstep, voffB); PG8_STAGE(PG8_SA(1, 0), a3, voffA);
;             PG8_WAIT_V(8); PG8_WAIT_L(0); PG8_BAR; PG8_MMA(1, 0, At, B0); PG8_MMA(1, 1, At, B1); PG8_BAR; PG8_SCHED;
;     ...
;         if constexpr (ALIGN_EPI) { if (wr == 0) PG8_BAR; }
	s_setprio 2
	v_mfma_f32_16x16x32_bf16 v[108:111], v[172:175], v[188:191], v[108:111]
	v_mfma_f32_16x16x32_bf16 v[104:107], v[180:183], v[188:191], v[104:107]
	v_mfma_f32_16x16x32_bf16 v[100:103], v[172:175], v[196:199], v[100:103]
	v_mfma_f32_16x16x32_bf16 v[92:95], v[180:183], v[196:199], v[92:95]
	v_mfma_f32_16x16x32_bf16 v[84:87], v[172:175], v[208:211], v[84:87]
	v_mfma_f32_16x16x32_bf16 v[76:79], v[180:183], v[208:211], v[76:79]
	v_mfma_f32_16x16x32_bf16 v[68:71], v[172:175], v[216:219], v[68:71]
	v_mfma_f32_16x16x32_bf16 v[64:67], v[180:183], v[216:219], v[64:67]
	s_setprio 0
	s_add_i32 s10, s79, s33
	v_lshl_add_u64 v[200:201], v[200:201], 0, s[22:23]
	s_mov_b32 m0, s10
	ds_read_b128 v[184:187], v158 offset:49152
	ds_read_b128 v[188:191], v158 offset:50176
	ds_read_b128 v[192:195], v158 offset:51200
	ds_read_b128 v[196:199], v158 offset:52224
	ds_read_b128 v[204:207], v158 offset:53248
	ds_read_b128 v[208:211], v158 offset:54272
	ds_read_b128 v[212:215], v158 offset:55296
	ds_read_b128 v[216:219], v158 offset:56320
	global_load_lds_dwordx4 v[200:201], off
	s_add_i32 m0, s10, 0x2000
	s_add_u32 s10, s58, 0x40080
	v_lshl_add_u64 v[200:201], v[220:221], 0, s[22:23]
	s_addc_u32 s11, s59, 0
	s_add_i32 s58, s80, s33
	global_load_lds_dwordx4 v[200:201], off
	v_lshl_add_u64 v[200:201], s[10:11], 0, v[130:131]
	s_mov_b32 m0, s58
	s_nop 0
	global_load_lds_dwordx4 v[200:201], off
	v_lshl_add_u64 v[200:201], s[10:11], 0, v[134:135]
	s_add_i32 m0, s58, 0x2000
	s_nop 0
	global_load_lds_dwordx4 v[200:201], off
	v_lshl_add_u64 v[200:201], v[222:223], 0, s[22:23]
	s_mov_b32 m0, s65
	s_nop 0
	global_load_lds_dwordx4 v[200:201], off
	v_lshl_add_u64 v[200:201], v[224:225], 0, s[22:23]
	s_mov_b32 m0, s66
	s_nop 0
	global_load_lds_dwordx4 v[200:201], off
	s_waitcnt vmcnt(8)
	s_waitcnt lgkmcnt(0)
	s_barrier
	s_setprio 1
	s_waitcnt lgkmcnt(0)
	v_mfma_f32_16x16x32_bf16 v[60:63], v[144:147], v[184:187], v[60:63]
	v_mfma_f32_16x16x32_bf16 v[56:59], v[160:163], v[184:187], v[56:59]
	v_mfma_f32_16x16x32_bf16 v[48:51], v[144:147], v[192:195], v[48:51]
	v_mfma_f32_16x16x32_bf16 v[40:43], v[160:163], v[192:195], v[40:43]
	v_mfma_f32_16x16x32_bf16 v[32:35], v[144:147], v[204:207], v[32:35]
	v_mfma_f32_16x16x32_bf16 v[24:27], v[160:163], v[204:207], v[24:27]
	v_mfma_f32_16x16x32_bf16 v[16:19], v[144:147], v[212:215], v[16:19]
	v_mfma_f32_16x16x32_bf16 v[8:11], v[160:163], v[212:215], v[8:11]
	v_mfma_f32_16x16x32_bf16 v[60:63], v[148:151], v[188:191], v[60:63]
	v_mfma_f32_16x16x32_bf16 v[56:59], v[164:167], v[188:191], v[56:59]
	v_mfma_f32_16x16x32_bf16 v[48:51], v[148:151], v[196:199], v[48:51]
	v_mfma_f32_16x16x32_bf16 v[40:43], v[164:167], v[196:199], v[40:43]
	v_mfma_f32_16x16x32_bf16 v[32:35], v[148:151], v[208:211], v[32:35]
	v_mfma_f32_16x16x32_bf16 v[24:27], v[164:167], v[208:211], v[24:27]
	v_mfma_f32_16x16x32_bf16 v[16:19], v[148:151], v[216:219], v[16:19]
	v_mfma_f32_16x16x32_bf16 v[8:11], v[164:167], v[216:219], v[8:11]
	s_setprio 0
	s_setprio 1
	v_mfma_f32_16x16x32_bf16 v[52:55], v[168:171], v[184:187], v[52:55]
	v_mfma_f32_16x16x32_bf16 v[44:47], v[176:179], v[184:187], v[44:47]
	v_mfma_f32_16x16x32_bf16 v[36:39], v[168:171], v[192:195], v[36:39]
	v_mfma_f32_16x16x32_bf16 v[28:31], v[176:179], v[192:195], v[28:31]
	v_mfma_f32_16x16x32_bf16 v[20:23], v[168:171], v[204:207], v[20:23]
	v_mfma_f32_16x16x32_bf16 v[12:15], v[176:179], v[204:207], v[12:15]
	v_mfma_f32_16x16x32_bf16 v[4:7], v[168:171], v[212:215], v[4:7]
	v_mfma_f32_16x16x32_bf16 v[0:3], v[176:179], v[212:215], v[0:3]
	s_barrier
	s_setprio 2
	v_mfma_f32_16x16x32_bf16 v[52:55], v[172:175], v[188:191], v[52:55]
	v_mfma_f32_16x16x32_bf16 v[44:47], v[180:183], v[188:191], v[44:47]
	v_mfma_f32_16x16x32_bf16 v[36:39], v[172:175], v[196:199], v[36:39]
	v_mfma_f32_16x16x32_bf16 v[28:31], v[180:183], v[196:199], v[28:31]
	v_mfma_f32_16x16x32_bf16 v[20:23], v[172:175], v[208:211], v[20:23]
	v_mfma_f32_16x16x32_bf16 v[12:15], v[180:183], v[208:211], v[12:15]
	v_mfma_f32_16x16x32_bf16 v[4:7], v[172:175], v[216:219], v[4:7]
	v_mfma_f32_16x16x32_bf16 v[0:3], v[180:183], v[216:219], v[0:3]
	s_setprio 0
	s_add_i32 s75, s75, 2
	s_add_u32 s56, s56, 0x100
	s_addc_u32 s57, s57, 0
	s_add_u32 s78, s78, 0x100
	s_addc_u32 s74, s74, 0
	s_cmp_gt_u32 s75, 13
	s_cbranch_scc0 .LBB0_724
	s_and_b64 vcc, exec, s[36:37]
	s_cbranch_vccz .LBB0_727
	s_barrier

; #define PG8_STAGE(bufoff, gbase, voff) do { _Pragma("unroll") for (int _i = 0; _i < 2; ++_i) \
;         __builtin_amdgcn_global_load_lds((const unsigned*)((const char*)(gbase) + (voff)[_i]), (PG8_LAS unsigned*)(lds + (bufoff) + ldsw + _i * 8192), 16, 0, 0); } while (0)
; #define PG8_LDA(dst, b, h) do { _Pragma("unroll") for (int m = 0; m < 4; ++m) _Pragma("unroll") for (int k = 0; k < 2; ++k) dst[m][k] = *(const PG8_LAS bf16x8*)(lds + PG8_SA(b, h) + aoff + m * 2048 + k * 1024); } while (0)
; #define PG8_LDB(dst, b, h) do { _Pragma("unroll") for (int n = 0; n < 2; ++n) _Pragma("unroll") for (int k = 0; k < 2; ++k) dst[n][k] = *(const PG8_LAS bf16x8*)(lds + PG8_SB(b, h) + boff + n * 2048 + k * 1024); } while (0)
; #define PG8_MMA(ai, bj, At, Bt) do { __builtin_amdgcn_s_setprio(1); _Pragma("unroll") for (int m = 0; m < 4; ++m) _Pragma("unroll") for (int n = 0; n < 2; ++n) _Pragma("unroll") for (int k = 0; k < 2; ++k) \
;         acc[ai][bj][m][n] = __builtin_amdgcn_mfma_f32_16x16x32_bf16(Bt[n][k], At[m][k], acc[ai][bj][m][n], 0, 0, 0); __builtin_amdgcn_s_setprio(0); } while (0)
; #define PG8_WAIT_V(n) asm volatile("s_waitcnt vmcnt(" #n ")" ::: "memory")
; #define PG8_WAIT_L(n) asm volatile("s_waitcnt lgkmcnt(" #n ")" ::: "memory")
; template <class Epi, class Sched, bool ALIGN_EPI = false, bool SP2 = false>
; __device__ __forceinline__ void gemm_phase(PG8_LAS unsigned char* lds, const Gemm g, const Sched& S, const Epi& E) {
;     ...
;             const bool last = (t == nt - 2);
;             const char* a1 = cA + (size_t)(t + 1) * kstep;
;             const char* a2 = last ? nA : cA + (size_t)(t + 2) * kstep; const char* b2 = last ? nB : cB + (size_t)(t + 2) * kstep;
;             const char* a3 = a2 + kstep; const char* b3 = b2 + kstep;
;             if (last && has_next) S.a_ready(nxt);
;             if constexpr (SP2) {
;             PG8_LDB(B0, 0, 0); PG8_LDB(B1, 0, 1); PG8_SCHED; PG8_LDA(At, 0, 0); PG8_STAGE(PG8_SA(1, 1), a1 + hstep, voffA);
;             PG8_WAIT_V(8); PG8_WAIT_L(0); PG8_BAR; PG8_MMA(0, 0, At, B0); PG8_MMA(0, 1, At, B1); PG8_BAR; PG8_SCHED;
;             PG8_LDA(At, 0, 1); PG8_STAGE(PG8_SB(0, 0), b2, voffB); PG8_STAGE(PG8_SB(0, 1), b2 + hstep, voffB); PG8_STAGE(PG8_SA(0, 0), a2, voffA);
;             PG8_WAIT_V(8); PG8_WAIT_L(0); PG8_BAR; PG8_MMA(1, 0, At, B0); PG8_MMA(1, 1, At, B1); PG8_BAR; PG8_SCHED;
.LBB0_848:
	ds_read_b128 v[150:153], v147
	ds_read_b128 v[158:161], v147 offset:1024
	ds_read_b128 v[162:165], v147 offset:2048
	ds_read_b128 v[166:169], v147 offset:3072
	ds_read_b128 v[170:173], v148
	ds_read_b128 v[174:177], v148 offset:1024
	ds_read_b128 v[178:181], v148 offset:2048
	ds_read_b128 v[182:185], v148 offset:3072
	s_add_u32 s42, s40, 0xfffc0080
	s_addc_u32 s43, s41, -1
	s_cmp_eq_u32 s63, 12
	s_cselect_b32 s45, s17, s43
	s_cselect_b32 s44, s59, s42
	s_cselect_b32 s43, s15, s62
	s_cselect_b32 s42, s60, s61
	v_lshl_add_u64 v[154:155], s[40:41], 0, v[136:137]
	s_add_i32 m0, s39, 0xc000
	ds_read_b128 v[186:189], v149
	ds_read_b128 v[190:193], v149 offset:1024
	ds_read_b128 v[194:197], v149 offset:2048
	ds_read_b128 v[198:201], v149 offset:3072
	ds_read_b128 v[204:207], v149 offset:4096
	ds_read_b128 v[208:211], v149 offset:5120
	ds_read_b128 v[212:215], v149 offset:6144
	ds_read_b128 v[216:219], v149 offset:7168
	global_load_lds_dwordx4 v[154:155], off
	v_lshl_add_u64 v[154:155], s[40:41], 0, v[138:139]
	s_add_i32 m0, s39, 0xe000
	s_nop 0
	global_load_lds_dwordx4 v[154:155], off
	s_waitcnt vmcnt(8)
	s_waitcnt lgkmcnt(0)
	s_barrier
	s_setprio 1
	s_waitcnt lgkmcnt(0)
	v_mfma_f32_16x16x32_bf16 v[124:127], v[150:153], v[186:189], v[124:127]
	v_mfma_f32_16x16x32_bf16 v[120:123], v[162:165], v[186:189], v[120:123]
	v_mfma_f32_16x16x32_bf16 v[108:111], v[150:153], v[194:197], v[108:111]
	v_mfma_f32_16x16x32_bf16 v[104:107], v[162:165], v[194:197], v[104:107]
	v_mfma_f32_16x16x32_bf16 v[92:95], v[150:153], v[204:207], v[92:95]
	v_mfma_f32_16x16x32_bf16 v[88:91], v[162:165], v[204:207], v[88:91]
	v_mfma_f32_16x16x32_bf16 v[76:79], v[150:153], v[212:215], v[76:79]
	v_mfma_f32_16x16x32_bf16 v[72:75], v[162:165], v[212:215], v[72:75]
	v_mfma_f32_16x16x32_bf16 v[124:127], v[158:161], v[190:193], v[124:127]
	v_mfma_f32_16x16x32_bf16 v[120:123], v[166:169], v[190:193], v[120:123]
	v_mfma_f32_16x16x32_bf16 v[108:111], v[158:161], v[198:201], v[108:111]
	v_mfma_f32_16x16x32_bf16 v[104:107], v[166:169], v[198:201], v[104:107]
	v_mfma_f32_16x16x32_bf16 v[92:95], v[158:161], v[208:211], v[92:95]
	v_mfma_f32_16x16x32_bf16 v[88:91], v[166:169], v[208:211], v[88:91]
	v_mfma_f32_16x16x32_bf16 v[76:79], v[158:161], v[216:219], v[76:79]
	v_mfma_f32_16x16x32_bf16 v[72:75], v[166:169], v[216:219], v[72:75]
	s_setprio 0
	s_setprio 1
	v_mfma_f32_16x16x32_bf16 v[116:119], v[170:173], v[186:189], v[116:119]
	v_mfma_f32_16x16x32_bf16 v[112:115], v[178:181], v[186:189], v[112:115]
	v_mfma_f32_16x16x32_bf16 v[100:103], v[170:173], v[194:197], v[100:103]
	v_mfma_f32_16x16x32_bf16 v[96:99], v[178:181], v[194:197], v[96:99]
	v_mfma_f32_16x16x32_bf16 v[84:87], v[170:173], v[204:207], v[84:87]
	v_mfma_f32_16x16x32_bf16 v[80:83], v[178:181], v[204:207], v[80:83]
	v_mfma_f32_16x16x32_bf16 v[68:71], v[170:173], v[212:215], v[68:71]
	v_mfma_f32_16x16x32_bf16 v[64:67], v[178:181], v[212:215], v[64:67]
	s_barrier
	s_setprio 2
	v_mfma_f32_16x16x32_bf16 v[116:119], v[174:177], v[190:193], v[116:119]
	v_mfma_f32_16x16x32_bf16 v[112:115], v[182:185], v[190:193], v[112:115]
	v_mfma_f32_16x16x32_bf16 v[100:103], v[174:177], v[198:201], v[100:103]
	v_mfma_f32_16x16x32_bf16 v[96:99], v[182:185], v[198:201], v[96:99]
	v_mfma_f32_16x16x32_bf16 v[84:87], v[174:177], v[208:211], v[84:87]
	v_mfma_f32_16x16x32_bf16 v[80:83], v[182:185], v[208:211], v[80:83]
	v_mfma_f32_16x16x32_bf16 v[68:71], v[174:177], v[216:219], v[68:71]
	v_mfma_f32_16x16x32_bf16 v[64:67], v[182:185], v[216:219], v[64:67]
	s_setprio 0
	s_add_i32 s64, s55, s33
	v_lshl_add_u64 v[154:155], s[42:43], 0, v[132:133]
	s_mov_b32 m0, s64
	ds_read_b128 v[186:189], v149 offset:16384
	ds_read_b128 v[190:193], v149 offset:17408
	ds_read_b128 v[194:197], v149 offset:18432
	ds_read_b128 v[198:201], v149 offset:19456
	ds_read_b128 v[204:207], v149 offset:20480
	ds_read_b128 v[208:211], v149 offset:21504
	ds_read_b128 v[212:215], v149 offset:22528
	ds_read_b128 v[216:219], v149 offset:23552
	global_load_lds_dwordx4 v[154:155], off
	s_add_i32 m0, s64, 0x2000
	s_add_u32 s64, s42, 0x40000
	v_lshl_add_u64 v[220:221], s[42:43], 0, v[128:129]
	s_addc_u32 s65, s43, 0
	s_add_i32 s66, s56, s33
	global_load_lds_dwordx4 v[220:221], off
	v_lshl_add_u64 v[222:223], s[64:65], 0, v[132:133]
	s_mov_b32 m0, s66
	v_lshl_add_u64 v[224:225], s[44:45], 0, v[130:131]
	global_load_lds_dwordx4 v[222:223], off
	v_lshl_add_u64 v[222:223], s[64:65], 0, v[128:129]
	s_add_i32 m0, s66, 0x2000
	s_nop 0
	global_load_lds_dwordx4 v[222:223], off
	v_lshl_add_u64 v[222:223], s[44:45], 0, v[134:135]
	s_mov_b32 m0, s39
	s_nop 0
	global_load_lds_dwordx4 v[222:223], off
	s_mov_b32 m0, s47
	s_nop 0
	global_load_lds_dwordx4 v[224:225], off
	s_waitcnt vmcnt(8)
	s_waitcnt lgkmcnt(0)
	s_barrier
	s_setprio 1
	s_waitcnt lgkmcnt(0)
	v_mfma_f32_16x16x32_bf16 v[60:63], v[150:153], v[186:189], v[60:63]
	v_mfma_f32_16x16x32_bf16 v[56:59], v[162:165], v[186:189], v[56:59]
	v_mfma_f32_16x16x32_bf16 v[44:47], v[150:153], v[194:197], v[44:47]
	v_mfma_f32_16x16x32_bf16 v[40:43], v[162:165], v[194:197], v[40:43]
	v_mfma_f32_16x16x32_bf16 v[28:31], v[150:153], v[204:207], v[28:31]
	v_mfma_f32_16x16x32_bf16 v[24:27], v[162:165], v[204:207], v[24:27]
	v_mfma_f32_16x16x32_bf16 v[12:15], v[150:153], v[212:215], v[12:15]
	v_mfma_f32_16x16x32_bf16 v[8:11], v[162:165], v[212:215], v[8:11]
	v_mfma_f32_16x16x32_bf16 v[60:63], v[158:161], v[190:193], v[60:63]
	v_mfma_f32_16x16x32_bf16 v[56:59], v[166:169], v[190:193], v[56:59]
	v_mfma_f32_16x16x32_bf16 v[44:47], v[158:161], v[198:201], v[44:47]
	v_mfma_f32_16x16x32_bf16 v[40:43], v[166:169], v[198:201], v[40:43]
	v_mfma_f32_16x16x32_bf16 v[28:31], v[158:161], v[208:211], v[28:31]
	v_mfma_f32_16x16x32_bf16 v[24:27], v[166:169], v[208:211], v[24:27]
	v_mfma_f32_16x16x32_bf16 v[12:15], v[158:161], v[216:219], v[12:15]
	v_mfma_f32_16x16x32_bf16 v[8:11], v[166:169], v[216:219], v[8:11]
	s_setprio 0
	s_setprio 1
	v_mfma_f32_16x16x32_bf16 v[52:55], v[170:173], v[186:189], v[52:55]
	v_mfma_f32_16x16x32_bf16 v[48:51], v[178:181], v[186:189], v[48:51]
	v_mfma_f32_16x16x32_bf16 v[36:39], v[170:173], v[194:197], v[36:39]
	v_mfma_f32_16x16x32_bf16 v[32:35], v[178:181], v[194:197], v[32:35]
	v_mfma_f32_16x16x32_bf16 v[20:23], v[170:173], v[204:207], v[20:23]
	v_mfma_f32_16x16x32_bf16 v[16:19], v[178:181], v[204:207], v[16:19]
	v_mfma_f32_16x16x32_bf16 v[4:7], v[170:173], v[212:215], v[4:7]
	v_mfma_f32_16x16x32_bf16 v[0:3], v[178:181], v[212:215], v[0:3]
	s_barrier
; #define PG8_STAGE(bufoff, gbase, voff) do { _Pragma("unroll") for (int _i = 0; _i < 2; ++_i) \
;         __builtin_amdgcn_global_load_lds((const unsigned*)((const char*)(gbase) + (voff)[_i]), (PG8_LAS unsigned*)(lds + (bufoff) + ldsw + _i * 8192), 16, 0, 0); } while (0)
; #define PG8_LDA(dst, b, h) do { _Pragma("unroll") for (int m = 0; m < 4; ++m) _Pragma("unroll") for (int k = 0; k < 2; ++k) dst[m][k] = *(const PG8_LAS bf16x8*)(lds + PG8_SA(b, h) + aoff + m * 2048 + k * 1024); } while (0)
; #define PG8_LDB(dst, b, h) do { _Pragma("unroll") for (int n = 0; n < 2; ++n) _Pragma("unroll") for (int k = 0; k < 2; ++k) dst[n][k] = *(const PG8_LAS bf16x8*)(lds + PG8_SB(b, h) + boff + n * 2048 + k * 1024); } while (0)
; #define PG8_MMA(ai, bj, At, Bt) do { __builtin_amdgcn_s_setprio(1); _Pragma("unroll") for (int m = 0; m < 4; ++m) _Pragma("unroll") for (int n = 0; n < 2; ++n) _Pragma("unroll") for (int k = 0; k < 2; ++k) \
;         acc[ai][bj][m][n] = __builtin_amdgcn_mfma_f32_16x16x32_bf16(Bt[n][k], At[m][k], acc[ai][bj][m][n], 0, 0, 0); __builtin_amdgcn_s_setprio(0); } while (0)
; #define PG8_WAIT_V(n) asm volatile("s_waitcnt vmcnt(" #n ")" ::: "memory")
; #define PG8_WAIT_L(n) asm volatile("s_waitcnt lgkmcnt(" #n ")" ::: "memory")
; #define PG8_BAR __builtin_amdgcn_s_barrier()
; #define PG8_SCHED __builtin_amdgcn_sched_barrier(0)
; template <class Epi, class Sched, bool ALIGN_EPI = false, bool SP2 = false>
; __device__ __forceinline__ void gemm_phase(PG8_LAS unsigned char* lds, const Gemm g, const Sched& S, const Epi& E) {
;     ...
;             PG8_WAIT_V(8); PG8_WAIT_L(0); PG8_BAR; PG8_MMA(1, 0, At, B0); PG8_MMA(1, 1, At, B1); PG8_BAR; PG8_SCHED;
;             PG8_LDB(B0, 1, 0); PG8_LDB(B1, 1, 1); PG8_SCHED; PG8_LDA(At, 1, 0); PG8_STAGE(PG8_SA(0, 1), a2 + hstep, voffA);
;             PG8_WAIT_V(8); PG8_WAIT_L(0); PG8_BAR; PG8_MMA(0, 0, At, B0); PG8_MMA(0, 1, At, B1); PG8_BAR; PG8_SCHED;
	s_setprio 2
	v_mfma_f32_16x16x32_bf16 v[52:55], v[174:177], v[190:193], v[52:55]
	v_mfma_f32_16x16x32_bf16 v[48:51], v[182:185], v[190:193], v[48:51]
	v_mfma_f32_16x16x32_bf16 v[36:39], v[174:177], v[198:201], v[36:39]
	v_mfma_f32_16x16x32_bf16 v[32:35], v[182:185], v[198:201], v[32:35]
	v_mfma_f32_16x16x32_bf16 v[20:23], v[174:177], v[208:211], v[20:23]
	v_mfma_f32_16x16x32_bf16 v[16:19], v[182:185], v[208:211], v[16:19]
	v_mfma_f32_16x16x32_bf16 v[4:7], v[174:177], v[216:219], v[4:7]
	v_mfma_f32_16x16x32_bf16 v[0:3], v[182:185], v[216:219], v[0:3]
	s_setprio 0
	s_add_i32 s64, 0, 0x18000
	v_add_u32_e32 v157, s64, v145
	s_add_i32 s65, 0, 0x1c000
	ds_read_b128 v[150:153], v157
	ds_read_b128 v[158:161], v157 offset:1024
	ds_read_b128 v[162:165], v157 offset:2048
	ds_read_b128 v[166:169], v157 offset:3072
	v_add_u32_e32 v157, s65, v145
	ds_read_b128 v[170:173], v157
	ds_read_b128 v[174:177], v157 offset:1024
	ds_read_b128 v[178:181], v157 offset:2048
	ds_read_b128 v[182:185], v157 offset:3072
	s_add_u32 s44, s44, 0x40000
	s_addc_u32 s45, s45, 0
	s_mov_b32 m0, s48
	v_lshl_add_u64 v[226:227], s[44:45], 0, v[134:135]
	ds_read_b128 v[186:189], v149 offset:32768
	ds_read_b128 v[190:193], v149 offset:33792
	ds_read_b128 v[194:197], v149 offset:34816
	ds_read_b128 v[198:201], v149 offset:35840
	ds_read_b128 v[204:207], v149 offset:36864
	ds_read_b128 v[208:211], v149 offset:37888
	ds_read_b128 v[212:215], v149 offset:38912
	ds_read_b128 v[216:219], v149 offset:39936
	global_load_lds_dwordx4 v[226:227], off
	v_lshl_add_u64 v[226:227], s[44:45], 0, v[130:131]
	s_mov_b32 m0, s49
	s_nop 0
	global_load_lds_dwordx4 v[226:227], off
	s_waitcnt vmcnt(8)
	s_waitcnt lgkmcnt(0)
	s_barrier
	s_setprio 1
	s_waitcnt lgkmcnt(0)
	v_mfma_f32_16x16x32_bf16 v[124:127], v[150:153], v[186:189], v[124:127]
	v_mfma_f32_16x16x32_bf16 v[120:123], v[162:165], v[186:189], v[120:123]
	v_mfma_f32_16x16x32_bf16 v[108:111], v[150:153], v[194:197], v[108:111]
	v_mfma_f32_16x16x32_bf16 v[104:107], v[162:165], v[194:197], v[104:107]
	v_mfma_f32_16x16x32_bf16 v[92:95], v[150:153], v[204:207], v[92:95]
	v_mfma_f32_16x16x32_bf16 v[88:91], v[162:165], v[204:207], v[88:91]
	v_mfma_f32_16x16x32_bf16 v[76:79], v[150:153], v[212:215], v[76:79]
	v_mfma_f32_16x16x32_bf16 v[72:75], v[162:165], v[212:215], v[72:75]
	v_mfma_f32_16x16x32_bf16 v[124:127], v[158:161], v[190:193], v[124:127]
	v_mfma_f32_16x16x32_bf16 v[120:123], v[166:169], v[190:193], v[120:123]
	v_mfma_f32_16x16x32_bf16 v[108:111], v[158:161], v[198:201], v[108:111]
	v_mfma_f32_16x16x32_bf16 v[104:107], v[166:169], v[198:201], v[104:107]
	v_mfma_f32_16x16x32_bf16 v[92:95], v[158:161], v[208:211], v[92:95]
	v_mfma_f32_16x16x32_bf16 v[88:91], v[166:169], v[208:211], v[88:91]
	v_mfma_f32_16x16x32_bf16 v[76:79], v[158:161], v[216:219], v[76:79]
	v_mfma_f32_16x16x32_bf16 v[72:75], v[166:169], v[216:219], v[72:75]
	s_setprio 0
	s_setprio 1
	v_mfma_f32_16x16x32_bf16 v[116:119], v[170:173], v[186:189], v[116:119]
	v_mfma_f32_16x16x32_bf16 v[112:115], v[178:181], v[186:189], v[112:115]
	v_mfma_f32_16x16x32_bf16 v[100:103], v[170:173], v[194:197], v[100:103]
	v_mfma_f32_16x16x32_bf16 v[96:99], v[178:181], v[194:197], v[96:99]
	v_mfma_f32_16x16x32_bf16 v[84:87], v[170:173], v[204:207], v[84:87]
	v_mfma_f32_16x16x32_bf16 v[80:83], v[178:181], v[204:207], v[80:83]
	v_mfma_f32_16x16x32_bf16 v[68:71], v[170:173], v[212:215], v[68:71]
	v_mfma_f32_16x16x32_bf16 v[64:67], v[178:181], v[212:215], v[64:67]
	s_barrier
; #define PG8_STAGE(bufoff, gbase, voff) do { _Pragma("unroll") for (int _i = 0; _i < 2; ++_i) \
;         __builtin_amdgcn_global_load_lds((const unsigned*)((const char*)(gbase) + (voff)[_i]), (PG8_LAS unsigned*)(lds + (bufoff) + ldsw + _i * 8192), 16, 0, 0); } while (0)
; #define PG8_LDA(dst, b, h) do { _Pragma("unroll") for (int m = 0; m < 4; ++m) _Pragma("unroll") for (int k = 0; k < 2; ++k) dst[m][k] = *(const PG8_LAS bf16x8*)(lds + PG8_SA(b, h) + aoff + m * 2048 + k * 1024); } while (0)
; #define PG8_MMA(ai, bj, At, Bt) do { __builtin_amdgcn_s_setprio(1); _Pragma("unroll") for (int m = 0; m < 4; ++m) _Pragma("unroll") for (int n = 0; n < 2; ++n) _Pragma("unroll") for (int k = 0; k < 2; ++k) \
;         acc[ai][bj][m][n] = __builtin_amdgcn_mfma_f32_16x16x32_bf16(Bt[n][k], At[m][k], acc[ai][bj][m][n], 0, 0, 0); __builtin_amdgcn_s_setprio(0); } while (0)
; #define PG8_WAIT_V(n) asm volatile("s_waitcnt vmcnt(" #n ")" ::: "memory")
; #define PG8_WAIT_L(n) asm volatile("s_waitcnt lgkmcnt(" #n ")" ::: "memory")
; #define PG8_BAR __builtin_amdgcn_s_barrier()
; #define PG8_SCHED __builtin_amdgcn_sched_barrier(0)
; template <class Epi, class Sched, bool ALIGN_EPI = false, bool SP2 = false>
; __device__ __forceinline__ void gemm_phase(PG8_LAS unsigned char* lds, const Gemm g, const Sched& S, const Epi& E) {
;     ...
;             PG8_WAIT_V(8); PG8_WAIT_L(0); PG8_BAR; PG8_MMA(0, 0, At, B0); PG8_MMA(0, 1, At, B1); PG8_BAR; PG8_SCHED;
;             PG8_LDA(At, 1, 1); PG8_STAGE(PG8_SB(1, 0), b3, voffB); PG8_STAGE(PG8_SB(1, 1), b3 + hstep, voffB); PG8_STAGE(PG8_SA(1, 0), a3, voffA);
;             PG8_WAIT_V(8); PG8_WAIT_L(0); PG8_BAR; PG8_MMA(1, 0, At, B0); PG8_MMA(1, 1, At, B1); PG8_BAR; PG8_SCHED;
;     ...
;         if constexpr (ALIGN_EPI) { if (wr == 0) PG8_BAR; }
	s_setprio 2
	v_mfma_f32_16x16x32_bf16 v[116:119], v[174:177], v[190:193], v[116:119]
	v_mfma_f32_16x16x32_bf16 v[112:115], v[182:185], v[190:193], v[112:115]
	v_mfma_f32_16x16x32_bf16 v[100:103], v[174:177], v[198:201], v[100:103]
	v_mfma_f32_16x16x32_bf16 v[96:99], v[182:185], v[198:201], v[96:99]
	v_mfma_f32_16x16x32_bf16 v[84:87], v[174:177], v[208:211], v[84:87]
	v_mfma_f32_16x16x32_bf16 v[80:83], v[182:185], v[208:211], v[80:83]
	v_mfma_f32_16x16x32_bf16 v[68:71], v[174:177], v[216:219], v[68:71]
	v_mfma_f32_16x16x32_bf16 v[64:67], v[182:185], v[216:219], v[64:67]
	s_setprio 0
	s_add_i32 s44, s64, s33
	v_lshl_add_u64 v[154:155], v[154:155], 0, s[8:9]
	s_mov_b32 m0, s44
	ds_read_b128 v[186:189], v149 offset:49152
	ds_read_b128 v[190:193], v149 offset:50176
	ds_read_b128 v[194:197], v149 offset:51200
	ds_read_b128 v[198:201], v149 offset:52224
	ds_read_b128 v[204:207], v149 offset:53248
	ds_read_b128 v[208:211], v149 offset:54272
	ds_read_b128 v[212:215], v149 offset:55296
	ds_read_b128 v[216:219], v149 offset:56320
	global_load_lds_dwordx4 v[154:155], off
	s_add_i32 m0, s44, 0x2000
	s_add_u32 s42, s42, 0x40080
	v_lshl_add_u64 v[154:155], v[220:221], 0, s[8:9]
	s_addc_u32 s43, s43, 0
	s_add_i32 s44, s65, s33
	global_load_lds_dwordx4 v[154:155], off
	v_lshl_add_u64 v[154:155], s[42:43], 0, v[132:133]
	s_mov_b32 m0, s44
	s_nop 0
	global_load_lds_dwordx4 v[154:155], off
	v_lshl_add_u64 v[154:155], s[42:43], 0, v[128:129]
	s_add_i32 m0, s44, 0x2000
	s_nop 0
	global_load_lds_dwordx4 v[154:155], off
	v_lshl_add_u64 v[154:155], v[222:223], 0, s[8:9]
	s_mov_b32 m0, s51
	s_nop 0
	global_load_lds_dwordx4 v[154:155], off
	v_lshl_add_u64 v[154:155], v[224:225], 0, s[8:9]
	s_mov_b32 m0, s52
	s_nop 0
	global_load_lds_dwordx4 v[154:155], off
	s_waitcnt vmcnt(8)
	s_waitcnt lgkmcnt(0)
	s_barrier
	s_setprio 1
	s_waitcnt lgkmcnt(0)
	v_mfma_f32_16x16x32_bf16 v[60:63], v[150:153], v[186:189], v[60:63]
	v_mfma_f32_16x16x32_bf16 v[56:59], v[162:165], v[186:189], v[56:59]
	v_mfma_f32_16x16x32_bf16 v[44:47], v[150:153], v[194:197], v[44:47]
	v_mfma_f32_16x16x32_bf16 v[40:43], v[162:165], v[194:197], v[40:43]
	v_mfma_f32_16x16x32_bf16 v[28:31], v[150:153], v[204:207], v[28:31]
	v_mfma_f32_16x16x32_bf16 v[24:27], v[162:165], v[204:207], v[24:27]
	v_mfma_f32_16x16x32_bf16 v[12:15], v[150:153], v[212:215], v[12:15]
	v_mfma_f32_16x16x32_bf16 v[8:11], v[162:165], v[212:215], v[8:11]
	v_mfma_f32_16x16x32_bf16 v[60:63], v[158:161], v[190:193], v[60:63]
	v_mfma_f32_16x16x32_bf16 v[56:59], v[166:169], v[190:193], v[56:59]
	v_mfma_f32_16x16x32_bf16 v[44:47], v[158:161], v[198:201], v[44:47]
	v_mfma_f32_16x16x32_bf16 v[40:43], v[166:169], v[198:201], v[40:43]
	v_mfma_f32_16x16x32_bf16 v[28:31], v[158:161], v[208:211], v[28:31]
	v_mfma_f32_16x16x32_bf16 v[24:27], v[166:169], v[208:211], v[24:27]
	v_mfma_f32_16x16x32_bf16 v[12:15], v[158:161], v[216:219], v[12:15]
	v_mfma_f32_16x16x32_bf16 v[8:11], v[166:169], v[216:219], v[8:11]
	s_setprio 0
	s_setprio 1
	v_mfma_f32_16x16x32_bf16 v[52:55], v[170:173], v[186:189], v[52:55]
	v_mfma_f32_16x16x32_bf16 v[48:51], v[178:181], v[186:189], v[48:51]
	v_mfma_f32_16x16x32_bf16 v[36:39], v[170:173], v[194:197], v[36:39]
	v_mfma_f32_16x16x32_bf16 v[32:35], v[178:181], v[194:197], v[32:35]
	v_mfma_f32_16x16x32_bf16 v[20:23], v[170:173], v[204:207], v[20:23]
	v_mfma_f32_16x16x32_bf16 v[16:19], v[178:181], v[204:207], v[16:19]
	v_mfma_f32_16x16x32_bf16 v[4:7], v[170:173], v[212:215], v[4:7]
	v_mfma_f32_16x16x32_bf16 v[0:3], v[178:181], v[212:215], v[0:3]
	s_barrier
	s_setprio 2
	v_mfma_f32_16x16x32_bf16 v[52:55], v[174:177], v[190:193], v[52:55]
	v_mfma_f32_16x16x32_bf16 v[48:51], v[182:185], v[190:193], v[48:51]
	v_mfma_f32_16x16x32_bf16 v[36:39], v[174:177], v[198:201], v[36:39]
	v_mfma_f32_16x16x32_bf16 v[32:35], v[182:185], v[198:201], v[32:35]
	v_mfma_f32_16x16x32_bf16 v[20:23], v[174:177], v[208:211], v[20:23]
	v_mfma_f32_16x16x32_bf16 v[16:19], v[182:185], v[208:211], v[16:19]
	v_mfma_f32_16x16x32_bf16 v[4:7], v[174:177], v[216:219], v[4:7]
	v_mfma_f32_16x16x32_bf16 v[0:3], v[182:185], v[216:219], v[0:3]
	s_setprio 0
	s_add_i32 s63, s63, 2
	s_add_u32 s40, s40, 0x100
	s_addc_u32 s41, s41, 0
	s_add_u32 s61, s61, 0x100
	s_addc_u32 s62, s62, 0
	s_cmp_gt_u32 s63, 13
	s_cbranch_scc0 .LBB0_848
	s_and_b64 vcc, exec, s[10:11]
	s_cbranch_vccz .LBB0_851
	s_barrier

; #define PG8_STAGE(bufoff, gbase, voff) do { _Pragma("unroll") for (int _i = 0; _i < 2; ++_i) \
;         __builtin_amdgcn_global_load_lds((const unsigned*)((const char*)(gbase) + (voff)[_i]), (PG8_LAS unsigned*)(lds + (bufoff) + ldsw + _i * 8192), 16, 0, 0); } while (0)
; #define PG8_LDA(dst, b, h) do { _Pragma("unroll") for (int m = 0; m < 4; ++m) _Pragma("unroll") for (int k = 0; k < 2; ++k) dst[m][k] = *(const PG8_LAS bf16x8*)(lds + PG8_SA(b, h) + aoff + m * 2048 + k * 1024); } while (0)
; #define PG8_LDB(dst, b, h) do { _Pragma("unroll") for (int n = 0; n < 2; ++n) _Pragma("unroll") for (int k = 0; k < 2; ++k) dst[n][k] = *(const PG8_LAS bf16x8*)(lds + PG8_SB(b, h) + boff + n * 2048 + k * 1024); } while (0)
; #define PG8_MMA(ai, bj, At, Bt) do { __builtin_amdgcn_s_setprio(1); _Pragma("unroll") for (int m = 0; m < 4; ++m) _Pragma("unroll") for (int n = 0; n < 2; ++n) _Pragma("unroll") for (int k = 0; k < 2; ++k) \
;         acc[ai][bj][m][n] = __builtin_amdgcn_mfma_f32_16x16x32_bf16(Bt[n][k], At[m][k], acc[ai][bj][m][n], 0, 0, 0); __builtin_amdgcn_s_setprio(0); } while (0)
; #define PG8_WAIT_V(n) asm volatile("s_waitcnt vmcnt(" #n ")" ::: "memory")
; #define PG8_WAIT_L(n) asm volatile("s_waitcnt lgkmcnt(" #n ")" ::: "memory")
; template <class Epi, class Sched, bool ALIGN_EPI = false, bool SP2 = false>
; __device__ __forceinline__ void gemm_phase(PG8_LAS unsigned char* lds, const Gemm g, const Sched& S, const Epi& E) {
;     ...
;             const bool last = (t == nt - 2);
;             const char* a1 = cA + (size_t)(t + 1) * kstep;
;             const char* a2 = last ? nA : cA + (size_t)(t + 2) * kstep; const char* b2 = last ? nB : cB + (size_t)(t + 2) * kstep;
;             const char* a3 = a2 + kstep; const char* b3 = b2 + kstep;
;             if (last && has_next) S.a_ready(nxt);
;             if constexpr (SP2) {
;             PG8_LDB(B0, 0, 0); PG8_LDB(B1, 0, 1); PG8_SCHED; PG8_LDA(At, 0, 0); PG8_STAGE(PG8_SA(1, 1), a1 + hstep, voffA);
;             PG8_WAIT_V(8); PG8_WAIT_L(0); PG8_BAR; PG8_MMA(0, 0, At, B0); PG8_MMA(0, 1, At, B1); PG8_BAR; PG8_SCHED;
;             PG8_LDA(At, 0, 1); PG8_STAGE(PG8_SB(0, 0), b2, voffB); PG8_STAGE(PG8_SB(0, 1), b2 + hstep, voffB); PG8_STAGE(PG8_SA(0, 0), a2, voffA);
;             PG8_WAIT_V(8); PG8_WAIT_L(0); PG8_BAR; PG8_MMA(1, 0, At, B0); PG8_MMA(1, 1, At, B1); PG8_BAR; PG8_SCHED;
.LBB0_927:
	ds_read_b128 v[128:131], v160
	ds_read_b128 v[148:151], v160 offset:1024
	ds_read_b128 v[152:155], v160 offset:2048
	ds_read_b128 v[164:167], v160 offset:3072
	ds_read_b128 v[168:171], v161
	ds_read_b128 v[172:175], v161 offset:1024
	ds_read_b128 v[176:179], v161 offset:2048
	ds_read_b128 v[180:183], v161 offset:3072
	s_add_u32 s46, s44, 0x100
	s_addc_u32 s47, s45, 0
	s_cmp_eq_u32 s70, 40
	s_cselect_b32 s51, s5, s47
	s_cselect_b32 s50, s4, s46
	s_cselect_b32 s49, s43, s67
	s_cselect_b32 s48, s42, s66
	v_lshl_add_u64 v[200:201], s[44:45], 0, v[140:141]
	s_add_i32 m0, s33, 0xc000
	ds_read_b128 v[184:187], v162
	ds_read_b128 v[188:191], v162 offset:1024
	ds_read_b128 v[192:195], v162 offset:2048
	ds_read_b128 v[196:199], v162 offset:3072
	ds_read_b128 v[204:207], v162 offset:4096
	ds_read_b128 v[208:211], v162 offset:5120
	ds_read_b128 v[212:215], v162 offset:6144
	ds_read_b128 v[216:219], v162 offset:7168
	global_load_lds_dwordx4 v[200:201], off
	v_lshl_add_u64 v[200:201], s[44:45], 0, v[142:143]
	s_add_i32 m0, s33, 0xe000
	s_nop 0
	global_load_lds_dwordx4 v[200:201], off
	s_waitcnt vmcnt(8)
	s_waitcnt lgkmcnt(0)
	s_barrier
	s_setprio 1
	s_waitcnt lgkmcnt(0)
	v_mfma_f32_16x16x32_bf16 v[124:127], v[128:131], v[184:187], v[124:127]
	v_mfma_f32_16x16x32_bf16 v[120:123], v[152:155], v[184:187], v[120:123]
	v_mfma_f32_16x16x32_bf16 v[116:119], v[128:131], v[192:195], v[116:119]
	v_mfma_f32_16x16x32_bf16 v[112:115], v[152:155], v[192:195], v[112:115]
	v_mfma_f32_16x16x32_bf16 v[96:99], v[128:131], v[204:207], v[96:99]
	v_mfma_f32_16x16x32_bf16 v[88:91], v[152:155], v[204:207], v[88:91]
	v_mfma_f32_16x16x32_bf16 v[80:83], v[128:131], v[212:215], v[80:83]
	v_mfma_f32_16x16x32_bf16 v[72:75], v[152:155], v[212:215], v[72:75]
	v_mfma_f32_16x16x32_bf16 v[124:127], v[148:151], v[188:191], v[124:127]
	v_mfma_f32_16x16x32_bf16 v[120:123], v[164:167], v[188:191], v[120:123]
	v_mfma_f32_16x16x32_bf16 v[116:119], v[148:151], v[196:199], v[116:119]
	v_mfma_f32_16x16x32_bf16 v[112:115], v[164:167], v[196:199], v[112:115]
	v_mfma_f32_16x16x32_bf16 v[96:99], v[148:151], v[208:211], v[96:99]
	v_mfma_f32_16x16x32_bf16 v[88:91], v[164:167], v[208:211], v[88:91]
	v_mfma_f32_16x16x32_bf16 v[80:83], v[148:151], v[216:219], v[80:83]
	v_mfma_f32_16x16x32_bf16 v[72:75], v[164:167], v[216:219], v[72:75]
	s_setprio 0
	s_setprio 1
	v_mfma_f32_16x16x32_bf16 v[108:111], v[168:171], v[184:187], v[108:111]
	v_mfma_f32_16x16x32_bf16 v[104:107], v[176:179], v[184:187], v[104:107]
	v_mfma_f32_16x16x32_bf16 v[100:103], v[168:171], v[192:195], v[100:103]
	v_mfma_f32_16x16x32_bf16 v[92:95], v[176:179], v[192:195], v[92:95]
	v_mfma_f32_16x16x32_bf16 v[84:87], v[168:171], v[204:207], v[84:87]
	v_mfma_f32_16x16x32_bf16 v[76:79], v[176:179], v[204:207], v[76:79]
	v_mfma_f32_16x16x32_bf16 v[68:71], v[168:171], v[212:215], v[68:71]
	v_mfma_f32_16x16x32_bf16 v[64:67], v[176:179], v[212:215], v[64:67]
	s_barrier
	s_setprio 2
	v_mfma_f32_16x16x32_bf16 v[108:111], v[172:175], v[188:191], v[108:111]
	v_mfma_f32_16x16x32_bf16 v[104:107], v[180:183], v[188:191], v[104:107]
	v_mfma_f32_16x16x32_bf16 v[100:103], v[172:175], v[196:199], v[100:103]
	v_mfma_f32_16x16x32_bf16 v[92:95], v[180:183], v[196:199], v[92:95]
	v_mfma_f32_16x16x32_bf16 v[84:87], v[172:175], v[208:211], v[84:87]
	v_mfma_f32_16x16x32_bf16 v[76:79], v[180:183], v[208:211], v[76:79]
	v_mfma_f32_16x16x32_bf16 v[68:71], v[172:175], v[216:219], v[68:71]
	v_mfma_f32_16x16x32_bf16 v[64:67], v[180:183], v[216:219], v[64:67]
	s_setprio 0
	s_add_i32 s44, s60, s17
	v_lshl_add_u64 v[200:201], s[48:49], 0, v[134:135]
	s_mov_b32 m0, s44
	ds_read_b128 v[184:187], v162 offset:16384
	ds_read_b128 v[188:191], v162 offset:17408
	ds_read_b128 v[192:195], v162 offset:18432
	ds_read_b128 v[196:199], v162 offset:19456
	ds_read_b128 v[204:207], v162 offset:20480
	ds_read_b128 v[208:211], v162 offset:21504
	ds_read_b128 v[212:215], v162 offset:22528
	ds_read_b128 v[216:219], v162 offset:23552
	global_load_lds_dwordx4 v[200:201], off
	s_add_i32 m0, s44, 0x2000
	s_add_u32 s44, s48, 0xb0000
	v_lshl_add_u64 v[220:221], s[48:49], 0, v[138:139]
	s_addc_u32 s45, s49, 0
	s_add_i32 s71, s61, s17
	global_load_lds_dwordx4 v[220:221], off
	v_lshl_add_u64 v[222:223], s[44:45], 0, v[134:135]
	s_mov_b32 m0, s71
	v_lshl_add_u64 v[224:225], s[50:51], 0, v[136:137]
	global_load_lds_dwordx4 v[222:223], off
	v_lshl_add_u64 v[222:223], s[44:45], 0, v[138:139]
	s_add_i32 m0, s71, 0x2000
	s_nop 0
	global_load_lds_dwordx4 v[222:223], off
	v_lshl_add_u64 v[222:223], s[50:51], 0, v[132:133]
	s_mov_b32 m0, s33
	s_nop 0
	global_load_lds_dwordx4 v[222:223], off
	s_mov_b32 m0, s52
	s_nop 0
	global_load_lds_dwordx4 v[224:225], off
	s_waitcnt vmcnt(8)
	s_waitcnt lgkmcnt(0)
	s_barrier
	s_setprio 1
	s_waitcnt lgkmcnt(0)
	v_mfma_f32_16x16x32_bf16 v[60:63], v[128:131], v[184:187], v[60:63]
	v_mfma_f32_16x16x32_bf16 v[56:59], v[152:155], v[184:187], v[56:59]
	v_mfma_f32_16x16x32_bf16 v[48:51], v[128:131], v[192:195], v[48:51]
	v_mfma_f32_16x16x32_bf16 v[40:43], v[152:155], v[192:195], v[40:43]
	v_mfma_f32_16x16x32_bf16 v[32:35], v[128:131], v[204:207], v[32:35]
	v_mfma_f32_16x16x32_bf16 v[24:27], v[152:155], v[204:207], v[24:27]
	v_mfma_f32_16x16x32_bf16 v[16:19], v[128:131], v[212:215], v[16:19]
	v_mfma_f32_16x16x32_bf16 v[8:11], v[152:155], v[212:215], v[8:11]
	v_mfma_f32_16x16x32_bf16 v[60:63], v[148:151], v[188:191], v[60:63]
	v_mfma_f32_16x16x32_bf16 v[56:59], v[164:167], v[188:191], v[56:59]
	v_mfma_f32_16x16x32_bf16 v[48:51], v[148:151], v[196:199], v[48:51]
	v_mfma_f32_16x16x32_bf16 v[40:43], v[164:167], v[196:199], v[40:43]
	v_mfma_f32_16x16x32_bf16 v[32:35], v[148:151], v[208:211], v[32:35]
	v_mfma_f32_16x16x32_bf16 v[24:27], v[164:167], v[208:211], v[24:27]
	v_mfma_f32_16x16x32_bf16 v[16:19], v[148:151], v[216:219], v[16:19]
	v_mfma_f32_16x16x32_bf16 v[8:11], v[164:167], v[216:219], v[8:11]
	s_setprio 0
	s_setprio 1
	v_mfma_f32_16x16x32_bf16 v[52:55], v[168:171], v[184:187], v[52:55]
	v_mfma_f32_16x16x32_bf16 v[44:47], v[176:179], v[184:187], v[44:47]
	v_mfma_f32_16x16x32_bf16 v[36:39], v[168:171], v[192:195], v[36:39]
	v_mfma_f32_16x16x32_bf16 v[28:31], v[176:179], v[192:195], v[28:31]
	v_mfma_f32_16x16x32_bf16 v[20:23], v[168:171], v[204:207], v[20:23]
	v_mfma_f32_16x16x32_bf16 v[12:15], v[176:179], v[204:207], v[12:15]
	v_mfma_f32_16x16x32_bf16 v[4:7], v[168:171], v[212:215], v[4:7]
	v_mfma_f32_16x16x32_bf16 v[0:3], v[176:179], v[212:215], v[0:3]
	s_barrier
; #define PG8_STAGE(bufoff, gbase, voff) do { _Pragma("unroll") for (int _i = 0; _i < 2; ++_i) \
;         __builtin_amdgcn_global_load_lds((const unsigned*)((const char*)(gbase) + (voff)[_i]), (PG8_LAS unsigned*)(lds + (bufoff) + ldsw + _i * 8192), 16, 0, 0); } while (0)
; #define PG8_LDA(dst, b, h) do { _Pragma("unroll") for (int m = 0; m < 4; ++m) _Pragma("unroll") for (int k = 0; k < 2; ++k) dst[m][k] = *(const PG8_LAS bf16x8*)(lds + PG8_SA(b, h) + aoff + m * 2048 + k * 1024); } while (0)
; #define PG8_LDB(dst, b, h) do { _Pragma("unroll") for (int n = 0; n < 2; ++n) _Pragma("unroll") for (int k = 0; k < 2; ++k) dst[n][k] = *(const PG8_LAS bf16x8*)(lds + PG8_SB(b, h) + boff + n * 2048 + k * 1024); } while (0)
; #define PG8_MMA(ai, bj, At, Bt) do { __builtin_amdgcn_s_setprio(1); _Pragma("unroll") for (int m = 0; m < 4; ++m) _Pragma("unroll") for (int n = 0; n < 2; ++n) _Pragma("unroll") for (int k = 0; k < 2; ++k) \
;         acc[ai][bj][m][n] = __builtin_amdgcn_mfma_f32_16x16x32_bf16(Bt[n][k], At[m][k], acc[ai][bj][m][n], 0, 0, 0); __builtin_amdgcn_s_setprio(0); } while (0)
; #define PG8_WAIT_V(n) asm volatile("s_waitcnt vmcnt(" #n ")" ::: "memory")
; #define PG8_WAIT_L(n) asm volatile("s_waitcnt lgkmcnt(" #n ")" ::: "memory")
; #define PG8_BAR __builtin_amdgcn_s_barrier()
; #define PG8_SCHED __builtin_amdgcn_sched_barrier(0)
; template <class Epi, class Sched, bool ALIGN_EPI = false, bool SP2 = false>
; __device__ __forceinline__ void gemm_phase(PG8_LAS unsigned char* lds, const Gemm g, const Sched& S, const Epi& E) {
;     ...
;             PG8_WAIT_V(8); PG8_WAIT_L(0); PG8_BAR; PG8_MMA(1, 0, At, B0); PG8_MMA(1, 1, At, B1); PG8_BAR; PG8_SCHED;
;             PG8_LDB(B0, 1, 0); PG8_LDB(B1, 1, 1); PG8_SCHED; PG8_LDA(At, 1, 0); PG8_STAGE(PG8_SA(0, 1), a2 + hstep, voffA);
;             PG8_WAIT_V(8); PG8_WAIT_L(0); PG8_BAR; PG8_MMA(0, 0, At, B0); PG8_MMA(0, 1, At, B1); PG8_BAR; PG8_SCHED;
	s_setprio 2
	v_mfma_f32_16x16x32_bf16 v[52:55], v[172:175], v[188:191], v[52:55]
	v_mfma_f32_16x16x32_bf16 v[44:47], v[180:183], v[188:191], v[44:47]
	v_mfma_f32_16x16x32_bf16 v[36:39], v[172:175], v[196:199], v[36:39]
	v_mfma_f32_16x16x32_bf16 v[28:31], v[180:183], v[196:199], v[28:31]
	v_mfma_f32_16x16x32_bf16 v[20:23], v[172:175], v[208:211], v[20:23]
	v_mfma_f32_16x16x32_bf16 v[12:15], v[180:183], v[208:211], v[12:15]
	v_mfma_f32_16x16x32_bf16 v[4:7], v[172:175], v[216:219], v[4:7]
	v_mfma_f32_16x16x32_bf16 v[0:3], v[180:183], v[216:219], v[0:3]
	s_setprio 0
	s_add_i32 s71, 0, 0x18000
	v_add_u32_e32 v163, s71, v158
	s_add_i32 s72, 0, 0x1c000
	ds_read_b128 v[128:131], v163
	ds_read_b128 v[148:151], v163 offset:1024
	ds_read_b128 v[152:155], v163 offset:2048
	ds_read_b128 v[164:167], v163 offset:3072
	v_add_u32_e32 v163, s72, v158
	ds_read_b128 v[168:171], v163
	ds_read_b128 v[172:175], v163 offset:1024
	ds_read_b128 v[176:179], v163 offset:2048
	ds_read_b128 v[180:183], v163 offset:3072
	s_add_u32 s44, s50, 0xb0000
	s_addc_u32 s45, s51, 0
	s_mov_b32 m0, s53
	v_lshl_add_u64 v[226:227], s[44:45], 0, v[132:133]
	ds_read_b128 v[184:187], v162 offset:32768
	ds_read_b128 v[188:191], v162 offset:33792
	ds_read_b128 v[192:195], v162 offset:34816
	ds_read_b128 v[196:199], v162 offset:35840
	ds_read_b128 v[204:207], v162 offset:36864
	ds_read_b128 v[208:211], v162 offset:37888
	ds_read_b128 v[212:215], v162 offset:38912
	ds_read_b128 v[216:219], v162 offset:39936
	global_load_lds_dwordx4 v[226:227], off
	v_lshl_add_u64 v[226:227], s[44:45], 0, v[136:137]
	s_mov_b32 m0, s54
	s_nop 0
	global_load_lds_dwordx4 v[226:227], off
	s_waitcnt vmcnt(8)
	s_waitcnt lgkmcnt(0)
	s_barrier
	s_setprio 1
	s_waitcnt lgkmcnt(0)
	v_mfma_f32_16x16x32_bf16 v[124:127], v[128:131], v[184:187], v[124:127]
	v_mfma_f32_16x16x32_bf16 v[120:123], v[152:155], v[184:187], v[120:123]
	v_mfma_f32_16x16x32_bf16 v[116:119], v[128:131], v[192:195], v[116:119]
	v_mfma_f32_16x16x32_bf16 v[112:115], v[152:155], v[192:195], v[112:115]
	v_mfma_f32_16x16x32_bf16 v[96:99], v[128:131], v[204:207], v[96:99]
	v_mfma_f32_16x16x32_bf16 v[88:91], v[152:155], v[204:207], v[88:91]
	v_mfma_f32_16x16x32_bf16 v[80:83], v[128:131], v[212:215], v[80:83]
	v_mfma_f32_16x16x32_bf16 v[72:75], v[152:155], v[212:215], v[72:75]
	v_mfma_f32_16x16x32_bf16 v[124:127], v[148:151], v[188:191], v[124:127]
	v_mfma_f32_16x16x32_bf16 v[120:123], v[164:167], v[188:191], v[120:123]
	v_mfma_f32_16x16x32_bf16 v[116:119], v[148:151], v[196:199], v[116:119]
	v_mfma_f32_16x16x32_bf16 v[112:115], v[164:167], v[196:199], v[112:115]
	v_mfma_f32_16x16x32_bf16 v[96:99], v[148:151], v[208:211], v[96:99]
	v_mfma_f32_16x16x32_bf16 v[88:91], v[164:167], v[208:211], v[88:91]
	v_mfma_f32_16x16x32_bf16 v[80:83], v[148:151], v[216:219], v[80:83]
	v_mfma_f32_16x16x32_bf16 v[72:75], v[164:167], v[216:219], v[72:75]
	s_setprio 0
	s_setprio 1
	v_mfma_f32_16x16x32_bf16 v[108:111], v[168:171], v[184:187], v[108:111]
	v_mfma_f32_16x16x32_bf16 v[104:107], v[176:179], v[184:187], v[104:107]
	v_mfma_f32_16x16x32_bf16 v[100:103], v[168:171], v[192:195], v[100:103]
	v_mfma_f32_16x16x32_bf16 v[92:95], v[176:179], v[192:195], v[92:95]
	v_mfma_f32_16x16x32_bf16 v[84:87], v[168:171], v[204:207], v[84:87]
	v_mfma_f32_16x16x32_bf16 v[76:79], v[176:179], v[204:207], v[76:79]
	v_mfma_f32_16x16x32_bf16 v[68:71], v[168:171], v[212:215], v[68:71]
	v_mfma_f32_16x16x32_bf16 v[64:67], v[176:179], v[212:215], v[64:67]
	s_barrier
; #define PG8_STAGE(bufoff, gbase, voff) do { _Pragma("unroll") for (int _i = 0; _i < 2; ++_i) \
;         __builtin_amdgcn_global_load_lds((const unsigned*)((const char*)(gbase) + (voff)[_i]), (PG8_LAS unsigned*)(lds + (bufoff) + ldsw + _i * 8192), 16, 0, 0); } while (0)
; #define PG8_LDA(dst, b, h) do { _Pragma("unroll") for (int m = 0; m < 4; ++m) _Pragma("unroll") for (int k = 0; k < 2; ++k) dst[m][k] = *(const PG8_LAS bf16x8*)(lds + PG8_SA(b, h) + aoff + m * 2048 + k * 1024); } while (0)
; #define PG8_MMA(ai, bj, At, Bt) do { __builtin_amdgcn_s_setprio(1); _Pragma("unroll") for (int m = 0; m < 4; ++m) _Pragma("unroll") for (int n = 0; n < 2; ++n) _Pragma("unroll") for (int k = 0; k < 2; ++k) \
;         acc[ai][bj][m][n] = __builtin_amdgcn_mfma_f32_16x16x32_bf16(Bt[n][k], At[m][k], acc[ai][bj][m][n], 0, 0, 0); __builtin_amdgcn_s_setprio(0); } while (0)
; #define PG8_WAIT_V(n) asm volatile("s_waitcnt vmcnt(" #n ")" ::: "memory")
; #define PG8_WAIT_L(n) asm volatile("s_waitcnt lgkmcnt(" #n ")" ::: "memory")
; #define PG8_BAR __builtin_amdgcn_s_barrier()
; #define PG8_SCHED __builtin_amdgcn_sched_barrier(0)
; template <class Epi, class Sched, bool ALIGN_EPI = false, bool SP2 = false>
; __device__ __forceinline__ void gemm_phase(PG8_LAS unsigned char* lds, const Gemm g, const Sched& S, const Epi& E) {
;     ...
;             PG8_WAIT_V(8); PG8_WAIT_L(0); PG8_BAR; PG8_MMA(0, 0, At, B0); PG8_MMA(0, 1, At, B1); PG8_BAR; PG8_SCHED;
;             PG8_LDA(At, 1, 1); PG8_STAGE(PG8_SB(1, 0), b3, voffB); PG8_STAGE(PG8_SB(1, 1), b3 + hstep, voffB); PG8_STAGE(PG8_SA(1, 0), a3, voffA);
;             PG8_WAIT_V(8); PG8_WAIT_L(0); PG8_BAR; PG8_MMA(1, 0, At, B0); PG8_MMA(1, 1, At, B1); PG8_BAR; PG8_SCHED;
;     ...
;         if constexpr (ALIGN_EPI) { if (wr == 0) PG8_BAR; }
	s_setprio 2
	v_mfma_f32_16x16x32_bf16 v[108:111], v[172:175], v[188:191], v[108:111]
	v_mfma_f32_16x16x32_bf16 v[104:107], v[180:183], v[188:191], v[104:107]
	v_mfma_f32_16x16x32_bf16 v[100:103], v[172:175], v[196:199], v[100:103]
	v_mfma_f32_16x16x32_bf16 v[92:95], v[180:183], v[196:199], v[92:95]
	v_mfma_f32_16x16x32_bf16 v[84:87], v[172:175], v[208:211], v[84:87]
	v_mfma_f32_16x16x32_bf16 v[76:79], v[180:183], v[208:211], v[76:79]
	v_mfma_f32_16x16x32_bf16 v[68:71], v[172:175], v[216:219], v[68:71]
	v_mfma_f32_16x16x32_bf16 v[64:67], v[180:183], v[216:219], v[64:67]
	s_setprio 0
	s_add_i32 s44, s71, s17
	v_lshl_add_u64 v[200:201], v[200:201], 0, s[10:11]
	s_mov_b32 m0, s44
	ds_read_b128 v[184:187], v162 offset:49152
	ds_read_b128 v[188:191], v162 offset:50176
	ds_read_b128 v[192:195], v162 offset:51200
	ds_read_b128 v[196:199], v162 offset:52224
	ds_read_b128 v[204:207], v162 offset:53248
	ds_read_b128 v[208:211], v162 offset:54272
	ds_read_b128 v[212:215], v162 offset:55296
	ds_read_b128 v[216:219], v162 offset:56320
	global_load_lds_dwordx4 v[200:201], off
	s_add_i32 m0, s44, 0x2000
	s_add_u32 s44, s48, 0xb0080
	v_lshl_add_u64 v[200:201], v[220:221], 0, s[10:11]
	s_addc_u32 s45, s49, 0
	s_add_i32 s48, s72, s17
	global_load_lds_dwordx4 v[200:201], off
	v_lshl_add_u64 v[200:201], s[44:45], 0, v[134:135]
	s_mov_b32 m0, s48
	s_nop 0
	global_load_lds_dwordx4 v[200:201], off
	v_lshl_add_u64 v[200:201], s[44:45], 0, v[138:139]
	s_add_i32 m0, s48, 0x2000
	s_nop 0
	global_load_lds_dwordx4 v[200:201], off
	v_lshl_add_u64 v[200:201], v[222:223], 0, s[10:11]
	s_mov_b32 m0, s56
	s_nop 0
	global_load_lds_dwordx4 v[200:201], off
	v_lshl_add_u64 v[200:201], v[224:225], 0, s[10:11]
	s_mov_b32 m0, s57
	s_nop 0
	global_load_lds_dwordx4 v[200:201], off
	s_waitcnt vmcnt(8)
	s_waitcnt lgkmcnt(0)
	s_barrier
	s_setprio 1
	s_waitcnt lgkmcnt(0)
	v_mfma_f32_16x16x32_bf16 v[60:63], v[128:131], v[184:187], v[60:63]
	v_mfma_f32_16x16x32_bf16 v[56:59], v[152:155], v[184:187], v[56:59]
	v_mfma_f32_16x16x32_bf16 v[48:51], v[128:131], v[192:195], v[48:51]
	v_mfma_f32_16x16x32_bf16 v[40:43], v[152:155], v[192:195], v[40:43]
	v_mfma_f32_16x16x32_bf16 v[32:35], v[128:131], v[204:207], v[32:35]
	v_mfma_f32_16x16x32_bf16 v[24:27], v[152:155], v[204:207], v[24:27]
	v_mfma_f32_16x16x32_bf16 v[16:19], v[128:131], v[212:215], v[16:19]
	v_mfma_f32_16x16x32_bf16 v[8:11], v[152:155], v[212:215], v[8:11]
	v_mfma_f32_16x16x32_bf16 v[60:63], v[148:151], v[188:191], v[60:63]
	v_mfma_f32_16x16x32_bf16 v[56:59], v[164:167], v[188:191], v[56:59]
	v_mfma_f32_16x16x32_bf16 v[48:51], v[148:151], v[196:199], v[48:51]
	v_mfma_f32_16x16x32_bf16 v[40:43], v[164:167], v[196:199], v[40:43]
	v_mfma_f32_16x16x32_bf16 v[32:35], v[148:151], v[208:211], v[32:35]
	v_mfma_f32_16x16x32_bf16 v[24:27], v[164:167], v[208:211], v[24:27]
	v_mfma_f32_16x16x32_bf16 v[16:19], v[148:151], v[216:219], v[16:19]
	v_mfma_f32_16x16x32_bf16 v[8:11], v[164:167], v[216:219], v[8:11]
	s_setprio 0
	s_setprio 1
	v_mfma_f32_16x16x32_bf16 v[52:55], v[168:171], v[184:187], v[52:55]
	v_mfma_f32_16x16x32_bf16 v[44:47], v[176:179], v[184:187], v[44:47]
	v_mfma_f32_16x16x32_bf16 v[36:39], v[168:171], v[192:195], v[36:39]
	v_mfma_f32_16x16x32_bf16 v[28:31], v[176:179], v[192:195], v[28:31]
	v_mfma_f32_16x16x32_bf16 v[20:23], v[168:171], v[204:207], v[20:23]
	v_mfma_f32_16x16x32_bf16 v[12:15], v[176:179], v[204:207], v[12:15]
	v_mfma_f32_16x16x32_bf16 v[4:7], v[168:171], v[212:215], v[4:7]
	v_mfma_f32_16x16x32_bf16 v[0:3], v[176:179], v[212:215], v[0:3]
	s_barrier
	s_setprio 2
	v_mfma_f32_16x16x32_bf16 v[52:55], v[172:175], v[188:191], v[52:55]
	v_mfma_f32_16x16x32_bf16 v[44:47], v[180:183], v[188:191], v[44:47]
	v_mfma_f32_16x16x32_bf16 v[36:39], v[172:175], v[196:199], v[36:39]
	v_mfma_f32_16x16x32_bf16 v[28:31], v[180:183], v[196:199], v[28:31]
	v_mfma_f32_16x16x32_bf16 v[20:23], v[172:175], v[208:211], v[20:23]
	v_mfma_f32_16x16x32_bf16 v[12:15], v[180:183], v[208:211], v[12:15]
	v_mfma_f32_16x16x32_bf16 v[4:7], v[172:175], v[216:219], v[4:7]
	v_mfma_f32_16x16x32_bf16 v[0:3], v[180:183], v[216:219], v[0:3]
	s_setprio 0
	s_add_i32 s70, s70, 2
	s_add_u32 s66, s66, 0x100
	s_addc_u32 s67, s67, 0
	s_cmp_gt_u32 s70, 41
	s_mov_b64 s[44:45], s[46:47]
	s_cbranch_scc0 .LBB0_927
	s_and_b64 vcc, exec, s[14:15]
	s_cbranch_vccz .LBB0_930
	s_barrier
